# GEMM epilogues (mix-out / FFN-down residual add, gated merge): the per-quad global loads are issued in groups of 16-32 with one wait instead of load+vmcnt(0) per quad
# speedup vs baseline: 1.0566x; 1.0448x over previous
; #define PG8_STAGE(bufoff, gbase, voff) do { _Pragma("unroll") for (int _i = 0; _i < 2; ++_i) \
;         __builtin_amdgcn_global_load_lds((const unsigned*)((const char*)(gbase) + (voff)[_i]), (LAS unsigned*)(lds + (bufoff) + ldsw + _i * 8192), 16, 0, 0); } while (0)
; #define PG8_LDA(dst, b, h) do { _Pragma("unroll") for (int m = 0; m < 4; ++m) _Pragma("unroll") for (int k = 0; k < 2; ++k) dst[m][k] = *(const LAS bf16x8*)(lds + PG8_SA(b, h) + aoff + m * 2048 + k * 1024); } while (0)
; #define PG8_LDB(dst, b, h) do { _Pragma("unroll") for (int n = 0; n < 2; ++n) _Pragma("unroll") for (int k = 0; k < 2; ++k) dst[n][k] = *(const LAS bf16x8*)(lds + PG8_SB(b, h) + boff + n * 2048 + k * 1024); } while (0)
; #define PG8_MMA(ai, bj, At, Bt) do { __builtin_amdgcn_s_setprio(1); _Pragma("unroll") for (int m = 0; m < 4; ++m) _Pragma("unroll") for (int n = 0; n < 2; ++n) _Pragma("unroll") for (int k = 0; k < 2; ++k) \
;         acc[ai][bj][m][n] = __builtin_amdgcn_mfma_f32_16x16x32_bf16(Bt[n][k], At[m][k], acc[ai][bj][m][n], 0, 0, 0); __builtin_amdgcn_s_setprio(0); } while (0)
; #define PG8_WAIT_V(n) asm volatile("s_waitcnt vmcnt(" #n ")" ::: "memory")
; #define PG8_WAIT_L(n) asm volatile("s_waitcnt lgkmcnt(" #n ")" ::: "memory")
; #define PG8_BAR __builtin_amdgcn_s_barrier()
; #define PG8_SCHED __builtin_amdgcn_sched_barrier(0)
; template <class Epi>
; __device__ __forceinline__ void gemm_phase(LAS unsigned char* lds, const Gemm g, const TileOrder& S, const Epi& E) {
;     ...
;             PG8_LDB(B0, 0, 0); PG8_SCHED; PG8_LDA(At, 0, 0); PG8_STAGE(PG8_SA(1, 1), a1 + hstepA, voffA);
;             PG8_WAIT_L(8); PG8_BAR; PG8_WAIT_L(0); PG8_MMA(0, 0, At, B0); PG8_BAR; PG8_SCHED;
;             PG8_LDB(B1, 0, 1); PG8_STAGE(PG8_SB(0, 0), b2, voffB);
;             PG8_BAR; PG8_WAIT_L(0); PG8_MMA(0, 1, At, B1); PG8_BAR;
;             PG8_LDA(At, 0, 1); PG8_STAGE(PG8_SA(0, 0), a2, voffA);
;             PG8_BAR; PG8_WAIT_L(0); PG8_MMA(1, 0, At, B0); PG8_BAR; PG8_SCHED;
;             PG8_STAGE(PG8_SB(0, 1), b2 + hstepB, voffB);
;             PG8_WAIT_V(6); PG8_BAR; PG8_MMA(1, 1, At, B1); PG8_BAR;
.LBB0_1134:
	v_add_u32_e32 v136, s64, v166
	ds_read_b128 v[156:159], v136
	ds_read_b128 v[160:163], v136 offset:1024
	ds_read_b128 v[172:175], v136 offset:2048
	ds_read_b128 v[194:197], v136 offset:3072
	s_add_u32 s26, s22, 0xfffc0080
	s_addc_u32 s27, s23, -1
	s_cmp_eq_u32 s67, 12
	s_cselect_b32 s29, s15, s27
	s_cselect_b32 s28, s25, s26
	s_cselect_b32 s27, s13, s66
	s_cselect_b32 s26, s55, s65
	v_lshl_add_u64 v[136:137], s[22:23], 0, v[132:133]
	s_add_i32 m0, s41, 0xc000
	ds_read_b128 v[198:201], v171
	ds_read_b128 v[202:205], v171 offset:1024
	ds_read_b128 v[206:209], v171 offset:2048
	ds_read_b128 v[210:213], v171 offset:3072
	ds_read_b128 v[214:217], v171 offset:4096
	ds_read_b128 v[218:221], v171 offset:5120
	ds_read_b128 v[222:225], v171 offset:6144
	ds_read_b128 v[226:229], v171 offset:7168
	global_load_lds_dwordx4 v[136:137], off
	v_lshl_add_u64 v[136:137], s[22:23], 0, v[134:135]
	s_add_i32 m0, s41, 0xe000
	s_nop 0
	global_load_lds_dwordx4 v[136:137], off
	s_waitcnt lgkmcnt(8)
	s_barrier
	s_waitcnt lgkmcnt(0)
	s_setprio 1
	s_waitcnt lgkmcnt(0)
	v_mfma_f32_16x16x32_bf16 v[126:129], v[156:159], v[198:201], v[126:129]
	v_mfma_f32_16x16x32_bf16 v[122:125], v[172:175], v[198:201], v[122:125]
	v_mfma_f32_16x16x32_bf16 v[118:121], v[156:159], v[206:209], v[118:121]
	v_mfma_f32_16x16x32_bf16 v[114:117], v[172:175], v[206:209], v[114:117]
	v_mfma_f32_16x16x32_bf16 v[110:113], v[156:159], v[214:217], v[110:113]
	v_mfma_f32_16x16x32_bf16 v[106:109], v[172:175], v[214:217], v[106:109]
	v_mfma_f32_16x16x32_bf16 v[102:105], v[156:159], v[222:225], v[102:105]
	v_mfma_f32_16x16x32_bf16 v[98:101], v[172:175], v[222:225], v[98:101]
	v_mfma_f32_16x16x32_bf16 v[126:129], v[160:163], v[202:205], v[126:129]
	v_mfma_f32_16x16x32_bf16 v[122:125], v[194:197], v[202:205], v[122:125]
	v_mfma_f32_16x16x32_bf16 v[118:121], v[160:163], v[210:213], v[118:121]
	v_mfma_f32_16x16x32_bf16 v[114:117], v[194:197], v[210:213], v[114:117]
	v_mfma_f32_16x16x32_bf16 v[110:113], v[160:163], v[218:221], v[110:113]
	v_mfma_f32_16x16x32_bf16 v[106:109], v[194:197], v[218:221], v[106:109]
	v_mfma_f32_16x16x32_bf16 v[102:105], v[160:163], v[226:229], v[102:105]
	v_mfma_f32_16x16x32_bf16 v[98:101], v[194:197], v[226:229], v[98:101]
	s_setprio 0
	s_barrier
	s_add_i32 s70, 0, 0x14000
	v_add_u32_e32 v136, s70, v166
	s_add_i32 s42, s64, s40
	ds_read_b128 v[230:233], v136
	ds_read_b128 v[234:237], v136 offset:1024
	ds_read_b128 v[238:241], v136 offset:2048
	ds_read_b128 v[242:245], v136 offset:3072
	v_lshl_add_u64 v[136:137], s[26:27], 0, v[0:1]
	s_mov_b32 m0, s42
	v_lshl_add_u64 v[164:165], s[26:27], 0, v[130:131]
	global_load_lds_dwordx4 v[136:137], off
	s_add_i32 m0, s42, 0x2000
	s_nop 0
	global_load_lds_dwordx4 v[164:165], off
	s_barrier
	s_waitcnt lgkmcnt(0)
	s_setprio 1
	s_waitcnt lgkmcnt(0)
	v_mfma_f32_16x16x32_bf16 v[94:97], v[230:233], v[198:201], v[94:97]
	v_mfma_f32_16x16x32_bf16 v[90:93], v[238:241], v[198:201], v[90:93]
	v_mfma_f32_16x16x32_bf16 v[86:89], v[230:233], v[206:209], v[86:89]
	v_mfma_f32_16x16x32_bf16 v[82:85], v[238:241], v[206:209], v[82:85]
	v_mfma_f32_16x16x32_bf16 v[78:81], v[230:233], v[214:217], v[78:81]
	v_mfma_f32_16x16x32_bf16 v[74:77], v[238:241], v[214:217], v[74:77]
	v_mfma_f32_16x16x32_bf16 v[70:73], v[230:233], v[222:225], v[70:73]
	v_mfma_f32_16x16x32_bf16 v[66:69], v[238:241], v[222:225], v[66:69]
	v_mfma_f32_16x16x32_bf16 v[94:97], v[234:237], v[202:205], v[94:97]
	v_mfma_f32_16x16x32_bf16 v[90:93], v[242:245], v[202:205], v[90:93]
	v_mfma_f32_16x16x32_bf16 v[86:89], v[234:237], v[210:213], v[86:89]
	v_mfma_f32_16x16x32_bf16 v[82:85], v[242:245], v[210:213], v[82:85]
	v_mfma_f32_16x16x32_bf16 v[78:81], v[234:237], v[218:221], v[78:81]
	v_mfma_f32_16x16x32_bf16 v[74:77], v[242:245], v[218:221], v[74:77]
	v_mfma_f32_16x16x32_bf16 v[70:73], v[234:237], v[226:229], v[70:73]
	v_mfma_f32_16x16x32_bf16 v[66:69], v[242:245], v[226:229], v[66:69]
	s_setprio 0
	s_mov_b32 m0, s41
	v_lshl_add_u64 v[246:247], s[28:29], 0, v[0:1]
	s_barrier
	ds_read_b128 v[198:201], v171 offset:16384
	ds_read_b128 v[202:205], v171 offset:17408
	ds_read_b128 v[206:209], v171 offset:18432
	ds_read_b128 v[210:213], v171 offset:19456
	ds_read_b128 v[214:217], v171 offset:20480
	ds_read_b128 v[218:221], v171 offset:21504
	ds_read_b128 v[222:225], v171 offset:22528
	ds_read_b128 v[226:229], v171 offset:23552
	global_load_lds_dwordx4 v[246:247], off
	v_lshl_add_u64 v[248:249], s[28:29], 0, v[130:131]
	s_mov_b32 m0, s44
	s_nop 0
	global_load_lds_dwordx4 v[248:249], off
	s_barrier
	s_waitcnt lgkmcnt(0)
	s_setprio 1
	s_waitcnt lgkmcnt(0)
	v_mfma_f32_16x16x32_bf16 v[62:65], v[156:159], v[198:201], v[62:65]
	v_mfma_f32_16x16x32_bf16 v[58:61], v[172:175], v[198:201], v[58:61]
	v_mfma_f32_16x16x32_bf16 v[54:57], v[156:159], v[206:209], v[54:57]
	v_mfma_f32_16x16x32_bf16 v[50:53], v[172:175], v[206:209], v[50:53]
	v_mfma_f32_16x16x32_bf16 v[46:49], v[156:159], v[214:217], v[46:49]
	v_mfma_f32_16x16x32_bf16 v[42:45], v[172:175], v[214:217], v[42:45]
	v_mfma_f32_16x16x32_bf16 v[38:41], v[156:159], v[222:225], v[38:41]
	v_mfma_f32_16x16x32_bf16 v[34:37], v[172:175], v[222:225], v[34:37]
	v_mfma_f32_16x16x32_bf16 v[62:65], v[160:163], v[202:205], v[62:65]
	v_mfma_f32_16x16x32_bf16 v[58:61], v[194:197], v[202:205], v[58:61]
	v_mfma_f32_16x16x32_bf16 v[54:57], v[160:163], v[210:213], v[54:57]
	v_mfma_f32_16x16x32_bf16 v[50:53], v[194:197], v[210:213], v[50:53]
	v_mfma_f32_16x16x32_bf16 v[46:49], v[160:163], v[218:221], v[46:49]
	v_mfma_f32_16x16x32_bf16 v[42:45], v[194:197], v[218:221], v[42:45]
	v_mfma_f32_16x16x32_bf16 v[38:41], v[160:163], v[226:229], v[38:41]
	v_mfma_f32_16x16x32_bf16 v[34:37], v[194:197], v[226:229], v[34:37]
	s_setprio 0
	s_barrier
; #define PG8_STAGE(bufoff, gbase, voff) do { _Pragma("unroll") for (int _i = 0; _i < 2; ++_i) \
;         __builtin_amdgcn_global_load_lds((const unsigned*)((const char*)(gbase) + (voff)[_i]), (LAS unsigned*)(lds + (bufoff) + ldsw + _i * 8192), 16, 0, 0); } while (0)
; #define PG8_LDA(dst, b, h) do { _Pragma("unroll") for (int m = 0; m < 4; ++m) _Pragma("unroll") for (int k = 0; k < 2; ++k) dst[m][k] = *(const LAS bf16x8*)(lds + PG8_SA(b, h) + aoff + m * 2048 + k * 1024); } while (0)
; #define PG8_LDB(dst, b, h) do { _Pragma("unroll") for (int n = 0; n < 2; ++n) _Pragma("unroll") for (int k = 0; k < 2; ++k) dst[n][k] = *(const LAS bf16x8*)(lds + PG8_SB(b, h) + boff + n * 2048 + k * 1024); } while (0)
; #define PG8_MMA(ai, bj, At, Bt) do { __builtin_amdgcn_s_setprio(1); _Pragma("unroll") for (int m = 0; m < 4; ++m) _Pragma("unroll") for (int n = 0; n < 2; ++n) _Pragma("unroll") for (int k = 0; k < 2; ++k) \
;         acc[ai][bj][m][n] = __builtin_amdgcn_mfma_f32_16x16x32_bf16(Bt[n][k], At[m][k], acc[ai][bj][m][n], 0, 0, 0); __builtin_amdgcn_s_setprio(0); } while (0)
; #define PG8_WAIT_L(n) asm volatile("s_waitcnt lgkmcnt(" #n ")" ::: "memory")
; #define PG8_BAR __builtin_amdgcn_s_barrier()
; #define PG8_SCHED __builtin_amdgcn_sched_barrier(0)
; template <class Epi>
; __device__ __forceinline__ void gemm_phase(LAS unsigned char* lds, const Gemm g, const TileOrder& S, const Epi& E) {
;     ...
;             PG8_LDB(B0, 1, 0); PG8_SCHED; PG8_LDA(At, 1, 0); PG8_STAGE(PG8_SA(0, 1), a2 + hstepA, voffA);
;             PG8_WAIT_L(8); PG8_BAR; PG8_WAIT_L(0); PG8_MMA(0, 0, At, B0); PG8_BAR; PG8_SCHED;
;             PG8_LDB(B1, 1, 1); PG8_STAGE(PG8_SB(1, 0), b3, voffB);
;             PG8_BAR; PG8_WAIT_L(0); PG8_MMA(0, 1, At, B1); PG8_BAR;
;             PG8_LDA(At, 1, 1); PG8_STAGE(PG8_SA(1, 0), a3, voffA);
;             PG8_BAR; PG8_WAIT_L(0); PG8_MMA(1, 0, At, B0); PG8_BAR; PG8_SCHED;
;             PG8_STAGE(PG8_SB(1, 1), b3 + hstepB, voffB);
	s_add_u32 s42, s26, 0x40000
	s_addc_u32 s43, s27, 0
	s_add_i32 s70, s70, s40
	v_lshl_add_u64 v[156:157], s[42:43], 0, v[0:1]
	s_mov_b32 m0, s70
	s_nop 0
	global_load_lds_dwordx4 v[156:157], off
	v_lshl_add_u64 v[156:157], s[42:43], 0, v[130:131]
	s_add_i32 m0, s70, 0x2000
	s_nop 0
	global_load_lds_dwordx4 v[156:157], off
	s_waitcnt vmcnt(6)
	s_barrier
	s_setprio 1
	v_mfma_f32_16x16x32_bf16 v[30:33], v[230:233], v[198:201], v[30:33]
	v_mfma_f32_16x16x32_bf16 v[26:29], v[238:241], v[198:201], v[26:29]
	v_mfma_f32_16x16x32_bf16 v[22:25], v[230:233], v[206:209], v[22:25]
	v_mfma_f32_16x16x32_bf16 v[18:21], v[238:241], v[206:209], v[18:21]
	v_mfma_f32_16x16x32_bf16 v[14:17], v[230:233], v[214:217], v[14:17]
	v_mfma_f32_16x16x32_bf16 v[10:13], v[238:241], v[214:217], v[10:13]
	v_mfma_f32_16x16x32_bf16 v[6:9], v[230:233], v[222:225], v[6:9]
	v_mfma_f32_16x16x32_bf16 v[2:5], v[238:241], v[222:225], v[2:5]
	v_mfma_f32_16x16x32_bf16 v[30:33], v[234:237], v[202:205], v[30:33]
	v_mfma_f32_16x16x32_bf16 v[26:29], v[242:245], v[202:205], v[26:29]
	v_mfma_f32_16x16x32_bf16 v[22:25], v[234:237], v[210:213], v[22:25]
	v_mfma_f32_16x16x32_bf16 v[18:21], v[242:245], v[210:213], v[18:21]
	v_mfma_f32_16x16x32_bf16 v[14:17], v[234:237], v[218:221], v[14:17]
	v_mfma_f32_16x16x32_bf16 v[10:13], v[242:245], v[218:221], v[10:13]
	v_mfma_f32_16x16x32_bf16 v[6:9], v[234:237], v[226:229], v[6:9]
	v_mfma_f32_16x16x32_bf16 v[2:5], v[242:245], v[226:229], v[2:5]
	s_setprio 0
	s_add_i32 s42, 0, 0x18000
	v_add_u32_e32 v193, s42, v166
	s_barrier
	ds_read_b128 v[156:159], v193
	ds_read_b128 v[160:163], v193 offset:1024
	ds_read_b128 v[172:175], v193 offset:2048
	ds_read_b128 v[194:197], v193 offset:3072
	s_add_u32 s28, s28, 0x40000
	s_addc_u32 s29, s29, 0
	s_mov_b32 m0, s45
	v_lshl_add_u64 v[230:231], s[28:29], 0, v[0:1]
	ds_read_b128 v[198:201], v171 offset:32768
	ds_read_b128 v[202:205], v171 offset:33792
	ds_read_b128 v[206:209], v171 offset:34816
	ds_read_b128 v[210:213], v171 offset:35840
	ds_read_b128 v[214:217], v171 offset:36864
	ds_read_b128 v[218:221], v171 offset:37888
	ds_read_b128 v[222:225], v171 offset:38912
	ds_read_b128 v[226:229], v171 offset:39936
	global_load_lds_dwordx4 v[230:231], off
	v_lshl_add_u64 v[230:231], s[28:29], 0, v[130:131]
	s_mov_b32 m0, s46
	s_nop 0
	global_load_lds_dwordx4 v[230:231], off
	s_waitcnt lgkmcnt(8)
	s_barrier
	s_waitcnt lgkmcnt(0)
	s_setprio 1
	s_waitcnt lgkmcnt(0)
	v_mfma_f32_16x16x32_bf16 v[126:129], v[156:159], v[198:201], v[126:129]
	v_mfma_f32_16x16x32_bf16 v[122:125], v[172:175], v[198:201], v[122:125]
	v_mfma_f32_16x16x32_bf16 v[118:121], v[156:159], v[206:209], v[118:121]
	v_mfma_f32_16x16x32_bf16 v[114:117], v[172:175], v[206:209], v[114:117]
	v_mfma_f32_16x16x32_bf16 v[110:113], v[156:159], v[214:217], v[110:113]
	v_mfma_f32_16x16x32_bf16 v[106:109], v[172:175], v[214:217], v[106:109]
	v_mfma_f32_16x16x32_bf16 v[102:105], v[156:159], v[222:225], v[102:105]
	v_mfma_f32_16x16x32_bf16 v[98:101], v[172:175], v[222:225], v[98:101]
	v_mfma_f32_16x16x32_bf16 v[126:129], v[160:163], v[202:205], v[126:129]
	v_mfma_f32_16x16x32_bf16 v[122:125], v[194:197], v[202:205], v[122:125]
	v_mfma_f32_16x16x32_bf16 v[118:121], v[160:163], v[210:213], v[118:121]
	v_mfma_f32_16x16x32_bf16 v[114:117], v[194:197], v[210:213], v[114:117]
	v_mfma_f32_16x16x32_bf16 v[110:113], v[160:163], v[218:221], v[110:113]
	v_mfma_f32_16x16x32_bf16 v[106:109], v[194:197], v[218:221], v[106:109]
	v_mfma_f32_16x16x32_bf16 v[102:105], v[160:163], v[226:229], v[102:105]
	v_mfma_f32_16x16x32_bf16 v[98:101], v[194:197], v[226:229], v[98:101]
	s_setprio 0
	s_barrier
	s_add_i32 s28, 0, 0x1c000
	s_add_i32 s29, s42, s40
	v_add_u32_e32 v193, s28, v166
	v_lshl_add_u64 v[136:137], v[136:137], 0, s[58:59]
	s_mov_b32 m0, s29
	ds_read_b128 v[230:233], v193
	ds_read_b128 v[234:237], v193 offset:1024
	ds_read_b128 v[238:241], v193 offset:2048
	ds_read_b128 v[242:245], v193 offset:3072
	global_load_lds_dwordx4 v[136:137], off
	v_lshl_add_u64 v[136:137], v[164:165], 0, s[58:59]
	s_add_i32 m0, s29, 0x2000
	s_nop 0
	global_load_lds_dwordx4 v[136:137], off
	s_barrier
	s_waitcnt lgkmcnt(0)
	s_setprio 1
	s_waitcnt lgkmcnt(0)
	v_mfma_f32_16x16x32_bf16 v[94:97], v[230:233], v[198:201], v[94:97]
	v_mfma_f32_16x16x32_bf16 v[90:93], v[238:241], v[198:201], v[90:93]
	v_mfma_f32_16x16x32_bf16 v[86:89], v[230:233], v[206:209], v[86:89]
	v_mfma_f32_16x16x32_bf16 v[82:85], v[238:241], v[206:209], v[82:85]
	v_mfma_f32_16x16x32_bf16 v[78:81], v[230:233], v[214:217], v[78:81]
	v_mfma_f32_16x16x32_bf16 v[74:77], v[238:241], v[214:217], v[74:77]
	v_mfma_f32_16x16x32_bf16 v[70:73], v[230:233], v[222:225], v[70:73]
	v_mfma_f32_16x16x32_bf16 v[66:69], v[238:241], v[222:225], v[66:69]
	v_mfma_f32_16x16x32_bf16 v[94:97], v[234:237], v[202:205], v[94:97]
	v_mfma_f32_16x16x32_bf16 v[90:93], v[242:245], v[202:205], v[90:93]
	v_mfma_f32_16x16x32_bf16 v[86:89], v[234:237], v[210:213], v[86:89]
	v_mfma_f32_16x16x32_bf16 v[82:85], v[242:245], v[210:213], v[82:85]
	v_mfma_f32_16x16x32_bf16 v[78:81], v[234:237], v[218:221], v[78:81]
	v_mfma_f32_16x16x32_bf16 v[74:77], v[242:245], v[218:221], v[74:77]
	v_mfma_f32_16x16x32_bf16 v[70:73], v[234:237], v[226:229], v[70:73]
	v_mfma_f32_16x16x32_bf16 v[66:69], v[242:245], v[226:229], v[66:69]
	s_setprio 0
	s_mov_b32 m0, s49
	v_lshl_add_u64 v[136:137], v[246:247], 0, s[58:59]
	s_barrier
	ds_read_b128 v[198:201], v171 offset:49152
	ds_read_b128 v[202:205], v171 offset:50176
	ds_read_b128 v[206:209], v171 offset:51200
	ds_read_b128 v[210:213], v171 offset:52224
	ds_read_b128 v[214:217], v171 offset:53248
	ds_read_b128 v[218:221], v171 offset:54272
	ds_read_b128 v[222:225], v171 offset:55296
	ds_read_b128 v[226:229], v171 offset:56320
	global_load_lds_dwordx4 v[136:137], off
	v_lshl_add_u64 v[136:137], v[248:249], 0, s[58:59]
	s_mov_b32 m0, s50
	s_nop 0
	global_load_lds_dwordx4 v[136:137], off
	s_barrier
; __device__ __forceinline__ float bflo(unsigned u) { return __uint_as_float(u << 16); }
; __device__ __forceinline__ float bfhi(unsigned u) { return __uint_as_float(u & 0xffff0000u); }
; #define PG8_MMA(ai, bj, At, Bt) do { __builtin_amdgcn_s_setprio(1); _Pragma("unroll") for (int m = 0; m < 4; ++m) _Pragma("unroll") for (int n = 0; n < 2; ++n) _Pragma("unroll") for (int k = 0; k < 2; ++k) \
;         acc[ai][bj][m][n] = __builtin_amdgcn_mfma_f32_16x16x32_bf16(Bt[n][k], At[m][k], acc[ai][bj][m][n], 0, 0, 0); __builtin_amdgcn_s_setprio(0); } while (0)
; #define PG8_WAIT_V(n) asm volatile("s_waitcnt vmcnt(" #n ")" ::: "memory")
; #define PG8_BAR __builtin_amdgcn_s_barrier()
; template <class Epi>
; __device__ __forceinline__ void gemm_phase(LAS unsigned char* lds, const Gemm g, const TileOrder& S, const Epi& E) {
;     ...
;             PG8_WAIT_V(6); PG8_BAR; PG8_MMA(1, 1, At, B1); PG8_BAR;
;         }
;     __device__ __forceinline__ void operator()(AccT& acc, const Unit& u, int wr, int wc, int fr, int fq) const {
;         const int z = u.z;
; #pragma unroll
;         for (int ai = 0; ai < 2; ++ai)
; #pragma unroll
;             for (int m = 0; m < 4; ++m) {
;                 const int row = u.pm * 256 + ai * 128 + wr * 64 + m * 16 + fr;
; #pragma unroll
;                 for (int bj = 0; bj < 2; ++bj)
; #pragma unroll
;                     for (int n = 0; n < 2; ++n) {
;                         const int col = u.pn * 256 + bj * 128 + wc * 32 + n * 16 + 4 * fq;
;                         const bf16_t* gp = proj + (size_t)row * NIN + OFF_MG + z * 2048 + col;
;                         const u32x2 ga = *(const u32x2*)gp;
;                         f32x4 v = acc[ai][bj][m][n];
;                         v[0] *= bflo(ga.x); v[1] *= bfhi(ga.x); v[2] *= bflo(ga.y); v[3] *= bfhi(ga.y);
;                         if ((DBG_ZMASK >> z) & 1) v = (f32x4){0.f, 0.f, 0.f, 0.f};
;                         if (z < 2) {
;                             const u32x2 gb = *(const u32x2*)(gp + 2048);
	s_waitcnt lgkmcnt(0)
	s_setprio 1
	s_waitcnt lgkmcnt(0)
	v_mfma_f32_16x16x32_bf16 v[62:65], v[156:159], v[198:201], v[62:65]
	v_mfma_f32_16x16x32_bf16 v[58:61], v[172:175], v[198:201], v[58:61]
	v_mfma_f32_16x16x32_bf16 v[54:57], v[156:159], v[206:209], v[54:57]
	v_mfma_f32_16x16x32_bf16 v[50:53], v[172:175], v[206:209], v[50:53]
	v_mfma_f32_16x16x32_bf16 v[46:49], v[156:159], v[214:217], v[46:49]
	v_mfma_f32_16x16x32_bf16 v[42:45], v[172:175], v[214:217], v[42:45]
	v_mfma_f32_16x16x32_bf16 v[38:41], v[156:159], v[222:225], v[38:41]
	v_mfma_f32_16x16x32_bf16 v[34:37], v[172:175], v[222:225], v[34:37]
	v_mfma_f32_16x16x32_bf16 v[62:65], v[160:163], v[202:205], v[62:65]
	v_mfma_f32_16x16x32_bf16 v[58:61], v[194:197], v[202:205], v[58:61]
	v_mfma_f32_16x16x32_bf16 v[54:57], v[160:163], v[210:213], v[54:57]
	v_mfma_f32_16x16x32_bf16 v[50:53], v[194:197], v[210:213], v[50:53]
	v_mfma_f32_16x16x32_bf16 v[46:49], v[160:163], v[218:221], v[46:49]
	v_mfma_f32_16x16x32_bf16 v[42:45], v[194:197], v[218:221], v[42:45]
	v_mfma_f32_16x16x32_bf16 v[38:41], v[160:163], v[226:229], v[38:41]
	v_mfma_f32_16x16x32_bf16 v[34:37], v[194:197], v[226:229], v[34:37]
	s_setprio 0
	s_barrier
	s_add_u32 s26, s26, 0x40080
	s_addc_u32 s27, s27, 0
	s_add_i32 s28, s28, s40
	v_lshl_add_u64 v[136:137], s[26:27], 0, v[0:1]
	s_mov_b32 m0, s28
	s_nop 0
	global_load_lds_dwordx4 v[136:137], off
	v_lshl_add_u64 v[136:137], s[26:27], 0, v[130:131]
	s_add_i32 m0, s28, 0x2000
	s_nop 0
	global_load_lds_dwordx4 v[136:137], off
	s_waitcnt vmcnt(6)
	s_barrier
	s_setprio 1
	v_mfma_f32_16x16x32_bf16 v[30:33], v[230:233], v[198:201], v[30:33]
	v_mfma_f32_16x16x32_bf16 v[26:29], v[238:241], v[198:201], v[26:29]
	v_mfma_f32_16x16x32_bf16 v[22:25], v[230:233], v[206:209], v[22:25]
	v_mfma_f32_16x16x32_bf16 v[18:21], v[238:241], v[206:209], v[18:21]
	v_mfma_f32_16x16x32_bf16 v[14:17], v[230:233], v[214:217], v[14:17]
	v_mfma_f32_16x16x32_bf16 v[10:13], v[238:241], v[214:217], v[10:13]
	v_mfma_f32_16x16x32_bf16 v[6:9], v[230:233], v[222:225], v[6:9]
	v_mfma_f32_16x16x32_bf16 v[2:5], v[238:241], v[222:225], v[2:5]
	v_mfma_f32_16x16x32_bf16 v[30:33], v[234:237], v[202:205], v[30:33]
	v_mfma_f32_16x16x32_bf16 v[26:29], v[242:245], v[202:205], v[26:29]
	v_mfma_f32_16x16x32_bf16 v[22:25], v[234:237], v[210:213], v[22:25]
	v_mfma_f32_16x16x32_bf16 v[18:21], v[242:245], v[210:213], v[18:21]
	v_mfma_f32_16x16x32_bf16 v[14:17], v[234:237], v[218:221], v[14:17]
	v_mfma_f32_16x16x32_bf16 v[10:13], v[242:245], v[218:221], v[10:13]
	v_mfma_f32_16x16x32_bf16 v[6:9], v[234:237], v[226:229], v[6:9]
	v_mfma_f32_16x16x32_bf16 v[2:5], v[242:245], v[226:229], v[2:5]
	s_setprio 0
	s_add_i32 s67, s67, 2
	s_add_u32 s22, s22, 0x100
	s_addc_u32 s23, s23, 0
	s_add_u32 s65, s65, 0x100
	s_addc_u32 s66, s66, 0
	s_cmp_gt_u32 s67, 13
	s_barrier
	s_cbranch_scc0 .LBB0_1134
	v_readlane_b32 s55, v252, 10
	s_lshl_b32 s22, s7, 11
	s_ashr_i32 s23, s22, 31
	s_cmp_gt_i32 s7, 1
	s_cselect_b64 s[26:27], -1, 0
	s_lshl_b32 s13, s24, 8
	v_add_u32_e32 v164, s13, v139
	v_mov_b64_e32 v[246:247], s[10:11]
	v_lshl_or_b32 v136, s6, 8, v170
	v_ashrrev_i32_e32 v137, 31, v136
	v_ashrrev_i32_e32 v165, 31, v164
	v_lshlrev_b64 v[248:249], 12, v[164:165]
	v_mad_i64_i32 v[246:247], s[6:7], v164, s73, v[246:247]
	v_lshl_add_u64 v[246:247], s[22:23], 1, v[246:247]
	v_lshl_add_u64 v[246:247], v[136:137], 1, v[246:247]
	s_mov_b64 s[6:7], 0x4000
	v_lshl_add_u64 v[246:247], v[246:247], 0, s[6:7]
	v_lshl_add_u64 v[248:249], s[8:9], 0, v[248:249]
	v_lshl_add_u64 v[248:249], v[136:137], 1, v[248:249]
	s_and_b64 vcc, exec, s[26:27]
	s_cbranch_vccnz .Lmerge_last
	s_mov_b64 s[6:7], 0x1000
	v_lshl_add_u64 v[250:251], v[246:247], 0, s[6:7]
	global_load_dwordx2 v[156:157], v[246:247], off
	global_load_dwordx2 v[158:159], v[250:251], off
	global_load_dwordx2 v[160:161], v[246:247], off offset:32
	global_load_dwordx2 v[162:163], v[250:251], off offset:32
	global_load_dwordx2 v[172:173], v[246:247], off offset:256
	global_load_dwordx2 v[174:175], v[250:251], off offset:256
	global_load_dwordx2 v[194:195], v[246:247], off offset:288
	global_load_dwordx2 v[196:197], v[250:251], off offset:288
	s_mov_b64 s[6:7], 0x72000
	v_lshl_add_u64 v[164:165], v[246:247], 0, s[6:7]
	s_mov_b64 s[6:7], 0x73000
	v_lshl_add_u64 v[250:251], v[246:247], 0, s[6:7]
	global_load_dwordx2 v[198:199], v[164:165], off
	global_load_dwordx2 v[200:201], v[250:251], off
	global_load_dwordx2 v[202:203], v[164:165], off offset:32
	global_load_dwordx2 v[204:205], v[250:251], off offset:32
	global_load_dwordx2 v[206:207], v[164:165], off offset:256
	global_load_dwordx2 v[208:209], v[250:251], off offset:256
	global_load_dwordx2 v[210:211], v[164:165], off offset:288
	global_load_dwordx2 v[212:213], v[250:251], off offset:288
	s_mov_b64 s[6:7], 0xe4000
	v_lshl_add_u64 v[164:165], v[246:247], 0, s[6:7]
	s_mov_b64 s[6:7], 0xe5000
	v_lshl_add_u64 v[250:251], v[246:247], 0, s[6:7]
	global_load_dwordx2 v[214:215], v[164:165], off
	global_load_dwordx2 v[216:217], v[250:251], off
	global_load_dwordx2 v[218:219], v[164:165], off offset:32
	global_load_dwordx2 v[220:221], v[250:251], off offset:32
	global_load_dwordx2 v[222:223], v[164:165], off offset:256
	global_load_dwordx2 v[224:225], v[250:251], off offset:256
	global_load_dwordx2 v[226:227], v[164:165], off offset:288
	global_load_dwordx2 v[228:229], v[250:251], off offset:288
	s_mov_b64 s[6:7], 0x156000
	v_lshl_add_u64 v[164:165], v[246:247], 0, s[6:7]
	s_mov_b64 s[6:7], 0x157000
	v_lshl_add_u64 v[250:251], v[246:247], 0, s[6:7]
	global_load_dwordx2 v[230:231], v[164:165], off
	global_load_dwordx2 v[232:233], v[250:251], off
	global_load_dwordx2 v[234:235], v[164:165], off offset:32
	global_load_dwordx2 v[236:237], v[250:251], off offset:32
	global_load_dwordx2 v[238:239], v[164:165], off offset:256
	global_load_dwordx2 v[240:241], v[250:251], off offset:256
	global_load_dwordx2 v[242:243], v[164:165], off offset:288
	global_load_dwordx2 v[244:245], v[250:251], off offset:288
	s_waitcnt vmcnt(0)
; __device__ __forceinline__ float bflo(unsigned u) { return __uint_as_float(u << 16); }
; __device__ __forceinline__ float bfhi(unsigned u) { return __uint_as_float(u & 0xffff0000u); }
;     __device__ __forceinline__ void operator()(AccT& acc, const Unit& u, int wr, int wc, int fr, int fq) const {
;     ...
;                     for (int n = 0; n < 2; ++n) {
;                         const int col = u.pn * 256 + bj * 128 + wc * 32 + n * 16 + 4 * fq;
;                         const bf16_t* gp = proj + (size_t)row * NIN + OFF_MG + z * 2048 + col;
;                         const u32x2 ga = *(const u32x2*)gp;
;                         f32x4 v = acc[ai][bj][m][n];
;                         v[0] *= bflo(ga.x); v[1] *= bfhi(ga.x); v[2] *= bflo(ga.y); v[3] *= bfhi(ga.y);
;                         if ((DBG_ZMASK >> z) & 1) v = (f32x4){0.f, 0.f, 0.f, 0.f};
;                         if (z < 2) {
;                             const u32x2 gb = *(const u32x2*)(gp + 2048);
;                             v[0] *= __builtin_amdgcn_rcpf(fmaxf(bflo(gb.x), 1e-30f)); v[1] *= __builtin_amdgcn_rcpf(fmaxf(bfhi(gb.x), 1e-30f));
;                             v[2] *= __builtin_amdgcn_rcpf(fmaxf(bflo(gb.y), 1e-30f)); v[3] *= __builtin_amdgcn_rcpf(fmaxf(bfhi(gb.y), 1e-30f));
;                             acc[ai][bj][m][n] = v;
	v_lshlrev_b32_e32 v250, 16, v156
	v_and_b32_e32 v251, 0xffff0000, v156
	v_lshlrev_b32_e32 v164, 16, v157
	v_and_b32_e32 v165, 0xffff0000, v157
	v_pk_mul_f32 v[126:127], v[126:127], v[250:251]
	v_pk_mul_f32 v[128:129], v[128:129], v[164:165]
	v_lshlrev_b32_e32 v250, 16, v158
	v_and_b32_e32 v251, 0xffff0000, v158
	v_lshlrev_b32_e32 v164, 16, v159
	v_and_b32_e32 v165, 0xffff0000, v159
	v_max_f32_e32 v250, v250, v250
	v_max_f32_e32 v251, v251, v251
	v_max_f32_e32 v164, v164, v164
	v_max_f32_e32 v165, v165, v165
	v_max_f32_e32 v250, 0xda24260, v250
	v_max_f32_e32 v251, 0xda24260, v251
	v_max_f32_e32 v164, 0xda24260, v164
	v_max_f32_e32 v165, 0xda24260, v165
	v_rcp_f32_e32 v250, v250
	v_rcp_f32_e32 v251, v251
	v_rcp_f32_e32 v164, v164
	v_rcp_f32_e32 v165, v165
	v_pk_mul_f32 v[126:127], v[126:127], v[250:251]
	v_pk_mul_f32 v[128:129], v[128:129], v[164:165]
	v_lshlrev_b32_e32 v250, 16, v160
	v_and_b32_e32 v251, 0xffff0000, v160
	v_lshlrev_b32_e32 v164, 16, v161
	v_and_b32_e32 v165, 0xffff0000, v161
	v_pk_mul_f32 v[122:123], v[122:123], v[250:251]
	v_pk_mul_f32 v[124:125], v[124:125], v[164:165]
	v_lshlrev_b32_e32 v250, 16, v162
	v_and_b32_e32 v251, 0xffff0000, v162
	v_lshlrev_b32_e32 v164, 16, v163
	v_and_b32_e32 v165, 0xffff0000, v163
	v_max_f32_e32 v250, v250, v250
	v_max_f32_e32 v251, v251, v251
	v_max_f32_e32 v164, v164, v164
	v_max_f32_e32 v165, v165, v165
	v_max_f32_e32 v250, 0xda24260, v250
	v_max_f32_e32 v251, 0xda24260, v251
	v_max_f32_e32 v164, 0xda24260, v164
	v_max_f32_e32 v165, 0xda24260, v165
	v_rcp_f32_e32 v250, v250
	v_rcp_f32_e32 v251, v251
	v_rcp_f32_e32 v164, v164
	v_rcp_f32_e32 v165, v165
	v_pk_mul_f32 v[122:123], v[122:123], v[250:251]
	v_pk_mul_f32 v[124:125], v[124:125], v[164:165]
	v_lshlrev_b32_e32 v250, 16, v172
	v_and_b32_e32 v251, 0xffff0000, v172
	v_lshlrev_b32_e32 v164, 16, v173
	v_and_b32_e32 v165, 0xffff0000, v173
	v_pk_mul_f32 v[94:95], v[94:95], v[250:251]
	v_pk_mul_f32 v[96:97], v[96:97], v[164:165]
	v_lshlrev_b32_e32 v250, 16, v174
	v_and_b32_e32 v251, 0xffff0000, v174
	v_lshlrev_b32_e32 v164, 16, v175
	v_and_b32_e32 v165, 0xffff0000, v175
	v_max_f32_e32 v250, v250, v250
	v_max_f32_e32 v251, v251, v251
	v_max_f32_e32 v164, v164, v164
	v_max_f32_e32 v165, v165, v165
	v_max_f32_e32 v250, 0xda24260, v250
	v_max_f32_e32 v251, 0xda24260, v251
	v_max_f32_e32 v164, 0xda24260, v164
	v_max_f32_e32 v165, 0xda24260, v165
	v_rcp_f32_e32 v250, v250
	v_rcp_f32_e32 v251, v251
	v_rcp_f32_e32 v164, v164
	v_rcp_f32_e32 v165, v165
	v_pk_mul_f32 v[94:95], v[94:95], v[250:251]
	v_pk_mul_f32 v[96:97], v[96:97], v[164:165]
	v_lshlrev_b32_e32 v250, 16, v194
	v_and_b32_e32 v251, 0xffff0000, v194
	v_lshlrev_b32_e32 v164, 16, v195
	v_and_b32_e32 v165, 0xffff0000, v195
	v_pk_mul_f32 v[90:91], v[90:91], v[250:251]
	v_pk_mul_f32 v[92:93], v[92:93], v[164:165]
	v_lshlrev_b32_e32 v250, 16, v196
	v_and_b32_e32 v251, 0xffff0000, v196
	v_lshlrev_b32_e32 v164, 16, v197
	v_and_b32_e32 v165, 0xffff0000, v197
	v_max_f32_e32 v250, v250, v250
	v_max_f32_e32 v251, v251, v251
	v_max_f32_e32 v164, v164, v164
	v_max_f32_e32 v165, v165, v165
	v_max_f32_e32 v250, 0xda24260, v250
	v_max_f32_e32 v251, 0xda24260, v251
	v_max_f32_e32 v164, 0xda24260, v164
	v_max_f32_e32 v165, 0xda24260, v165
	v_rcp_f32_e32 v250, v250
	v_rcp_f32_e32 v251, v251
	v_rcp_f32_e32 v164, v164
	v_rcp_f32_e32 v165, v165
	v_pk_mul_f32 v[90:91], v[90:91], v[250:251]
	v_pk_mul_f32 v[92:93], v[92:93], v[164:165]
	v_lshlrev_b32_e32 v250, 16, v198
	v_and_b32_e32 v251, 0xffff0000, v198
	v_lshlrev_b32_e32 v164, 16, v199
	v_and_b32_e32 v165, 0xffff0000, v199
	v_pk_mul_f32 v[118:119], v[118:119], v[250:251]
	v_pk_mul_f32 v[120:121], v[120:121], v[164:165]
	v_lshlrev_b32_e32 v250, 16, v200
	v_and_b32_e32 v251, 0xffff0000, v200
	v_lshlrev_b32_e32 v164, 16, v201
	v_and_b32_e32 v165, 0xffff0000, v201
	v_max_f32_e32 v250, v250, v250
	v_max_f32_e32 v251, v251, v251
	v_max_f32_e32 v164, v164, v164
	v_max_f32_e32 v165, v165, v165
	v_max_f32_e32 v250, 0xda24260, v250
	v_max_f32_e32 v251, 0xda24260, v251
	v_max_f32_e32 v164, 0xda24260, v164
	v_max_f32_e32 v165, 0xda24260, v165
	v_rcp_f32_e32 v250, v250
	v_rcp_f32_e32 v251, v251
	v_rcp_f32_e32 v164, v164
	v_rcp_f32_e32 v165, v165
	v_pk_mul_f32 v[118:119], v[118:119], v[250:251]
	v_pk_mul_f32 v[120:121], v[120:121], v[164:165]
	v_lshlrev_b32_e32 v250, 16, v202
	v_and_b32_e32 v251, 0xffff0000, v202
	v_lshlrev_b32_e32 v164, 16, v203
	v_and_b32_e32 v165, 0xffff0000, v203
	v_pk_mul_f32 v[114:115], v[114:115], v[250:251]
	v_pk_mul_f32 v[116:117], v[116:117], v[164:165]
	v_lshlrev_b32_e32 v250, 16, v204
	v_and_b32_e32 v251, 0xffff0000, v204
	v_lshlrev_b32_e32 v164, 16, v205
	v_and_b32_e32 v165, 0xffff0000, v205
	v_max_f32_e32 v250, v250, v250
	v_max_f32_e32 v251, v251, v251
	v_max_f32_e32 v164, v164, v164
	v_max_f32_e32 v165, v165, v165
	v_max_f32_e32 v250, 0xda24260, v250
	v_max_f32_e32 v251, 0xda24260, v251
	v_max_f32_e32 v164, 0xda24260, v164
	v_max_f32_e32 v165, 0xda24260, v165
	v_rcp_f32_e32 v250, v250
	v_rcp_f32_e32 v251, v251
	v_rcp_f32_e32 v164, v164
	v_rcp_f32_e32 v165, v165
	v_pk_mul_f32 v[114:115], v[114:115], v[250:251]
	v_pk_mul_f32 v[116:117], v[116:117], v[164:165]
	v_lshlrev_b32_e32 v250, 16, v206
	v_and_b32_e32 v251, 0xffff0000, v206
	v_lshlrev_b32_e32 v164, 16, v207
	v_and_b32_e32 v165, 0xffff0000, v207
	v_pk_mul_f32 v[86:87], v[86:87], v[250:251]
	v_pk_mul_f32 v[88:89], v[88:89], v[164:165]
	v_lshlrev_b32_e32 v250, 16, v208
	v_and_b32_e32 v251, 0xffff0000, v208
	v_lshlrev_b32_e32 v164, 16, v209
	v_and_b32_e32 v165, 0xffff0000, v209
	v_max_f32_e32 v250, v250, v250
	v_max_f32_e32 v251, v251, v251
	v_max_f32_e32 v164, v164, v164
; __device__ __forceinline__ float bflo(unsigned u) { return __uint_as_float(u << 16); }
; __device__ __forceinline__ float bfhi(unsigned u) { return __uint_as_float(u & 0xffff0000u); }
;     __device__ __forceinline__ void operator()(AccT& acc, const Unit& u, int wr, int wc, int fr, int fq) const {
;     ...
;                     for (int n = 0; n < 2; ++n) {
;                         const int col = u.pn * 256 + bj * 128 + wc * 32 + n * 16 + 4 * fq;
;                         const bf16_t* gp = proj + (size_t)row * NIN + OFF_MG + z * 2048 + col;
;                         const u32x2 ga = *(const u32x2*)gp;
;                         f32x4 v = acc[ai][bj][m][n];
;                         v[0] *= bflo(ga.x); v[1] *= bfhi(ga.x); v[2] *= bflo(ga.y); v[3] *= bfhi(ga.y);
;                         if ((DBG_ZMASK >> z) & 1) v = (f32x4){0.f, 0.f, 0.f, 0.f};
;                         if (z < 2) {
;                             const u32x2 gb = *(const u32x2*)(gp + 2048);
;                             v[0] *= __builtin_amdgcn_rcpf(fmaxf(bflo(gb.x), 1e-30f)); v[1] *= __builtin_amdgcn_rcpf(fmaxf(bfhi(gb.x), 1e-30f));
;                             v[2] *= __builtin_amdgcn_rcpf(fmaxf(bflo(gb.y), 1e-30f)); v[3] *= __builtin_amdgcn_rcpf(fmaxf(bfhi(gb.y), 1e-30f));
;                             acc[ai][bj][m][n] = v;
	v_max_f32_e32 v165, v165, v165
	v_max_f32_e32 v250, 0xda24260, v250
	v_max_f32_e32 v251, 0xda24260, v251
	v_max_f32_e32 v164, 0xda24260, v164
	v_max_f32_e32 v165, 0xda24260, v165
	v_rcp_f32_e32 v250, v250
	v_rcp_f32_e32 v251, v251
	v_rcp_f32_e32 v164, v164
	v_rcp_f32_e32 v165, v165
	v_pk_mul_f32 v[86:87], v[86:87], v[250:251]
	v_pk_mul_f32 v[88:89], v[88:89], v[164:165]
	v_lshlrev_b32_e32 v250, 16, v210
	v_and_b32_e32 v251, 0xffff0000, v210
	v_lshlrev_b32_e32 v164, 16, v211
	v_and_b32_e32 v165, 0xffff0000, v211
	v_pk_mul_f32 v[82:83], v[82:83], v[250:251]
	v_pk_mul_f32 v[84:85], v[84:85], v[164:165]
	v_lshlrev_b32_e32 v250, 16, v212
	v_and_b32_e32 v251, 0xffff0000, v212
	v_lshlrev_b32_e32 v164, 16, v213
	v_and_b32_e32 v165, 0xffff0000, v213
	v_max_f32_e32 v250, v250, v250
	v_max_f32_e32 v251, v251, v251
	v_max_f32_e32 v164, v164, v164
	v_max_f32_e32 v165, v165, v165
	v_max_f32_e32 v250, 0xda24260, v250
	v_max_f32_e32 v251, 0xda24260, v251
	v_max_f32_e32 v164, 0xda24260, v164
	v_max_f32_e32 v165, 0xda24260, v165
	v_rcp_f32_e32 v250, v250
	v_rcp_f32_e32 v251, v251
	v_rcp_f32_e32 v164, v164
	v_rcp_f32_e32 v165, v165
	v_pk_mul_f32 v[82:83], v[82:83], v[250:251]
	v_pk_mul_f32 v[84:85], v[84:85], v[164:165]
	v_lshlrev_b32_e32 v250, 16, v214
	v_and_b32_e32 v251, 0xffff0000, v214
	v_lshlrev_b32_e32 v164, 16, v215
	v_and_b32_e32 v165, 0xffff0000, v215
	v_pk_mul_f32 v[110:111], v[110:111], v[250:251]
	v_pk_mul_f32 v[112:113], v[112:113], v[164:165]
	v_lshlrev_b32_e32 v250, 16, v216
	v_and_b32_e32 v251, 0xffff0000, v216
	v_lshlrev_b32_e32 v164, 16, v217
	v_and_b32_e32 v165, 0xffff0000, v217
	v_max_f32_e32 v250, v250, v250
	v_max_f32_e32 v251, v251, v251
	v_max_f32_e32 v164, v164, v164
	v_max_f32_e32 v165, v165, v165
	v_max_f32_e32 v250, 0xda24260, v250
	v_max_f32_e32 v251, 0xda24260, v251
	v_max_f32_e32 v164, 0xda24260, v164
	v_max_f32_e32 v165, 0xda24260, v165
	v_rcp_f32_e32 v250, v250
	v_rcp_f32_e32 v251, v251
	v_rcp_f32_e32 v164, v164
	v_rcp_f32_e32 v165, v165
	v_pk_mul_f32 v[110:111], v[110:111], v[250:251]
	v_pk_mul_f32 v[112:113], v[112:113], v[164:165]
	v_lshlrev_b32_e32 v250, 16, v218
	v_and_b32_e32 v251, 0xffff0000, v218
	v_lshlrev_b32_e32 v164, 16, v219
	v_and_b32_e32 v165, 0xffff0000, v219
	v_pk_mul_f32 v[106:107], v[106:107], v[250:251]
	v_pk_mul_f32 v[108:109], v[108:109], v[164:165]
	v_lshlrev_b32_e32 v250, 16, v220
	v_and_b32_e32 v251, 0xffff0000, v220
	v_lshlrev_b32_e32 v164, 16, v221
	v_and_b32_e32 v165, 0xffff0000, v221
	v_max_f32_e32 v250, v250, v250
	v_max_f32_e32 v251, v251, v251
	v_max_f32_e32 v164, v164, v164
	v_max_f32_e32 v165, v165, v165
	v_max_f32_e32 v250, 0xda24260, v250
	v_max_f32_e32 v251, 0xda24260, v251
	v_max_f32_e32 v164, 0xda24260, v164
	v_max_f32_e32 v165, 0xda24260, v165
	v_rcp_f32_e32 v250, v250
	v_rcp_f32_e32 v251, v251
	v_rcp_f32_e32 v164, v164
	v_rcp_f32_e32 v165, v165
	v_pk_mul_f32 v[106:107], v[106:107], v[250:251]
	v_pk_mul_f32 v[108:109], v[108:109], v[164:165]
	v_lshlrev_b32_e32 v250, 16, v222
	v_and_b32_e32 v251, 0xffff0000, v222
	v_lshlrev_b32_e32 v164, 16, v223
	v_and_b32_e32 v165, 0xffff0000, v223
	v_pk_mul_f32 v[78:79], v[78:79], v[250:251]
	v_pk_mul_f32 v[80:81], v[80:81], v[164:165]
	v_lshlrev_b32_e32 v250, 16, v224
	v_and_b32_e32 v251, 0xffff0000, v224
	v_lshlrev_b32_e32 v164, 16, v225
	v_and_b32_e32 v165, 0xffff0000, v225
	v_max_f32_e32 v250, v250, v250
	v_max_f32_e32 v251, v251, v251
	v_max_f32_e32 v164, v164, v164
	v_max_f32_e32 v165, v165, v165
	v_max_f32_e32 v250, 0xda24260, v250
	v_max_f32_e32 v251, 0xda24260, v251
	v_max_f32_e32 v164, 0xda24260, v164
	v_max_f32_e32 v165, 0xda24260, v165
	v_rcp_f32_e32 v250, v250
	v_rcp_f32_e32 v251, v251
	v_rcp_f32_e32 v164, v164
	v_rcp_f32_e32 v165, v165
	v_pk_mul_f32 v[78:79], v[78:79], v[250:251]
	v_pk_mul_f32 v[80:81], v[80:81], v[164:165]
	v_lshlrev_b32_e32 v250, 16, v226
	v_and_b32_e32 v251, 0xffff0000, v226
	v_lshlrev_b32_e32 v164, 16, v227
	v_and_b32_e32 v165, 0xffff0000, v227
	v_pk_mul_f32 v[74:75], v[74:75], v[250:251]
	v_pk_mul_f32 v[76:77], v[76:77], v[164:165]
	v_lshlrev_b32_e32 v250, 16, v228
	v_and_b32_e32 v251, 0xffff0000, v228
	v_lshlrev_b32_e32 v164, 16, v229
	v_and_b32_e32 v165, 0xffff0000, v229
	v_max_f32_e32 v250, v250, v250
	v_max_f32_e32 v251, v251, v251
	v_max_f32_e32 v164, v164, v164
	v_max_f32_e32 v165, v165, v165
	v_max_f32_e32 v250, 0xda24260, v250
	v_max_f32_e32 v251, 0xda24260, v251
	v_max_f32_e32 v164, 0xda24260, v164
	v_max_f32_e32 v165, 0xda24260, v165
	v_rcp_f32_e32 v250, v250
	v_rcp_f32_e32 v251, v251
	v_rcp_f32_e32 v164, v164
	v_rcp_f32_e32 v165, v165
	v_pk_mul_f32 v[74:75], v[74:75], v[250:251]
	v_pk_mul_f32 v[76:77], v[76:77], v[164:165]
	v_lshlrev_b32_e32 v250, 16, v230
	v_and_b32_e32 v251, 0xffff0000, v230
	v_lshlrev_b32_e32 v164, 16, v231
	v_and_b32_e32 v165, 0xffff0000, v231
	v_pk_mul_f32 v[102:103], v[102:103], v[250:251]
	v_pk_mul_f32 v[104:105], v[104:105], v[164:165]
	v_lshlrev_b32_e32 v250, 16, v232
	v_and_b32_e32 v251, 0xffff0000, v232
	v_lshlrev_b32_e32 v164, 16, v233
	v_and_b32_e32 v165, 0xffff0000, v233
	v_max_f32_e32 v250, v250, v250
	v_max_f32_e32 v251, v251, v251
	v_max_f32_e32 v164, v164, v164
	v_max_f32_e32 v165, v165, v165
	v_max_f32_e32 v250, 0xda24260, v250
	v_max_f32_e32 v251, 0xda24260, v251
	v_max_f32_e32 v164, 0xda24260, v164
	v_max_f32_e32 v165, 0xda24260, v165
	v_rcp_f32_e32 v250, v250
	v_rcp_f32_e32 v251, v251
	v_rcp_f32_e32 v164, v164
	v_rcp_f32_e32 v165, v165
	v_pk_mul_f32 v[102:103], v[102:103], v[250:251]
	v_pk_mul_f32 v[104:105], v[104:105], v[164:165]
	v_lshlrev_b32_e32 v250, 16, v234
	v_and_b32_e32 v251, 0xffff0000, v234
	v_lshlrev_b32_e32 v164, 16, v235
	v_and_b32_e32 v165, 0xffff0000, v235
; __device__ __forceinline__ float bflo(unsigned u) { return __uint_as_float(u << 16); }
; __device__ __forceinline__ float bfhi(unsigned u) { return __uint_as_float(u & 0xffff0000u); }
;     __device__ __forceinline__ void operator()(AccT& acc, const Unit& u, int wr, int wc, int fr, int fq) const {
;     ...
;                     for (int n = 0; n < 2; ++n) {
;                         const int col = u.pn * 256 + bj * 128 + wc * 32 + n * 16 + 4 * fq;
;                         const bf16_t* gp = proj + (size_t)row * NIN + OFF_MG + z * 2048 + col;
;                         const u32x2 ga = *(const u32x2*)gp;
;                         f32x4 v = acc[ai][bj][m][n];
;                         v[0] *= bflo(ga.x); v[1] *= bfhi(ga.x); v[2] *= bflo(ga.y); v[3] *= bfhi(ga.y);
;                         if ((DBG_ZMASK >> z) & 1) v = (f32x4){0.f, 0.f, 0.f, 0.f};
;                         if (z < 2) {
;                             const u32x2 gb = *(const u32x2*)(gp + 2048);
;                             v[0] *= __builtin_amdgcn_rcpf(fmaxf(bflo(gb.x), 1e-30f)); v[1] *= __builtin_amdgcn_rcpf(fmaxf(bfhi(gb.x), 1e-30f));
;                             v[2] *= __builtin_amdgcn_rcpf(fmaxf(bflo(gb.y), 1e-30f)); v[3] *= __builtin_amdgcn_rcpf(fmaxf(bfhi(gb.y), 1e-30f));
;                             acc[ai][bj][m][n] = v;
	v_pk_mul_f32 v[98:99], v[98:99], v[250:251]
	v_pk_mul_f32 v[100:101], v[100:101], v[164:165]
	v_lshlrev_b32_e32 v250, 16, v236
	v_and_b32_e32 v251, 0xffff0000, v236
	v_lshlrev_b32_e32 v164, 16, v237
	v_and_b32_e32 v165, 0xffff0000, v237
	v_max_f32_e32 v250, v250, v250
	v_max_f32_e32 v251, v251, v251
	v_max_f32_e32 v164, v164, v164
	v_max_f32_e32 v165, v165, v165
	v_max_f32_e32 v250, 0xda24260, v250
	v_max_f32_e32 v251, 0xda24260, v251
	v_max_f32_e32 v164, 0xda24260, v164
	v_max_f32_e32 v165, 0xda24260, v165
	v_rcp_f32_e32 v250, v250
	v_rcp_f32_e32 v251, v251
	v_rcp_f32_e32 v164, v164
	v_rcp_f32_e32 v165, v165
	v_pk_mul_f32 v[98:99], v[98:99], v[250:251]
	v_pk_mul_f32 v[100:101], v[100:101], v[164:165]
	v_lshlrev_b32_e32 v250, 16, v238
	v_and_b32_e32 v251, 0xffff0000, v238
	v_lshlrev_b32_e32 v164, 16, v239
	v_and_b32_e32 v165, 0xffff0000, v239
	v_pk_mul_f32 v[70:71], v[70:71], v[250:251]
	v_pk_mul_f32 v[72:73], v[72:73], v[164:165]
	v_lshlrev_b32_e32 v250, 16, v240
	v_and_b32_e32 v251, 0xffff0000, v240
	v_lshlrev_b32_e32 v164, 16, v241
	v_and_b32_e32 v165, 0xffff0000, v241
	v_max_f32_e32 v250, v250, v250
	v_max_f32_e32 v251, v251, v251
	v_max_f32_e32 v164, v164, v164
	v_max_f32_e32 v165, v165, v165
	v_max_f32_e32 v250, 0xda24260, v250
	v_max_f32_e32 v251, 0xda24260, v251
	v_max_f32_e32 v164, 0xda24260, v164
	v_max_f32_e32 v165, 0xda24260, v165
	v_rcp_f32_e32 v250, v250
	v_rcp_f32_e32 v251, v251
	v_rcp_f32_e32 v164, v164
	v_rcp_f32_e32 v165, v165
	v_pk_mul_f32 v[70:71], v[70:71], v[250:251]
	v_pk_mul_f32 v[72:73], v[72:73], v[164:165]
	v_lshlrev_b32_e32 v250, 16, v242
	v_and_b32_e32 v251, 0xffff0000, v242
	v_lshlrev_b32_e32 v164, 16, v243
	v_and_b32_e32 v165, 0xffff0000, v243
	v_pk_mul_f32 v[66:67], v[66:67], v[250:251]
	v_pk_mul_f32 v[68:69], v[68:69], v[164:165]
	v_lshlrev_b32_e32 v250, 16, v244
	v_and_b32_e32 v251, 0xffff0000, v244
	v_lshlrev_b32_e32 v164, 16, v245
	v_and_b32_e32 v165, 0xffff0000, v245
	v_max_f32_e32 v250, v250, v250
	v_max_f32_e32 v251, v251, v251
	v_max_f32_e32 v164, v164, v164
	v_max_f32_e32 v165, v165, v165
	v_max_f32_e32 v250, 0xda24260, v250
	v_max_f32_e32 v251, 0xda24260, v251
	v_max_f32_e32 v164, 0xda24260, v164
	v_max_f32_e32 v165, 0xda24260, v165
	v_rcp_f32_e32 v250, v250
	v_rcp_f32_e32 v251, v251
	v_rcp_f32_e32 v164, v164
	v_rcp_f32_e32 v165, v165
	v_pk_mul_f32 v[66:67], v[66:67], v[250:251]
	v_pk_mul_f32 v[68:69], v[68:69], v[164:165]
	s_mov_b64 s[6:7], 0x390000
	v_lshl_add_u64 v[164:165], v[246:247], 0, s[6:7]
	s_mov_b64 s[6:7], 0x391000
	v_lshl_add_u64 v[250:251], v[246:247], 0, s[6:7]
	global_load_dwordx2 v[156:157], v[164:165], off
	global_load_dwordx2 v[158:159], v[250:251], off
	global_load_dwordx2 v[160:161], v[164:165], off offset:32
	global_load_dwordx2 v[162:163], v[250:251], off offset:32
	global_load_dwordx2 v[172:173], v[164:165], off offset:256
	global_load_dwordx2 v[174:175], v[250:251], off offset:256
	global_load_dwordx2 v[194:195], v[164:165], off offset:288
	global_load_dwordx2 v[196:197], v[250:251], off offset:288
	s_mov_b64 s[6:7], 0x402000
	v_lshl_add_u64 v[164:165], v[246:247], 0, s[6:7]
	s_mov_b64 s[6:7], 0x403000
	v_lshl_add_u64 v[250:251], v[246:247], 0, s[6:7]
	global_load_dwordx2 v[198:199], v[164:165], off
	global_load_dwordx2 v[200:201], v[250:251], off
	global_load_dwordx2 v[202:203], v[164:165], off offset:32
	global_load_dwordx2 v[204:205], v[250:251], off offset:32
	global_load_dwordx2 v[206:207], v[164:165], off offset:256
	global_load_dwordx2 v[208:209], v[250:251], off offset:256
	global_load_dwordx2 v[210:211], v[164:165], off offset:288
	global_load_dwordx2 v[212:213], v[250:251], off offset:288
	s_mov_b64 s[6:7], 0x474000
	v_lshl_add_u64 v[164:165], v[246:247], 0, s[6:7]
	s_mov_b64 s[6:7], 0x475000
	v_lshl_add_u64 v[250:251], v[246:247], 0, s[6:7]
	global_load_dwordx2 v[214:215], v[164:165], off
	global_load_dwordx2 v[216:217], v[250:251], off
	global_load_dwordx2 v[218:219], v[164:165], off offset:32
	global_load_dwordx2 v[220:221], v[250:251], off offset:32
	global_load_dwordx2 v[222:223], v[164:165], off offset:256
	global_load_dwordx2 v[224:225], v[250:251], off offset:256
	global_load_dwordx2 v[226:227], v[164:165], off offset:288
	global_load_dwordx2 v[228:229], v[250:251], off offset:288
	s_mov_b64 s[6:7], 0x4e6000
	v_lshl_add_u64 v[164:165], v[246:247], 0, s[6:7]
	s_mov_b64 s[6:7], 0x4e7000
	v_lshl_add_u64 v[250:251], v[246:247], 0, s[6:7]
	global_load_dwordx2 v[230:231], v[164:165], off
	global_load_dwordx2 v[232:233], v[250:251], off
	global_load_dwordx2 v[234:235], v[164:165], off offset:32
	global_load_dwordx2 v[236:237], v[250:251], off offset:32
	global_load_dwordx2 v[238:239], v[164:165], off offset:256
	global_load_dwordx2 v[240:241], v[250:251], off offset:256
	global_load_dwordx2 v[242:243], v[164:165], off offset:288
	global_load_dwordx2 v[244:245], v[250:251], off offset:288
	s_waitcnt vmcnt(0)
; __device__ __forceinline__ float bflo(unsigned u) { return __uint_as_float(u << 16); }
; __device__ __forceinline__ float bfhi(unsigned u) { return __uint_as_float(u & 0xffff0000u); }
;     __device__ __forceinline__ void operator()(AccT& acc, const Unit& u, int wr, int wc, int fr, int fq) const {
;     ...
;                     for (int n = 0; n < 2; ++n) {
;                         const int col = u.pn * 256 + bj * 128 + wc * 32 + n * 16 + 4 * fq;
;                         const bf16_t* gp = proj + (size_t)row * NIN + OFF_MG + z * 2048 + col;
;                         const u32x2 ga = *(const u32x2*)gp;
;                         f32x4 v = acc[ai][bj][m][n];
;                         v[0] *= bflo(ga.x); v[1] *= bfhi(ga.x); v[2] *= bflo(ga.y); v[3] *= bfhi(ga.y);
;                         if ((DBG_ZMASK >> z) & 1) v = (f32x4){0.f, 0.f, 0.f, 0.f};
;                         if (z < 2) {
;                             const u32x2 gb = *(const u32x2*)(gp + 2048);
;                             v[0] *= __builtin_amdgcn_rcpf(fmaxf(bflo(gb.x), 1e-30f)); v[1] *= __builtin_amdgcn_rcpf(fmaxf(bfhi(gb.x), 1e-30f));
;                             v[2] *= __builtin_amdgcn_rcpf(fmaxf(bflo(gb.y), 1e-30f)); v[3] *= __builtin_amdgcn_rcpf(fmaxf(bfhi(gb.y), 1e-30f));
;                             acc[ai][bj][m][n] = v;
	v_lshlrev_b32_e32 v250, 16, v156
	v_and_b32_e32 v251, 0xffff0000, v156
	v_lshlrev_b32_e32 v164, 16, v157
	v_and_b32_e32 v165, 0xffff0000, v157
	v_pk_mul_f32 v[62:63], v[62:63], v[250:251]
	v_pk_mul_f32 v[64:65], v[64:65], v[164:165]
	v_lshlrev_b32_e32 v250, 16, v158
	v_and_b32_e32 v251, 0xffff0000, v158
	v_lshlrev_b32_e32 v164, 16, v159
	v_and_b32_e32 v165, 0xffff0000, v159
	v_max_f32_e32 v250, v250, v250
	v_max_f32_e32 v251, v251, v251
	v_max_f32_e32 v164, v164, v164
	v_max_f32_e32 v165, v165, v165
	v_max_f32_e32 v250, 0xda24260, v250
	v_max_f32_e32 v251, 0xda24260, v251
	v_max_f32_e32 v164, 0xda24260, v164
	v_max_f32_e32 v165, 0xda24260, v165
	v_rcp_f32_e32 v250, v250
	v_rcp_f32_e32 v251, v251
	v_rcp_f32_e32 v164, v164
	v_rcp_f32_e32 v165, v165
	v_pk_mul_f32 v[62:63], v[62:63], v[250:251]
	v_pk_mul_f32 v[64:65], v[64:65], v[164:165]
	v_lshlrev_b32_e32 v250, 16, v160
	v_and_b32_e32 v251, 0xffff0000, v160
	v_lshlrev_b32_e32 v164, 16, v161
	v_and_b32_e32 v165, 0xffff0000, v161
	v_pk_mul_f32 v[58:59], v[58:59], v[250:251]
	v_pk_mul_f32 v[60:61], v[60:61], v[164:165]
	v_lshlrev_b32_e32 v250, 16, v162
	v_and_b32_e32 v251, 0xffff0000, v162
	v_lshlrev_b32_e32 v164, 16, v163
	v_and_b32_e32 v165, 0xffff0000, v163
	v_max_f32_e32 v250, v250, v250
	v_max_f32_e32 v251, v251, v251
	v_max_f32_e32 v164, v164, v164
	v_max_f32_e32 v165, v165, v165
	v_max_f32_e32 v250, 0xda24260, v250
	v_max_f32_e32 v251, 0xda24260, v251
	v_max_f32_e32 v164, 0xda24260, v164
	v_max_f32_e32 v165, 0xda24260, v165
	v_rcp_f32_e32 v250, v250
	v_rcp_f32_e32 v251, v251
	v_rcp_f32_e32 v164, v164
	v_rcp_f32_e32 v165, v165
	v_pk_mul_f32 v[58:59], v[58:59], v[250:251]
	v_pk_mul_f32 v[60:61], v[60:61], v[164:165]
	v_lshlrev_b32_e32 v250, 16, v172
	v_and_b32_e32 v251, 0xffff0000, v172
	v_lshlrev_b32_e32 v164, 16, v173
	v_and_b32_e32 v165, 0xffff0000, v173
	v_pk_mul_f32 v[30:31], v[30:31], v[250:251]
	v_pk_mul_f32 v[32:33], v[32:33], v[164:165]
	v_lshlrev_b32_e32 v250, 16, v174
	v_and_b32_e32 v251, 0xffff0000, v174
	v_lshlrev_b32_e32 v164, 16, v175
	v_and_b32_e32 v165, 0xffff0000, v175
	v_max_f32_e32 v250, v250, v250
	v_max_f32_e32 v251, v251, v251
	v_max_f32_e32 v164, v164, v164
	v_max_f32_e32 v165, v165, v165
	v_max_f32_e32 v250, 0xda24260, v250
	v_max_f32_e32 v251, 0xda24260, v251
	v_max_f32_e32 v164, 0xda24260, v164
	v_max_f32_e32 v165, 0xda24260, v165
	v_rcp_f32_e32 v250, v250
	v_rcp_f32_e32 v251, v251
	v_rcp_f32_e32 v164, v164
	v_rcp_f32_e32 v165, v165
	v_pk_mul_f32 v[30:31], v[30:31], v[250:251]
	v_pk_mul_f32 v[32:33], v[32:33], v[164:165]
	v_lshlrev_b32_e32 v250, 16, v194
	v_and_b32_e32 v251, 0xffff0000, v194
	v_lshlrev_b32_e32 v164, 16, v195
	v_and_b32_e32 v165, 0xffff0000, v195
	v_pk_mul_f32 v[26:27], v[26:27], v[250:251]
	v_pk_mul_f32 v[28:29], v[28:29], v[164:165]
	v_lshlrev_b32_e32 v250, 16, v196
	v_and_b32_e32 v251, 0xffff0000, v196
	v_lshlrev_b32_e32 v164, 16, v197
	v_and_b32_e32 v165, 0xffff0000, v197
	v_max_f32_e32 v250, v250, v250
	v_max_f32_e32 v251, v251, v251
	v_max_f32_e32 v164, v164, v164
	v_max_f32_e32 v165, v165, v165
	v_max_f32_e32 v250, 0xda24260, v250
	v_max_f32_e32 v251, 0xda24260, v251
	v_max_f32_e32 v164, 0xda24260, v164
	v_max_f32_e32 v165, 0xda24260, v165
	v_rcp_f32_e32 v250, v250
	v_rcp_f32_e32 v251, v251
	v_rcp_f32_e32 v164, v164
	v_rcp_f32_e32 v165, v165
	v_pk_mul_f32 v[26:27], v[26:27], v[250:251]
	v_pk_mul_f32 v[28:29], v[28:29], v[164:165]
	v_lshlrev_b32_e32 v250, 16, v198
	v_and_b32_e32 v251, 0xffff0000, v198
	v_lshlrev_b32_e32 v164, 16, v199
	v_and_b32_e32 v165, 0xffff0000, v199
	v_pk_mul_f32 v[54:55], v[54:55], v[250:251]
	v_pk_mul_f32 v[56:57], v[56:57], v[164:165]
	v_lshlrev_b32_e32 v250, 16, v200
	v_and_b32_e32 v251, 0xffff0000, v200
	v_lshlrev_b32_e32 v164, 16, v201
	v_and_b32_e32 v165, 0xffff0000, v201
	v_max_f32_e32 v250, v250, v250
	v_max_f32_e32 v251, v251, v251
	v_max_f32_e32 v164, v164, v164
	v_max_f32_e32 v165, v165, v165
	v_max_f32_e32 v250, 0xda24260, v250
	v_max_f32_e32 v251, 0xda24260, v251
	v_max_f32_e32 v164, 0xda24260, v164
	v_max_f32_e32 v165, 0xda24260, v165
	v_rcp_f32_e32 v250, v250
	v_rcp_f32_e32 v251, v251
	v_rcp_f32_e32 v164, v164
	v_rcp_f32_e32 v165, v165
	v_pk_mul_f32 v[54:55], v[54:55], v[250:251]
	v_pk_mul_f32 v[56:57], v[56:57], v[164:165]
	v_lshlrev_b32_e32 v250, 16, v202
	v_and_b32_e32 v251, 0xffff0000, v202
	v_lshlrev_b32_e32 v164, 16, v203
	v_and_b32_e32 v165, 0xffff0000, v203
	v_pk_mul_f32 v[50:51], v[50:51], v[250:251]
	v_pk_mul_f32 v[52:53], v[52:53], v[164:165]
	v_lshlrev_b32_e32 v250, 16, v204
	v_and_b32_e32 v251, 0xffff0000, v204
	v_lshlrev_b32_e32 v164, 16, v205
	v_and_b32_e32 v165, 0xffff0000, v205
	v_max_f32_e32 v250, v250, v250
	v_max_f32_e32 v251, v251, v251
	v_max_f32_e32 v164, v164, v164
	v_max_f32_e32 v165, v165, v165
	v_max_f32_e32 v250, 0xda24260, v250
	v_max_f32_e32 v251, 0xda24260, v251
	v_max_f32_e32 v164, 0xda24260, v164
	v_max_f32_e32 v165, 0xda24260, v165
	v_rcp_f32_e32 v250, v250
	v_rcp_f32_e32 v251, v251
	v_rcp_f32_e32 v164, v164
	v_rcp_f32_e32 v165, v165
	v_pk_mul_f32 v[50:51], v[50:51], v[250:251]
	v_pk_mul_f32 v[52:53], v[52:53], v[164:165]
	v_lshlrev_b32_e32 v250, 16, v206
	v_and_b32_e32 v251, 0xffff0000, v206
	v_lshlrev_b32_e32 v164, 16, v207
	v_and_b32_e32 v165, 0xffff0000, v207
	v_pk_mul_f32 v[22:23], v[22:23], v[250:251]
	v_pk_mul_f32 v[24:25], v[24:25], v[164:165]
	v_lshlrev_b32_e32 v250, 16, v208
	v_and_b32_e32 v251, 0xffff0000, v208
	v_lshlrev_b32_e32 v164, 16, v209
	v_and_b32_e32 v165, 0xffff0000, v209
	v_max_f32_e32 v250, v250, v250
	v_max_f32_e32 v251, v251, v251
	v_max_f32_e32 v164, v164, v164
	v_max_f32_e32 v165, v165, v165
	v_max_f32_e32 v250, 0xda24260, v250
; __device__ __forceinline__ float bflo(unsigned u) { return __uint_as_float(u << 16); }
; __device__ __forceinline__ float bfhi(unsigned u) { return __uint_as_float(u & 0xffff0000u); }
;     __device__ __forceinline__ void operator()(AccT& acc, const Unit& u, int wr, int wc, int fr, int fq) const {
;     ...
;                     for (int n = 0; n < 2; ++n) {
;                         const int col = u.pn * 256 + bj * 128 + wc * 32 + n * 16 + 4 * fq;
;                         const bf16_t* gp = proj + (size_t)row * NIN + OFF_MG + z * 2048 + col;
;                         const u32x2 ga = *(const u32x2*)gp;
;                         f32x4 v = acc[ai][bj][m][n];
;                         v[0] *= bflo(ga.x); v[1] *= bfhi(ga.x); v[2] *= bflo(ga.y); v[3] *= bfhi(ga.y);
;                         if ((DBG_ZMASK >> z) & 1) v = (f32x4){0.f, 0.f, 0.f, 0.f};
;                         if (z < 2) {
;                             const u32x2 gb = *(const u32x2*)(gp + 2048);
;                             v[0] *= __builtin_amdgcn_rcpf(fmaxf(bflo(gb.x), 1e-30f)); v[1] *= __builtin_amdgcn_rcpf(fmaxf(bfhi(gb.x), 1e-30f));
;                             v[2] *= __builtin_amdgcn_rcpf(fmaxf(bflo(gb.y), 1e-30f)); v[3] *= __builtin_amdgcn_rcpf(fmaxf(bfhi(gb.y), 1e-30f));
;                             acc[ai][bj][m][n] = v;
	v_max_f32_e32 v251, 0xda24260, v251
	v_max_f32_e32 v164, 0xda24260, v164
	v_max_f32_e32 v165, 0xda24260, v165
	v_rcp_f32_e32 v250, v250
	v_rcp_f32_e32 v251, v251
	v_rcp_f32_e32 v164, v164
	v_rcp_f32_e32 v165, v165
	v_pk_mul_f32 v[22:23], v[22:23], v[250:251]
	v_pk_mul_f32 v[24:25], v[24:25], v[164:165]
	v_lshlrev_b32_e32 v250, 16, v210
	v_and_b32_e32 v251, 0xffff0000, v210
	v_lshlrev_b32_e32 v164, 16, v211
	v_and_b32_e32 v165, 0xffff0000, v211
	v_pk_mul_f32 v[18:19], v[18:19], v[250:251]
	v_pk_mul_f32 v[20:21], v[20:21], v[164:165]
	v_lshlrev_b32_e32 v250, 16, v212
	v_and_b32_e32 v251, 0xffff0000, v212
	v_lshlrev_b32_e32 v164, 16, v213
	v_and_b32_e32 v165, 0xffff0000, v213
	v_max_f32_e32 v250, v250, v250
	v_max_f32_e32 v251, v251, v251
	v_max_f32_e32 v164, v164, v164
	v_max_f32_e32 v165, v165, v165
	v_max_f32_e32 v250, 0xda24260, v250
	v_max_f32_e32 v251, 0xda24260, v251
	v_max_f32_e32 v164, 0xda24260, v164
	v_max_f32_e32 v165, 0xda24260, v165
	v_rcp_f32_e32 v250, v250
	v_rcp_f32_e32 v251, v251
	v_rcp_f32_e32 v164, v164
	v_rcp_f32_e32 v165, v165
	v_pk_mul_f32 v[18:19], v[18:19], v[250:251]
	v_pk_mul_f32 v[20:21], v[20:21], v[164:165]
	v_lshlrev_b32_e32 v250, 16, v214
	v_and_b32_e32 v251, 0xffff0000, v214
	v_lshlrev_b32_e32 v164, 16, v215
	v_and_b32_e32 v165, 0xffff0000, v215
	v_pk_mul_f32 v[46:47], v[46:47], v[250:251]
	v_pk_mul_f32 v[48:49], v[48:49], v[164:165]
	v_lshlrev_b32_e32 v250, 16, v216
	v_and_b32_e32 v251, 0xffff0000, v216
	v_lshlrev_b32_e32 v164, 16, v217
	v_and_b32_e32 v165, 0xffff0000, v217
	v_max_f32_e32 v250, v250, v250
	v_max_f32_e32 v251, v251, v251
	v_max_f32_e32 v164, v164, v164
	v_max_f32_e32 v165, v165, v165
	v_max_f32_e32 v250, 0xda24260, v250
	v_max_f32_e32 v251, 0xda24260, v251
	v_max_f32_e32 v164, 0xda24260, v164
	v_max_f32_e32 v165, 0xda24260, v165
	v_rcp_f32_e32 v250, v250
	v_rcp_f32_e32 v251, v251
	v_rcp_f32_e32 v164, v164
	v_rcp_f32_e32 v165, v165
	v_pk_mul_f32 v[46:47], v[46:47], v[250:251]
	v_pk_mul_f32 v[48:49], v[48:49], v[164:165]
	v_lshlrev_b32_e32 v250, 16, v218
	v_and_b32_e32 v251, 0xffff0000, v218
	v_lshlrev_b32_e32 v164, 16, v219
	v_and_b32_e32 v165, 0xffff0000, v219
	v_pk_mul_f32 v[42:43], v[42:43], v[250:251]
	v_pk_mul_f32 v[44:45], v[44:45], v[164:165]
	v_lshlrev_b32_e32 v250, 16, v220
	v_and_b32_e32 v251, 0xffff0000, v220
	v_lshlrev_b32_e32 v164, 16, v221
	v_and_b32_e32 v165, 0xffff0000, v221
	v_max_f32_e32 v250, v250, v250
	v_max_f32_e32 v251, v251, v251
	v_max_f32_e32 v164, v164, v164
	v_max_f32_e32 v165, v165, v165
	v_max_f32_e32 v250, 0xda24260, v250
	v_max_f32_e32 v251, 0xda24260, v251
	v_max_f32_e32 v164, 0xda24260, v164
	v_max_f32_e32 v165, 0xda24260, v165
	v_rcp_f32_e32 v250, v250
	v_rcp_f32_e32 v251, v251
	v_rcp_f32_e32 v164, v164
	v_rcp_f32_e32 v165, v165
	v_pk_mul_f32 v[42:43], v[42:43], v[250:251]
	v_pk_mul_f32 v[44:45], v[44:45], v[164:165]
	v_lshlrev_b32_e32 v250, 16, v222
	v_and_b32_e32 v251, 0xffff0000, v222
	v_lshlrev_b32_e32 v164, 16, v223
	v_and_b32_e32 v165, 0xffff0000, v223
	v_pk_mul_f32 v[14:15], v[14:15], v[250:251]
	v_pk_mul_f32 v[16:17], v[16:17], v[164:165]
	v_lshlrev_b32_e32 v250, 16, v224
	v_and_b32_e32 v251, 0xffff0000, v224
	v_lshlrev_b32_e32 v164, 16, v225
	v_and_b32_e32 v165, 0xffff0000, v225
	v_max_f32_e32 v250, v250, v250
	v_max_f32_e32 v251, v251, v251
	v_max_f32_e32 v164, v164, v164
	v_max_f32_e32 v165, v165, v165
	v_max_f32_e32 v250, 0xda24260, v250
	v_max_f32_e32 v251, 0xda24260, v251
	v_max_f32_e32 v164, 0xda24260, v164
	v_max_f32_e32 v165, 0xda24260, v165
	v_rcp_f32_e32 v250, v250
	v_rcp_f32_e32 v251, v251
	v_rcp_f32_e32 v164, v164
	v_rcp_f32_e32 v165, v165
	v_pk_mul_f32 v[14:15], v[14:15], v[250:251]
	v_pk_mul_f32 v[16:17], v[16:17], v[164:165]
	v_lshlrev_b32_e32 v250, 16, v226
	v_and_b32_e32 v251, 0xffff0000, v226
	v_lshlrev_b32_e32 v164, 16, v227
	v_and_b32_e32 v165, 0xffff0000, v227
	v_pk_mul_f32 v[10:11], v[10:11], v[250:251]
	v_pk_mul_f32 v[12:13], v[12:13], v[164:165]
	v_lshlrev_b32_e32 v250, 16, v228
	v_and_b32_e32 v251, 0xffff0000, v228
	v_lshlrev_b32_e32 v164, 16, v229
	v_and_b32_e32 v165, 0xffff0000, v229
	v_max_f32_e32 v250, v250, v250
	v_max_f32_e32 v251, v251, v251
	v_max_f32_e32 v164, v164, v164
	v_max_f32_e32 v165, v165, v165
	v_max_f32_e32 v250, 0xda24260, v250
	v_max_f32_e32 v251, 0xda24260, v251
	v_max_f32_e32 v164, 0xda24260, v164
	v_max_f32_e32 v165, 0xda24260, v165
	v_rcp_f32_e32 v250, v250
	v_rcp_f32_e32 v251, v251
	v_rcp_f32_e32 v164, v164
	v_rcp_f32_e32 v165, v165
	v_pk_mul_f32 v[10:11], v[10:11], v[250:251]
	v_pk_mul_f32 v[12:13], v[12:13], v[164:165]
	v_lshlrev_b32_e32 v250, 16, v230
	v_and_b32_e32 v251, 0xffff0000, v230
	v_lshlrev_b32_e32 v164, 16, v231
	v_and_b32_e32 v165, 0xffff0000, v231
	v_pk_mul_f32 v[38:39], v[38:39], v[250:251]
	v_pk_mul_f32 v[40:41], v[40:41], v[164:165]
	v_lshlrev_b32_e32 v250, 16, v232
	v_and_b32_e32 v251, 0xffff0000, v232
	v_lshlrev_b32_e32 v164, 16, v233
	v_and_b32_e32 v165, 0xffff0000, v233
	v_max_f32_e32 v250, v250, v250
	v_max_f32_e32 v251, v251, v251
	v_max_f32_e32 v164, v164, v164
	v_max_f32_e32 v165, v165, v165
	v_max_f32_e32 v250, 0xda24260, v250
	v_max_f32_e32 v251, 0xda24260, v251
	v_max_f32_e32 v164, 0xda24260, v164
	v_max_f32_e32 v165, 0xda24260, v165
	v_rcp_f32_e32 v250, v250
	v_rcp_f32_e32 v251, v251
	v_rcp_f32_e32 v164, v164
	v_rcp_f32_e32 v165, v165
	v_pk_mul_f32 v[38:39], v[38:39], v[250:251]
	v_pk_mul_f32 v[40:41], v[40:41], v[164:165]
	v_lshlrev_b32_e32 v250, 16, v234
	v_and_b32_e32 v251, 0xffff0000, v234
	v_lshlrev_b32_e32 v164, 16, v235
	v_and_b32_e32 v165, 0xffff0000, v235
	v_pk_mul_f32 v[34:35], v[34:35], v[250:251]
	v_pk_mul_f32 v[36:37], v[36:37], v[164:165]
; __device__ __forceinline__ unsigned cvt_pk_bf16(float lo, float hi) { const f32x2 v = {lo, hi}; const bf16x2_t b = __builtin_convertvector(v, bf16x2_t); return __builtin_bit_cast(unsigned, b); }
; __device__ __forceinline__ float bflo(unsigned u) { return __uint_as_float(u << 16); }
; __device__ __forceinline__ float bfhi(unsigned u) { return __uint_as_float(u & 0xffff0000u); }
;     __device__ __forceinline__ void operator()(AccT& acc, const Unit& u, int wr, int wc, int fr, int fq) const {
;     ...
;                         if (z < 2) {
;                             const u32x2 gb = *(const u32x2*)(gp + 2048);
;                             v[0] *= __builtin_amdgcn_rcpf(fmaxf(bflo(gb.x), 1e-30f)); v[1] *= __builtin_amdgcn_rcpf(fmaxf(bfhi(gb.x), 1e-30f));
;                             v[2] *= __builtin_amdgcn_rcpf(fmaxf(bflo(gb.y), 1e-30f)); v[3] *= __builtin_amdgcn_rcpf(fmaxf(bfhi(gb.y), 1e-30f));
;                             acc[ai][bj][m][n] = v;
;                         } else { u32x2 w; w.x = cvt_pk_bf16(v[0], v[1]); w.y = cvt_pk_bf16(v[2], v[3]); *(u32x2*)(O + (size_t)row * DM + col) = w; }
	v_lshlrev_b32_e32 v250, 16, v236
	v_and_b32_e32 v251, 0xffff0000, v236
	v_lshlrev_b32_e32 v164, 16, v237
	v_and_b32_e32 v165, 0xffff0000, v237
	v_max_f32_e32 v250, v250, v250
	v_max_f32_e32 v251, v251, v251
	v_max_f32_e32 v164, v164, v164
	v_max_f32_e32 v165, v165, v165
	v_max_f32_e32 v250, 0xda24260, v250
	v_max_f32_e32 v251, 0xda24260, v251
	v_max_f32_e32 v164, 0xda24260, v164
	v_max_f32_e32 v165, 0xda24260, v165
	v_rcp_f32_e32 v250, v250
	v_rcp_f32_e32 v251, v251
	v_rcp_f32_e32 v164, v164
	v_rcp_f32_e32 v165, v165
	v_pk_mul_f32 v[34:35], v[34:35], v[250:251]
	v_pk_mul_f32 v[36:37], v[36:37], v[164:165]
	v_lshlrev_b32_e32 v250, 16, v238
	v_and_b32_e32 v251, 0xffff0000, v238
	v_lshlrev_b32_e32 v164, 16, v239
	v_and_b32_e32 v165, 0xffff0000, v239
	v_pk_mul_f32 v[6:7], v[6:7], v[250:251]
	v_pk_mul_f32 v[8:9], v[8:9], v[164:165]
	v_lshlrev_b32_e32 v250, 16, v240
	v_and_b32_e32 v251, 0xffff0000, v240
	v_lshlrev_b32_e32 v164, 16, v241
	v_and_b32_e32 v165, 0xffff0000, v241
	v_max_f32_e32 v250, v250, v250
	v_max_f32_e32 v251, v251, v251
	v_max_f32_e32 v164, v164, v164
	v_max_f32_e32 v165, v165, v165
	v_max_f32_e32 v250, 0xda24260, v250
	v_max_f32_e32 v251, 0xda24260, v251
	v_max_f32_e32 v164, 0xda24260, v164
	v_max_f32_e32 v165, 0xda24260, v165
	v_rcp_f32_e32 v250, v250
	v_rcp_f32_e32 v251, v251
	v_rcp_f32_e32 v164, v164
	v_rcp_f32_e32 v165, v165
	v_pk_mul_f32 v[6:7], v[6:7], v[250:251]
	v_pk_mul_f32 v[8:9], v[8:9], v[164:165]
	v_lshlrev_b32_e32 v250, 16, v242
	v_and_b32_e32 v251, 0xffff0000, v242
	v_lshlrev_b32_e32 v164, 16, v243
	v_and_b32_e32 v165, 0xffff0000, v243
	v_pk_mul_f32 v[2:3], v[2:3], v[250:251]
	v_pk_mul_f32 v[4:5], v[4:5], v[164:165]
	v_lshlrev_b32_e32 v250, 16, v244
	v_and_b32_e32 v251, 0xffff0000, v244
	v_lshlrev_b32_e32 v164, 16, v245
	v_and_b32_e32 v165, 0xffff0000, v245
	v_max_f32_e32 v250, v250, v250
	v_max_f32_e32 v251, v251, v251
	v_max_f32_e32 v164, v164, v164
	v_max_f32_e32 v165, v165, v165
	v_max_f32_e32 v250, 0xda24260, v250
	v_max_f32_e32 v251, 0xda24260, v251
	v_max_f32_e32 v164, 0xda24260, v164
	v_max_f32_e32 v165, 0xda24260, v165
	v_rcp_f32_e32 v250, v250
	v_rcp_f32_e32 v251, v251
	v_rcp_f32_e32 v164, v164
	v_rcp_f32_e32 v165, v165
	v_pk_mul_f32 v[2:3], v[2:3], v[250:251]
	v_pk_mul_f32 v[4:5], v[4:5], v[164:165]
	s_branch .Lmerge_done
.Lmerge_last:
	global_load_dwordx2 v[156:157], v[246:247], off
	global_load_dwordx2 v[160:161], v[246:247], off offset:32
	global_load_dwordx2 v[172:173], v[246:247], off offset:256
	global_load_dwordx2 v[194:195], v[246:247], off offset:288
	s_mov_b64 s[6:7], 0x72000
	v_lshl_add_u64 v[164:165], v[246:247], 0, s[6:7]
	global_load_dwordx2 v[198:199], v[164:165], off
	global_load_dwordx2 v[202:203], v[164:165], off offset:32
	global_load_dwordx2 v[206:207], v[164:165], off offset:256
	global_load_dwordx2 v[210:211], v[164:165], off offset:288
	s_mov_b64 s[6:7], 0xe4000
	v_lshl_add_u64 v[250:251], v[246:247], 0, s[6:7]
	global_load_dwordx2 v[214:215], v[250:251], off
	global_load_dwordx2 v[218:219], v[250:251], off offset:32
	global_load_dwordx2 v[222:223], v[250:251], off offset:256
	global_load_dwordx2 v[226:227], v[250:251], off offset:288
	s_mov_b64 s[6:7], 0x156000
	v_lshl_add_u64 v[164:165], v[246:247], 0, s[6:7]
	global_load_dwordx2 v[230:231], v[164:165], off
	global_load_dwordx2 v[234:235], v[164:165], off offset:32
	global_load_dwordx2 v[238:239], v[164:165], off offset:256
	global_load_dwordx2 v[242:243], v[164:165], off offset:288
	s_waitcnt vmcnt(0)
	v_lshlrev_b32_e32 v250, 16, v156
	v_and_b32_e32 v251, 0xffff0000, v156
	v_lshlrev_b32_e32 v164, 16, v157
	v_and_b32_e32 v165, 0xffff0000, v157
	v_pk_mul_f32 v[126:127], v[126:127], v[250:251]
	v_pk_mul_f32 v[128:129], v[128:129], v[164:165]
	s_nop 1
	v_cvt_pk_bf16_f32 v158, v126, v127
	v_cvt_pk_bf16_f32 v159, v128, v129
	global_store_dwordx2 v[248:249], v[158:159], off
	v_lshlrev_b32_e32 v250, 16, v160
	v_and_b32_e32 v251, 0xffff0000, v160
	v_lshlrev_b32_e32 v164, 16, v161
	v_and_b32_e32 v165, 0xffff0000, v161
	v_pk_mul_f32 v[122:123], v[122:123], v[250:251]
	v_pk_mul_f32 v[124:125], v[124:125], v[164:165]
	s_nop 1
	v_cvt_pk_bf16_f32 v162, v122, v123
	v_cvt_pk_bf16_f32 v163, v124, v125
	global_store_dwordx2 v[248:249], v[162:163], off offset:32
	v_lshlrev_b32_e32 v250, 16, v172
	v_and_b32_e32 v251, 0xffff0000, v172
	v_lshlrev_b32_e32 v164, 16, v173
	v_and_b32_e32 v165, 0xffff0000, v173
	v_pk_mul_f32 v[94:95], v[94:95], v[250:251]
	v_pk_mul_f32 v[96:97], v[96:97], v[164:165]
	s_nop 1
	v_cvt_pk_bf16_f32 v174, v94, v95
	v_cvt_pk_bf16_f32 v175, v96, v97
	global_store_dwordx2 v[248:249], v[174:175], off offset:256
	v_lshlrev_b32_e32 v250, 16, v194
	v_and_b32_e32 v251, 0xffff0000, v194
	v_lshlrev_b32_e32 v164, 16, v195
	v_and_b32_e32 v165, 0xffff0000, v195
	v_pk_mul_f32 v[90:91], v[90:91], v[250:251]
	v_pk_mul_f32 v[92:93], v[92:93], v[164:165]
	s_nop 1
	v_cvt_pk_bf16_f32 v196, v90, v91
	v_cvt_pk_bf16_f32 v197, v92, v93
	global_store_dwordx2 v[248:249], v[196:197], off offset:288
	s_mov_b64 s[6:7], 0x10000
	v_lshl_add_u64 v[136:137], v[248:249], 0, s[6:7]
	v_lshlrev_b32_e32 v250, 16, v198
	v_and_b32_e32 v251, 0xffff0000, v198
	v_lshlrev_b32_e32 v164, 16, v199
	v_and_b32_e32 v165, 0xffff0000, v199
	v_pk_mul_f32 v[118:119], v[118:119], v[250:251]
	v_pk_mul_f32 v[120:121], v[120:121], v[164:165]
	s_nop 1
	v_cvt_pk_bf16_f32 v200, v118, v119
	v_cvt_pk_bf16_f32 v201, v120, v121
	global_store_dwordx2 v[136:137], v[200:201], off
	v_lshlrev_b32_e32 v250, 16, v202
	v_and_b32_e32 v251, 0xffff0000, v202
	v_lshlrev_b32_e32 v164, 16, v203
	v_and_b32_e32 v165, 0xffff0000, v203
	v_pk_mul_f32 v[114:115], v[114:115], v[250:251]
; __device__ __forceinline__ unsigned cvt_pk_bf16(float lo, float hi) { const f32x2 v = {lo, hi}; const bf16x2_t b = __builtin_convertvector(v, bf16x2_t); return __builtin_bit_cast(unsigned, b); }
; __device__ __forceinline__ float bflo(unsigned u) { return __uint_as_float(u << 16); }
; __device__ __forceinline__ float bfhi(unsigned u) { return __uint_as_float(u & 0xffff0000u); }
;     __device__ __forceinline__ void operator()(AccT& acc, const Unit& u, int wr, int wc, int fr, int fq) const {
;     ...
;                     for (int n = 0; n < 2; ++n) {
;                         const int col = u.pn * 256 + bj * 128 + wc * 32 + n * 16 + 4 * fq;
;                         const bf16_t* gp = proj + (size_t)row * NIN + OFF_MG + z * 2048 + col;
;                         const u32x2 ga = *(const u32x2*)gp;
;                         f32x4 v = acc[ai][bj][m][n];
;                         v[0] *= bflo(ga.x); v[1] *= bfhi(ga.x); v[2] *= bflo(ga.y); v[3] *= bfhi(ga.y);
;                         if ((DBG_ZMASK >> z) & 1) v = (f32x4){0.f, 0.f, 0.f, 0.f};
;                         if (z < 2) {
;                             const u32x2 gb = *(const u32x2*)(gp + 2048);
;                             v[0] *= __builtin_amdgcn_rcpf(fmaxf(bflo(gb.x), 1e-30f)); v[1] *= __builtin_amdgcn_rcpf(fmaxf(bfhi(gb.x), 1e-30f));
;                             v[2] *= __builtin_amdgcn_rcpf(fmaxf(bflo(gb.y), 1e-30f)); v[3] *= __builtin_amdgcn_rcpf(fmaxf(bfhi(gb.y), 1e-30f));
;                             acc[ai][bj][m][n] = v;
;                         } else { u32x2 w; w.x = cvt_pk_bf16(v[0], v[1]); w.y = cvt_pk_bf16(v[2], v[3]); *(u32x2*)(O + (size_t)row * DM + col) = w; }
	v_pk_mul_f32 v[116:117], v[116:117], v[164:165]
	s_nop 1
	v_cvt_pk_bf16_f32 v204, v114, v115
	v_cvt_pk_bf16_f32 v205, v116, v117
	global_store_dwordx2 v[136:137], v[204:205], off offset:32
	v_lshlrev_b32_e32 v250, 16, v206
	v_and_b32_e32 v251, 0xffff0000, v206
	v_lshlrev_b32_e32 v164, 16, v207
	v_and_b32_e32 v165, 0xffff0000, v207
	v_pk_mul_f32 v[86:87], v[86:87], v[250:251]
	v_pk_mul_f32 v[88:89], v[88:89], v[164:165]
	s_nop 1
	v_cvt_pk_bf16_f32 v208, v86, v87
	v_cvt_pk_bf16_f32 v209, v88, v89
	global_store_dwordx2 v[136:137], v[208:209], off offset:256
	v_lshlrev_b32_e32 v250, 16, v210
	v_and_b32_e32 v251, 0xffff0000, v210
	v_lshlrev_b32_e32 v164, 16, v211
	v_and_b32_e32 v165, 0xffff0000, v211
	v_pk_mul_f32 v[82:83], v[82:83], v[250:251]
	v_pk_mul_f32 v[84:85], v[84:85], v[164:165]
	s_nop 1
	v_cvt_pk_bf16_f32 v212, v82, v83
	v_cvt_pk_bf16_f32 v213, v84, v85
	global_store_dwordx2 v[136:137], v[212:213], off offset:288
	s_mov_b64 s[6:7], 0x20000
	v_lshl_add_u64 v[136:137], v[248:249], 0, s[6:7]
	v_lshlrev_b32_e32 v250, 16, v214
	v_and_b32_e32 v251, 0xffff0000, v214
	v_lshlrev_b32_e32 v164, 16, v215
	v_and_b32_e32 v165, 0xffff0000, v215
	v_pk_mul_f32 v[110:111], v[110:111], v[250:251]
	v_pk_mul_f32 v[112:113], v[112:113], v[164:165]
	s_nop 1
	v_cvt_pk_bf16_f32 v216, v110, v111
	v_cvt_pk_bf16_f32 v217, v112, v113
	global_store_dwordx2 v[136:137], v[216:217], off
	v_lshlrev_b32_e32 v250, 16, v218
	v_and_b32_e32 v251, 0xffff0000, v218
	v_lshlrev_b32_e32 v164, 16, v219
	v_and_b32_e32 v165, 0xffff0000, v219
	v_pk_mul_f32 v[106:107], v[106:107], v[250:251]
	v_pk_mul_f32 v[108:109], v[108:109], v[164:165]
	s_nop 1
	v_cvt_pk_bf16_f32 v220, v106, v107
	v_cvt_pk_bf16_f32 v221, v108, v109
	global_store_dwordx2 v[136:137], v[220:221], off offset:32
	v_lshlrev_b32_e32 v250, 16, v222
	v_and_b32_e32 v251, 0xffff0000, v222
	v_lshlrev_b32_e32 v164, 16, v223
	v_and_b32_e32 v165, 0xffff0000, v223
	v_pk_mul_f32 v[78:79], v[78:79], v[250:251]
	v_pk_mul_f32 v[80:81], v[80:81], v[164:165]
	s_nop 1
	v_cvt_pk_bf16_f32 v224, v78, v79
	v_cvt_pk_bf16_f32 v225, v80, v81
	global_store_dwordx2 v[136:137], v[224:225], off offset:256
	v_lshlrev_b32_e32 v250, 16, v226
	v_and_b32_e32 v251, 0xffff0000, v226
	v_lshlrev_b32_e32 v164, 16, v227
	v_and_b32_e32 v165, 0xffff0000, v227
	v_pk_mul_f32 v[74:75], v[74:75], v[250:251]
	v_pk_mul_f32 v[76:77], v[76:77], v[164:165]
	s_nop 1
	v_cvt_pk_bf16_f32 v228, v74, v75
	v_cvt_pk_bf16_f32 v229, v76, v77
	global_store_dwordx2 v[136:137], v[228:229], off offset:288
	s_mov_b64 s[6:7], 0x30000
	v_lshl_add_u64 v[136:137], v[248:249], 0, s[6:7]
	v_lshlrev_b32_e32 v250, 16, v230
	v_and_b32_e32 v251, 0xffff0000, v230
	v_lshlrev_b32_e32 v164, 16, v231
	v_and_b32_e32 v165, 0xffff0000, v231
	v_pk_mul_f32 v[102:103], v[102:103], v[250:251]
	v_pk_mul_f32 v[104:105], v[104:105], v[164:165]
	s_nop 1
	v_cvt_pk_bf16_f32 v232, v102, v103
	v_cvt_pk_bf16_f32 v233, v104, v105
	global_store_dwordx2 v[136:137], v[232:233], off
	v_lshlrev_b32_e32 v250, 16, v234
	v_and_b32_e32 v251, 0xffff0000, v234
	v_lshlrev_b32_e32 v164, 16, v235
	v_and_b32_e32 v165, 0xffff0000, v235
	v_pk_mul_f32 v[98:99], v[98:99], v[250:251]
	v_pk_mul_f32 v[100:101], v[100:101], v[164:165]
	s_nop 1
	v_cvt_pk_bf16_f32 v236, v98, v99
	v_cvt_pk_bf16_f32 v237, v100, v101
	global_store_dwordx2 v[136:137], v[236:237], off offset:32
	v_lshlrev_b32_e32 v250, 16, v238
	v_and_b32_e32 v251, 0xffff0000, v238
	v_lshlrev_b32_e32 v164, 16, v239
	v_and_b32_e32 v165, 0xffff0000, v239
	v_pk_mul_f32 v[70:71], v[70:71], v[250:251]
	v_pk_mul_f32 v[72:73], v[72:73], v[164:165]
	s_nop 1
	v_cvt_pk_bf16_f32 v240, v70, v71
	v_cvt_pk_bf16_f32 v241, v72, v73
	global_store_dwordx2 v[136:137], v[240:241], off offset:256
	v_lshlrev_b32_e32 v250, 16, v242
	v_and_b32_e32 v251, 0xffff0000, v242
	v_lshlrev_b32_e32 v164, 16, v243
	v_and_b32_e32 v165, 0xffff0000, v243
	v_pk_mul_f32 v[66:67], v[66:67], v[250:251]
	v_pk_mul_f32 v[68:69], v[68:69], v[164:165]
	s_nop 1
	v_cvt_pk_bf16_f32 v244, v66, v67
	v_cvt_pk_bf16_f32 v245, v68, v69
	global_store_dwordx2 v[136:137], v[244:245], off offset:288
	s_mov_b64 s[6:7], 0x390000
	v_lshl_add_u64 v[250:251], v[246:247], 0, s[6:7]
	global_load_dwordx2 v[156:157], v[250:251], off
	global_load_dwordx2 v[160:161], v[250:251], off offset:32
	global_load_dwordx2 v[172:173], v[250:251], off offset:256
	global_load_dwordx2 v[194:195], v[250:251], off offset:288
	s_mov_b64 s[6:7], 0x402000
	v_lshl_add_u64 v[164:165], v[246:247], 0, s[6:7]
	global_load_dwordx2 v[198:199], v[164:165], off
	global_load_dwordx2 v[202:203], v[164:165], off offset:32
	global_load_dwordx2 v[206:207], v[164:165], off offset:256
	global_load_dwordx2 v[210:211], v[164:165], off offset:288
	s_mov_b64 s[6:7], 0x474000
	v_lshl_add_u64 v[250:251], v[246:247], 0, s[6:7]
	global_load_dwordx2 v[214:215], v[250:251], off
	global_load_dwordx2 v[218:219], v[250:251], off offset:32
	global_load_dwordx2 v[222:223], v[250:251], off offset:256
	global_load_dwordx2 v[226:227], v[250:251], off offset:288
	s_mov_b64 s[6:7], 0x4e6000
	v_lshl_add_u64 v[164:165], v[246:247], 0, s[6:7]
	global_load_dwordx2 v[230:231], v[164:165], off
	global_load_dwordx2 v[234:235], v[164:165], off offset:32
	global_load_dwordx2 v[238:239], v[164:165], off offset:256
	global_load_dwordx2 v[242:243], v[164:165], off offset:288
	s_waitcnt vmcnt(0)
; __device__ __forceinline__ unsigned cvt_pk_bf16(float lo, float hi) { const f32x2 v = {lo, hi}; const bf16x2_t b = __builtin_convertvector(v, bf16x2_t); return __builtin_bit_cast(unsigned, b); }
; __device__ __forceinline__ float bflo(unsigned u) { return __uint_as_float(u << 16); }
; __device__ __forceinline__ float bfhi(unsigned u) { return __uint_as_float(u & 0xffff0000u); }
;     __device__ __forceinline__ void operator()(AccT& acc, const Unit& u, int wr, int wc, int fr, int fq) const {
;     ...
;                     for (int n = 0; n < 2; ++n) {
;                         const int col = u.pn * 256 + bj * 128 + wc * 32 + n * 16 + 4 * fq;
;                         const bf16_t* gp = proj + (size_t)row * NIN + OFF_MG + z * 2048 + col;
;                         const u32x2 ga = *(const u32x2*)gp;
;                         f32x4 v = acc[ai][bj][m][n];
;                         v[0] *= bflo(ga.x); v[1] *= bfhi(ga.x); v[2] *= bflo(ga.y); v[3] *= bfhi(ga.y);
;                         if ((DBG_ZMASK >> z) & 1) v = (f32x4){0.f, 0.f, 0.f, 0.f};
;                         if (z < 2) {
;                             const u32x2 gb = *(const u32x2*)(gp + 2048);
;                             v[0] *= __builtin_amdgcn_rcpf(fmaxf(bflo(gb.x), 1e-30f)); v[1] *= __builtin_amdgcn_rcpf(fmaxf(bfhi(gb.x), 1e-30f));
;                             v[2] *= __builtin_amdgcn_rcpf(fmaxf(bflo(gb.y), 1e-30f)); v[3] *= __builtin_amdgcn_rcpf(fmaxf(bfhi(gb.y), 1e-30f));
;                             acc[ai][bj][m][n] = v;
;                         } else { u32x2 w; w.x = cvt_pk_bf16(v[0], v[1]); w.y = cvt_pk_bf16(v[2], v[3]); *(u32x2*)(O + (size_t)row * DM + col) = w; }
	s_mov_b64 s[6:7], 0x80000
	v_lshl_add_u64 v[136:137], v[248:249], 0, s[6:7]
	v_lshlrev_b32_e32 v250, 16, v156
	v_and_b32_e32 v251, 0xffff0000, v156
	v_lshlrev_b32_e32 v164, 16, v157
	v_and_b32_e32 v165, 0xffff0000, v157
	v_pk_mul_f32 v[62:63], v[62:63], v[250:251]
	v_pk_mul_f32 v[64:65], v[64:65], v[164:165]
	s_nop 1
	v_cvt_pk_bf16_f32 v158, v62, v63
	v_cvt_pk_bf16_f32 v159, v64, v65
	global_store_dwordx2 v[136:137], v[158:159], off
	v_lshlrev_b32_e32 v250, 16, v160
	v_and_b32_e32 v251, 0xffff0000, v160
	v_lshlrev_b32_e32 v164, 16, v161
	v_and_b32_e32 v165, 0xffff0000, v161
	v_pk_mul_f32 v[58:59], v[58:59], v[250:251]
	v_pk_mul_f32 v[60:61], v[60:61], v[164:165]
	s_nop 1
	v_cvt_pk_bf16_f32 v162, v58, v59
	v_cvt_pk_bf16_f32 v163, v60, v61
	global_store_dwordx2 v[136:137], v[162:163], off offset:32
	v_lshlrev_b32_e32 v250, 16, v172
	v_and_b32_e32 v251, 0xffff0000, v172
	v_lshlrev_b32_e32 v164, 16, v173
	v_and_b32_e32 v165, 0xffff0000, v173
	v_pk_mul_f32 v[30:31], v[30:31], v[250:251]
	v_pk_mul_f32 v[32:33], v[32:33], v[164:165]
	s_nop 1
	v_cvt_pk_bf16_f32 v174, v30, v31
	v_cvt_pk_bf16_f32 v175, v32, v33
	global_store_dwordx2 v[136:137], v[174:175], off offset:256
	v_lshlrev_b32_e32 v250, 16, v194
	v_and_b32_e32 v251, 0xffff0000, v194
	v_lshlrev_b32_e32 v164, 16, v195
	v_and_b32_e32 v165, 0xffff0000, v195
	v_pk_mul_f32 v[26:27], v[26:27], v[250:251]
	v_pk_mul_f32 v[28:29], v[28:29], v[164:165]
	s_nop 1
	v_cvt_pk_bf16_f32 v196, v26, v27
	v_cvt_pk_bf16_f32 v197, v28, v29
	global_store_dwordx2 v[136:137], v[196:197], off offset:288
	s_mov_b64 s[6:7], 0x90000
	v_lshl_add_u64 v[136:137], v[248:249], 0, s[6:7]
	v_lshlrev_b32_e32 v250, 16, v198
	v_and_b32_e32 v251, 0xffff0000, v198
	v_lshlrev_b32_e32 v164, 16, v199
	v_and_b32_e32 v165, 0xffff0000, v199
	v_pk_mul_f32 v[54:55], v[54:55], v[250:251]
	v_pk_mul_f32 v[56:57], v[56:57], v[164:165]
	s_nop 1
	v_cvt_pk_bf16_f32 v200, v54, v55
	v_cvt_pk_bf16_f32 v201, v56, v57
	global_store_dwordx2 v[136:137], v[200:201], off
	v_lshlrev_b32_e32 v250, 16, v202
	v_and_b32_e32 v251, 0xffff0000, v202
	v_lshlrev_b32_e32 v164, 16, v203
	v_and_b32_e32 v165, 0xffff0000, v203
	v_pk_mul_f32 v[50:51], v[50:51], v[250:251]
	v_pk_mul_f32 v[52:53], v[52:53], v[164:165]
	s_nop 1
	v_cvt_pk_bf16_f32 v204, v50, v51
	v_cvt_pk_bf16_f32 v205, v52, v53
	global_store_dwordx2 v[136:137], v[204:205], off offset:32
	v_lshlrev_b32_e32 v250, 16, v206
	v_and_b32_e32 v251, 0xffff0000, v206
	v_lshlrev_b32_e32 v164, 16, v207
	v_and_b32_e32 v165, 0xffff0000, v207
	v_pk_mul_f32 v[22:23], v[22:23], v[250:251]
	v_pk_mul_f32 v[24:25], v[24:25], v[164:165]
	s_nop 1
	v_cvt_pk_bf16_f32 v208, v22, v23
	v_cvt_pk_bf16_f32 v209, v24, v25
	global_store_dwordx2 v[136:137], v[208:209], off offset:256
	v_lshlrev_b32_e32 v250, 16, v210
	v_and_b32_e32 v251, 0xffff0000, v210
	v_lshlrev_b32_e32 v164, 16, v211
	v_and_b32_e32 v165, 0xffff0000, v211
	v_pk_mul_f32 v[18:19], v[18:19], v[250:251]
	v_pk_mul_f32 v[20:21], v[20:21], v[164:165]
	s_nop 1
	v_cvt_pk_bf16_f32 v212, v18, v19
	v_cvt_pk_bf16_f32 v213, v20, v21
	global_store_dwordx2 v[136:137], v[212:213], off offset:288
	s_mov_b64 s[6:7], 0xa0000
	v_lshl_add_u64 v[136:137], v[248:249], 0, s[6:7]
	v_lshlrev_b32_e32 v250, 16, v214
	v_and_b32_e32 v251, 0xffff0000, v214
	v_lshlrev_b32_e32 v164, 16, v215
	v_and_b32_e32 v165, 0xffff0000, v215
	v_pk_mul_f32 v[46:47], v[46:47], v[250:251]
	v_pk_mul_f32 v[48:49], v[48:49], v[164:165]
	s_nop 1
	v_cvt_pk_bf16_f32 v216, v46, v47
	v_cvt_pk_bf16_f32 v217, v48, v49
	global_store_dwordx2 v[136:137], v[216:217], off
	v_lshlrev_b32_e32 v250, 16, v218
	v_and_b32_e32 v251, 0xffff0000, v218
	v_lshlrev_b32_e32 v164, 16, v219
	v_and_b32_e32 v165, 0xffff0000, v219
	v_pk_mul_f32 v[42:43], v[42:43], v[250:251]
	v_pk_mul_f32 v[44:45], v[44:45], v[164:165]
	s_nop 1
	v_cvt_pk_bf16_f32 v220, v42, v43
	v_cvt_pk_bf16_f32 v221, v44, v45
	global_store_dwordx2 v[136:137], v[220:221], off offset:32
	v_lshlrev_b32_e32 v250, 16, v222
	v_and_b32_e32 v251, 0xffff0000, v222
	v_lshlrev_b32_e32 v164, 16, v223
	v_and_b32_e32 v165, 0xffff0000, v223
	v_pk_mul_f32 v[14:15], v[14:15], v[250:251]
	v_pk_mul_f32 v[16:17], v[16:17], v[164:165]
	s_nop 1
	v_cvt_pk_bf16_f32 v224, v14, v15
	v_cvt_pk_bf16_f32 v225, v16, v17
	global_store_dwordx2 v[136:137], v[224:225], off offset:256
	v_lshlrev_b32_e32 v250, 16, v226
	v_and_b32_e32 v251, 0xffff0000, v226
	v_lshlrev_b32_e32 v164, 16, v227
	v_and_b32_e32 v165, 0xffff0000, v227
	v_pk_mul_f32 v[10:11], v[10:11], v[250:251]
	v_pk_mul_f32 v[12:13], v[12:13], v[164:165]
	s_nop 1
	v_cvt_pk_bf16_f32 v228, v10, v11
	v_cvt_pk_bf16_f32 v229, v12, v13
	global_store_dwordx2 v[136:137], v[228:229], off offset:288
	s_mov_b64 s[6:7], 0xb0000
	v_lshl_add_u64 v[136:137], v[248:249], 0, s[6:7]
	v_lshlrev_b32_e32 v250, 16, v230
	v_and_b32_e32 v251, 0xffff0000, v230
	v_lshlrev_b32_e32 v164, 16, v231
	v_and_b32_e32 v165, 0xffff0000, v231
	v_pk_mul_f32 v[38:39], v[38:39], v[250:251]
	v_pk_mul_f32 v[40:41], v[40:41], v[164:165]
	s_nop 1
	v_cvt_pk_bf16_f32 v232, v38, v39
	v_cvt_pk_bf16_f32 v233, v40, v41
	global_store_dwordx2 v[136:137], v[232:233], off
	v_lshlrev_b32_e32 v250, 16, v234
	v_and_b32_e32 v251, 0xffff0000, v234
	v_lshlrev_b32_e32 v164, 16, v235
	v_and_b32_e32 v165, 0xffff0000, v235
	v_pk_mul_f32 v[34:35], v[34:35], v[250:251]
	v_pk_mul_f32 v[36:37], v[36:37], v[164:165]
	s_nop 1
	v_cvt_pk_bf16_f32 v236, v34, v35
	v_cvt_pk_bf16_f32 v237, v36, v37
	global_store_dwordx2 v[136:137], v[236:237], off offset:32
	v_lshlrev_b32_e32 v250, 16, v238
	v_and_b32_e32 v251, 0xffff0000, v238
	v_lshlrev_b32_e32 v164, 16, v239
	v_and_b32_e32 v165, 0xffff0000, v239
	v_pk_mul_f32 v[6:7], v[6:7], v[250:251]
	v_pk_mul_f32 v[8:9], v[8:9], v[164:165]
	s_nop 1
	v_cvt_pk_bf16_f32 v240, v6, v7
	v_cvt_pk_bf16_f32 v241, v8, v9
	global_store_dwordx2 v[136:137], v[240:241], off offset:256
	v_lshlrev_b32_e32 v250, 16, v242
	v_and_b32_e32 v251, 0xffff0000, v242
	v_lshlrev_b32_e32 v164, 16, v243
	v_and_b32_e32 v165, 0xffff0000, v243
	v_pk_mul_f32 v[2:3], v[2:3], v[250:251]
	v_pk_mul_f32 v[4:5], v[4:5], v[164:165]
	s_nop 1
	v_cvt_pk_bf16_f32 v244, v2, v3
	v_cvt_pk_bf16_f32 v245, v4, v5
	global_store_dwordx2 v[136:137], v[244:245], off offset:288
; template <class Epi>
; __device__ __forceinline__ void gemm_phase(LAS unsigned char* lds, const Gemm g, const TileOrder& S, const Epi& E) {
;     ...
;         E(acc, cur, wr, wc, fr, fq);
;         if (!has_next) break;
;         if (nxt.z == 0) {
; #pragma unroll
;             for (int a = 0; a < 2; ++a)
; #pragma unroll
;                 for (int b = 0; b < 2; ++b)
; #pragma unroll
;                     for (int m = 0; m < 4; ++m)
; #pragma unroll
;                         for (int n = 0; n < 2; ++n) acc[a][b][m][n] = (f32x4){0.f, 0.f, 0.f, 0.f};
;         }
;         cur = nxt; cA = nA; cB = nB; ++ui;
.Lmerge_done:
	s_mov_b64 s[6:7], -1
	s_and_b64 vcc, exec, s[4:5]
	s_cbranch_vccz .LBB0_1126
	s_branch .LBB0_1264
.LBB0_1264:
	s_andn2_b64 vcc, exec, s[20:21]
	s_cbranch_vccnz .LBB0_1125
	v_mov_b32_e32 v2, 0
	v_mov_b32_e32 v3, v2
	v_mov_b32_e32 v4, v2
	v_mov_b32_e32 v5, v2
	v_mov_b32_e32 v6, v2
	v_mov_b32_e32 v7, v2
	v_mov_b32_e32 v8, v2
	v_mov_b32_e32 v9, v2
	v_mov_b32_e32 v10, v2
	v_mov_b32_e32 v11, v2
	v_mov_b32_e32 v12, v2
	v_mov_b32_e32 v13, v2
	v_mov_b32_e32 v14, v2
	v_mov_b32_e32 v15, v2
	v_mov_b32_e32 v16, v2
	v_mov_b32_e32 v17, v2
	v_mov_b32_e32 v18, v2
	v_mov_b32_e32 v19, v2
	v_mov_b32_e32 v20, v2
	v_mov_b32_e32 v21, v2
	v_mov_b32_e32 v22, v2
	v_mov_b32_e32 v23, v2
	v_mov_b32_e32 v24, v2
	v_mov_b32_e32 v25, v2
	v_mov_b32_e32 v26, v2
	v_mov_b32_e32 v27, v2
	v_mov_b32_e32 v28, v2
	v_mov_b32_e32 v29, v2
	v_mov_b32_e32 v30, v2
	v_mov_b32_e32 v31, v2
	v_mov_b32_e32 v32, v2
	v_mov_b32_e32 v33, v2
	v_mov_b32_e32 v34, v2
	v_mov_b32_e32 v35, v2
	v_mov_b32_e32 v36, v2
	v_mov_b32_e32 v37, v2
	v_mov_b32_e32 v38, v2
	v_mov_b32_e32 v39, v2
	v_mov_b32_e32 v40, v2
	v_mov_b32_e32 v41, v2
	v_mov_b32_e32 v42, v2
	v_mov_b32_e32 v43, v2
	v_mov_b32_e32 v44, v2
	v_mov_b32_e32 v45, v2
	v_mov_b32_e32 v46, v2
	v_mov_b32_e32 v47, v2
	v_mov_b32_e32 v48, v2
	v_mov_b32_e32 v49, v2
	v_mov_b32_e32 v50, v2
	v_mov_b32_e32 v51, v2
	v_mov_b32_e32 v52, v2
	v_mov_b32_e32 v53, v2
	v_mov_b32_e32 v54, v2
	v_mov_b32_e32 v55, v2
	v_mov_b32_e32 v56, v2
	v_mov_b32_e32 v57, v2
	v_mov_b32_e32 v58, v2
	v_mov_b32_e32 v59, v2
	v_mov_b32_e32 v60, v2
	v_mov_b32_e32 v61, v2
	v_mov_b32_e32 v62, v2
	v_mov_b32_e32 v63, v2
	v_mov_b32_e32 v64, v2
	v_mov_b32_e32 v65, v2
	v_mov_b32_e32 v66, v2
	v_mov_b32_e32 v67, v2
	v_mov_b32_e32 v68, v2
	v_mov_b32_e32 v69, v2
	v_mov_b32_e32 v70, v2
	v_mov_b32_e32 v71, v2
	v_mov_b32_e32 v72, v2
	v_mov_b32_e32 v73, v2
	v_mov_b32_e32 v74, v2
	v_mov_b32_e32 v75, v2
	v_mov_b32_e32 v76, v2
	v_mov_b32_e32 v77, v2
	v_mov_b32_e32 v78, v2
	v_mov_b32_e32 v79, v2
	v_mov_b32_e32 v80, v2
	v_mov_b32_e32 v81, v2
	v_mov_b32_e32 v82, v2
	v_mov_b32_e32 v83, v2
	v_mov_b32_e32 v84, v2
	v_mov_b32_e32 v85, v2
	v_mov_b32_e32 v86, v2
	v_mov_b32_e32 v87, v2
	v_mov_b32_e32 v88, v2
	v_mov_b32_e32 v89, v2
	v_mov_b32_e32 v90, v2
	v_mov_b32_e32 v91, v2
	v_mov_b32_e32 v92, v2
	v_mov_b32_e32 v93, v2
	v_mov_b32_e32 v94, v2
	v_mov_b32_e32 v95, v2
	v_mov_b32_e32 v96, v2
	v_mov_b32_e32 v97, v2
	v_mov_b32_e32 v98, v2
	v_mov_b32_e32 v99, v2
	v_mov_b32_e32 v100, v2
	v_mov_b32_e32 v101, v2
	v_mov_b32_e32 v102, v2
	v_mov_b32_e32 v103, v2
	v_mov_b32_e32 v104, v2
	v_mov_b32_e32 v105, v2
	v_mov_b32_e32 v106, v2
	v_mov_b32_e32 v107, v2
	v_mov_b32_e32 v108, v2
	v_mov_b32_e32 v109, v2
	v_mov_b32_e32 v110, v2
	v_mov_b32_e32 v111, v2
	v_mov_b32_e32 v112, v2
	v_mov_b32_e32 v113, v2
	v_mov_b32_e32 v114, v2
	v_mov_b32_e32 v115, v2
	v_mov_b32_e32 v116, v2
	v_mov_b32_e32 v117, v2
	v_mov_b32_e32 v118, v2
	v_mov_b32_e32 v119, v2
	v_mov_b32_e32 v120, v2
	v_mov_b32_e32 v121, v2
	v_mov_b32_e32 v122, v2
	v_mov_b32_e32 v123, v2
	v_mov_b32_e32 v124, v2
	v_mov_b32_e32 v125, v2
	v_mov_b32_e32 v126, v2
	v_mov_b32_e32 v127, v2
	v_mov_b32_e32 v128, v2
	v_mov_b32_e32 v129, v2
	s_branch .LBB0_1125

; template <class Epi>
; __device__ __forceinline__ void gemm_phase(LAS unsigned char* lds, const Gemm g, const TileOrder& S, const Epi& E) {
;     ...
;     for (;;) {
;         const bool has_next = S.next(ui + 1, nxt);
;         const char* nA = has_next ? PG8_BASEA(nxt.z) + (size_t)nxt.pm * tstepA : cA; const char* nB = has_next ? PG8_BASEB(nxt.z) + (size_t)nxt.pn * tstepB : cB;
.LBB0_1335:
	s_and_b64 vcc, exec, s[4:5]
	s_mov_b32 s6, s18
	s_mov_b32 s8, s20
	s_mov_b64 s[28:29], s[24:25]
	s_mov_b64 s[26:27], s[22:23]
	s_cbranch_vccnz .LBB0_1408

; #define PG8_STAGE(bufoff, gbase, voff) do { _Pragma("unroll") for (int _i = 0; _i < 2; ++_i) \
;         __builtin_amdgcn_global_load_lds((const unsigned*)((const char*)(gbase) + (voff)[_i]), (LAS unsigned*)(lds + (bufoff) + ldsw + _i * 8192), 16, 0, 0); } while (0)
; #define PG8_LDA(dst, b, h) do { _Pragma("unroll") for (int m = 0; m < 4; ++m) _Pragma("unroll") for (int k = 0; k < 2; ++k) dst[m][k] = *(const LAS bf16x8*)(lds + PG8_SA(b, h) + aoff + m * 2048 + k * 1024); } while (0)
; #define PG8_LDB(dst, b, h) do { _Pragma("unroll") for (int n = 0; n < 2; ++n) _Pragma("unroll") for (int k = 0; k < 2; ++k) dst[n][k] = *(const LAS bf16x8*)(lds + PG8_SB(b, h) + boff + n * 2048 + k * 1024); } while (0)
; #define PG8_MMA(ai, bj, At, Bt) do { __builtin_amdgcn_s_setprio(1); _Pragma("unroll") for (int m = 0; m < 4; ++m) _Pragma("unroll") for (int n = 0; n < 2; ++n) _Pragma("unroll") for (int k = 0; k < 2; ++k) \
;         acc[ai][bj][m][n] = __builtin_amdgcn_mfma_f32_16x16x32_bf16(Bt[n][k], At[m][k], acc[ai][bj][m][n], 0, 0, 0); __builtin_amdgcn_s_setprio(0); } while (0)
; #define PG8_WAIT_V(n) asm volatile("s_waitcnt vmcnt(" #n ")" ::: "memory")
; #define PG8_WAIT_L(n) asm volatile("s_waitcnt lgkmcnt(" #n ")" ::: "memory")
; #define PG8_BAR __builtin_amdgcn_s_barrier()
; #define PG8_SCHED __builtin_amdgcn_sched_barrier(0)
; template <class Epi>
; __device__ __forceinline__ void gemm_phase(LAS unsigned char* lds, const Gemm g, const TileOrder& S, const Epi& E) {
;     ...
;             PG8_LDB(B0, 0, 0); PG8_SCHED; PG8_LDA(At, 0, 0); PG8_STAGE(PG8_SA(1, 1), a1 + hstepA, voffA);
;             PG8_WAIT_L(8); PG8_BAR; PG8_WAIT_L(0); PG8_MMA(0, 0, At, B0); PG8_BAR; PG8_SCHED;
;             PG8_LDB(B1, 0, 1); PG8_STAGE(PG8_SB(0, 0), b2, voffB);
;             PG8_BAR; PG8_WAIT_L(0); PG8_MMA(0, 1, At, B1); PG8_BAR;
;             PG8_LDA(At, 0, 1); PG8_STAGE(PG8_SA(0, 0), a2, voffA);
;             PG8_BAR; PG8_WAIT_L(0); PG8_MMA(1, 0, At, B0); PG8_BAR; PG8_SCHED;
;             PG8_STAGE(PG8_SB(0, 1), b2 + hstepB, voffB);
;             PG8_WAIT_V(6); PG8_BAR; PG8_MMA(1, 1, At, B1); PG8_BAR;
.LBB0_1343:
	v_add_u32_e32 v136, s64, v162
	ds_read_b128 v[156:159], v136
	ds_read_b128 v[166:169], v136 offset:1024
	ds_read_b128 v[170:173], v136 offset:2048
	ds_read_b128 v[194:197], v136 offset:3072
	s_add_u32 s28, s26, 0xfff80080
	s_addc_u32 s29, s27, -1
	s_cmp_eq_u32 s67, 28
	s_cselect_b32 s31, s7, s29
	s_cselect_b32 s30, s9, s28
	s_cselect_b32 s29, s19, s66
	s_cselect_b32 s28, s21, s65
	v_lshl_add_u64 v[136:137], s[26:27], 0, v[132:133]
	s_add_i32 m0, s47, 0xc000
	ds_read_b128 v[198:201], v164
	ds_read_b128 v[202:205], v164 offset:1024
	ds_read_b128 v[206:209], v164 offset:2048
	ds_read_b128 v[210:213], v164 offset:3072
	ds_read_b128 v[214:217], v164 offset:4096
	ds_read_b128 v[218:221], v164 offset:5120
	ds_read_b128 v[222:225], v164 offset:6144
	ds_read_b128 v[226:229], v164 offset:7168
	global_load_lds_dwordx4 v[136:137], off
	v_lshl_add_u64 v[136:137], s[26:27], 0, v[134:135]
	s_add_i32 m0, s47, 0xe000
	s_nop 0
	global_load_lds_dwordx4 v[136:137], off
	s_waitcnt lgkmcnt(8)
	s_barrier
	s_waitcnt lgkmcnt(0)
	s_setprio 1
	s_waitcnt lgkmcnt(0)
	v_mfma_f32_16x16x32_bf16 v[126:129], v[156:159], v[198:201], v[126:129]
	v_mfma_f32_16x16x32_bf16 v[122:125], v[170:173], v[198:201], v[122:125]
	v_mfma_f32_16x16x32_bf16 v[110:113], v[156:159], v[206:209], v[110:113]
	v_mfma_f32_16x16x32_bf16 v[106:109], v[170:173], v[206:209], v[106:109]
	v_mfma_f32_16x16x32_bf16 v[94:97], v[156:159], v[214:217], v[94:97]
	v_mfma_f32_16x16x32_bf16 v[90:93], v[170:173], v[214:217], v[90:93]
	v_mfma_f32_16x16x32_bf16 v[78:81], v[156:159], v[222:225], v[78:81]
	v_mfma_f32_16x16x32_bf16 v[74:77], v[170:173], v[222:225], v[74:77]
	v_mfma_f32_16x16x32_bf16 v[126:129], v[166:169], v[202:205], v[126:129]
	v_mfma_f32_16x16x32_bf16 v[122:125], v[194:197], v[202:205], v[122:125]
	v_mfma_f32_16x16x32_bf16 v[110:113], v[166:169], v[210:213], v[110:113]
	v_mfma_f32_16x16x32_bf16 v[106:109], v[194:197], v[210:213], v[106:109]
	v_mfma_f32_16x16x32_bf16 v[94:97], v[166:169], v[218:221], v[94:97]
	v_mfma_f32_16x16x32_bf16 v[90:93], v[194:197], v[218:221], v[90:93]
	v_mfma_f32_16x16x32_bf16 v[78:81], v[166:169], v[226:229], v[78:81]
	v_mfma_f32_16x16x32_bf16 v[74:77], v[194:197], v[226:229], v[74:77]
	s_setprio 0
	s_barrier
	s_add_i32 s70, 0, 0x14000
	v_add_u32_e32 v136, s70, v162
	s_add_i32 s42, s64, s40
	ds_read_b128 v[230:233], v136
	ds_read_b128 v[234:237], v136 offset:1024
	ds_read_b128 v[238:241], v136 offset:2048
	ds_read_b128 v[242:245], v136 offset:3072
	v_lshl_add_u64 v[136:137], s[28:29], 0, v[0:1]
	s_mov_b32 m0, s42
	v_lshl_add_u64 v[160:161], s[28:29], 0, v[130:131]
	global_load_lds_dwordx4 v[136:137], off
	s_add_i32 m0, s42, 0x2000
	s_nop 0
	global_load_lds_dwordx4 v[160:161], off
	s_barrier
	s_waitcnt lgkmcnt(0)
	s_setprio 1
	s_waitcnt lgkmcnt(0)
	v_mfma_f32_16x16x32_bf16 v[118:121], v[230:233], v[198:201], v[118:121]
	v_mfma_f32_16x16x32_bf16 v[114:117], v[238:241], v[198:201], v[114:117]
	v_mfma_f32_16x16x32_bf16 v[102:105], v[230:233], v[206:209], v[102:105]
	v_mfma_f32_16x16x32_bf16 v[98:101], v[238:241], v[206:209], v[98:101]
	v_mfma_f32_16x16x32_bf16 v[86:89], v[230:233], v[214:217], v[86:89]
	v_mfma_f32_16x16x32_bf16 v[82:85], v[238:241], v[214:217], v[82:85]
	v_mfma_f32_16x16x32_bf16 v[70:73], v[230:233], v[222:225], v[70:73]
	v_mfma_f32_16x16x32_bf16 v[66:69], v[238:241], v[222:225], v[66:69]
	v_mfma_f32_16x16x32_bf16 v[118:121], v[234:237], v[202:205], v[118:121]
	v_mfma_f32_16x16x32_bf16 v[114:117], v[242:245], v[202:205], v[114:117]
	v_mfma_f32_16x16x32_bf16 v[102:105], v[234:237], v[210:213], v[102:105]
	v_mfma_f32_16x16x32_bf16 v[98:101], v[242:245], v[210:213], v[98:101]
	v_mfma_f32_16x16x32_bf16 v[86:89], v[234:237], v[218:221], v[86:89]
	v_mfma_f32_16x16x32_bf16 v[82:85], v[242:245], v[218:221], v[82:85]
	v_mfma_f32_16x16x32_bf16 v[70:73], v[234:237], v[226:229], v[70:73]
	v_mfma_f32_16x16x32_bf16 v[66:69], v[242:245], v[226:229], v[66:69]
	s_setprio 0
	s_mov_b32 m0, s47
	v_lshl_add_u64 v[174:175], s[30:31], 0, v[0:1]
	s_barrier
	ds_read_b128 v[198:201], v164 offset:16384
	ds_read_b128 v[202:205], v164 offset:17408
	ds_read_b128 v[206:209], v164 offset:18432
	ds_read_b128 v[210:213], v164 offset:19456
	ds_read_b128 v[214:217], v164 offset:20480
	ds_read_b128 v[218:221], v164 offset:21504
	ds_read_b128 v[222:225], v164 offset:22528
	ds_read_b128 v[226:229], v164 offset:23552
	global_load_lds_dwordx4 v[174:175], off
	v_lshl_add_u64 v[246:247], s[30:31], 0, v[130:131]
	s_mov_b32 m0, s48
	s_nop 0
	global_load_lds_dwordx4 v[246:247], off
	s_barrier
	s_waitcnt lgkmcnt(0)
	s_setprio 1
	s_waitcnt lgkmcnt(0)
	v_mfma_f32_16x16x32_bf16 v[62:65], v[156:159], v[198:201], v[62:65]
	v_mfma_f32_16x16x32_bf16 v[58:61], v[170:173], v[198:201], v[58:61]
	v_mfma_f32_16x16x32_bf16 v[46:49], v[156:159], v[206:209], v[46:49]
	v_mfma_f32_16x16x32_bf16 v[42:45], v[170:173], v[206:209], v[42:45]
	v_mfma_f32_16x16x32_bf16 v[30:33], v[156:159], v[214:217], v[30:33]
	v_mfma_f32_16x16x32_bf16 v[26:29], v[170:173], v[214:217], v[26:29]
	v_mfma_f32_16x16x32_bf16 v[14:17], v[156:159], v[222:225], v[14:17]
	v_mfma_f32_16x16x32_bf16 v[10:13], v[170:173], v[222:225], v[10:13]
	v_mfma_f32_16x16x32_bf16 v[62:65], v[166:169], v[202:205], v[62:65]
	v_mfma_f32_16x16x32_bf16 v[58:61], v[194:197], v[202:205], v[58:61]
	v_mfma_f32_16x16x32_bf16 v[46:49], v[166:169], v[210:213], v[46:49]
	v_mfma_f32_16x16x32_bf16 v[42:45], v[194:197], v[210:213], v[42:45]
	v_mfma_f32_16x16x32_bf16 v[30:33], v[166:169], v[218:221], v[30:33]
	v_mfma_f32_16x16x32_bf16 v[26:29], v[194:197], v[218:221], v[26:29]
	v_mfma_f32_16x16x32_bf16 v[14:17], v[166:169], v[226:229], v[14:17]
	v_mfma_f32_16x16x32_bf16 v[10:13], v[194:197], v[226:229], v[10:13]
	s_setprio 0
	s_barrier
; #define PG8_STAGE(bufoff, gbase, voff) do { _Pragma("unroll") for (int _i = 0; _i < 2; ++_i) \
;         __builtin_amdgcn_global_load_lds((const unsigned*)((const char*)(gbase) + (voff)[_i]), (LAS unsigned*)(lds + (bufoff) + ldsw + _i * 8192), 16, 0, 0); } while (0)
; #define PG8_LDA(dst, b, h) do { _Pragma("unroll") for (int m = 0; m < 4; ++m) _Pragma("unroll") for (int k = 0; k < 2; ++k) dst[m][k] = *(const LAS bf16x8*)(lds + PG8_SA(b, h) + aoff + m * 2048 + k * 1024); } while (0)
; #define PG8_LDB(dst, b, h) do { _Pragma("unroll") for (int n = 0; n < 2; ++n) _Pragma("unroll") for (int k = 0; k < 2; ++k) dst[n][k] = *(const LAS bf16x8*)(lds + PG8_SB(b, h) + boff + n * 2048 + k * 1024); } while (0)
; #define PG8_MMA(ai, bj, At, Bt) do { __builtin_amdgcn_s_setprio(1); _Pragma("unroll") for (int m = 0; m < 4; ++m) _Pragma("unroll") for (int n = 0; n < 2; ++n) _Pragma("unroll") for (int k = 0; k < 2; ++k) \
;         acc[ai][bj][m][n] = __builtin_amdgcn_mfma_f32_16x16x32_bf16(Bt[n][k], At[m][k], acc[ai][bj][m][n], 0, 0, 0); __builtin_amdgcn_s_setprio(0); } while (0)
; #define PG8_WAIT_L(n) asm volatile("s_waitcnt lgkmcnt(" #n ")" ::: "memory")
; #define PG8_BAR __builtin_amdgcn_s_barrier()
; #define PG8_SCHED __builtin_amdgcn_sched_barrier(0)
; template <class Epi>
; __device__ __forceinline__ void gemm_phase(LAS unsigned char* lds, const Gemm g, const TileOrder& S, const Epi& E) {
;     ...
;             PG8_LDB(B0, 1, 0); PG8_SCHED; PG8_LDA(At, 1, 0); PG8_STAGE(PG8_SA(0, 1), a2 + hstepA, voffA);
;             PG8_WAIT_L(8); PG8_BAR; PG8_WAIT_L(0); PG8_MMA(0, 0, At, B0); PG8_BAR; PG8_SCHED;
;             PG8_LDB(B1, 1, 1); PG8_STAGE(PG8_SB(1, 0), b3, voffB);
;             PG8_BAR; PG8_WAIT_L(0); PG8_MMA(0, 1, At, B1); PG8_BAR;
;             PG8_LDA(At, 1, 1); PG8_STAGE(PG8_SA(1, 0), a3, voffA);
;             PG8_BAR; PG8_WAIT_L(0); PG8_MMA(1, 0, At, B0); PG8_BAR; PG8_SCHED;
;             PG8_STAGE(PG8_SB(1, 1), b3 + hstepB, voffB);
	s_add_u32 s42, s28, 0x80000
	s_addc_u32 s43, s29, 0
	s_add_i32 s70, s70, s40
	v_lshl_add_u64 v[156:157], s[42:43], 0, v[0:1]
	s_mov_b32 m0, s70
	s_nop 0
	global_load_lds_dwordx4 v[156:157], off
	v_lshl_add_u64 v[156:157], s[42:43], 0, v[130:131]
	s_add_i32 m0, s70, 0x2000
	s_nop 0
	global_load_lds_dwordx4 v[156:157], off
	s_waitcnt vmcnt(6)
	s_barrier
	s_setprio 1
	v_mfma_f32_16x16x32_bf16 v[54:57], v[230:233], v[198:201], v[54:57]
	v_mfma_f32_16x16x32_bf16 v[50:53], v[238:241], v[198:201], v[50:53]
	v_mfma_f32_16x16x32_bf16 v[38:41], v[230:233], v[206:209], v[38:41]
	v_mfma_f32_16x16x32_bf16 v[34:37], v[238:241], v[206:209], v[34:37]
	v_mfma_f32_16x16x32_bf16 v[22:25], v[230:233], v[214:217], v[22:25]
	v_mfma_f32_16x16x32_bf16 v[18:21], v[238:241], v[214:217], v[18:21]
	v_mfma_f32_16x16x32_bf16 v[6:9], v[230:233], v[222:225], v[6:9]
	v_mfma_f32_16x16x32_bf16 v[2:5], v[238:241], v[222:225], v[2:5]
	v_mfma_f32_16x16x32_bf16 v[54:57], v[234:237], v[202:205], v[54:57]
	v_mfma_f32_16x16x32_bf16 v[50:53], v[242:245], v[202:205], v[50:53]
	v_mfma_f32_16x16x32_bf16 v[38:41], v[234:237], v[210:213], v[38:41]
	v_mfma_f32_16x16x32_bf16 v[34:37], v[242:245], v[210:213], v[34:37]
	v_mfma_f32_16x16x32_bf16 v[22:25], v[234:237], v[218:221], v[22:25]
	v_mfma_f32_16x16x32_bf16 v[18:21], v[242:245], v[218:221], v[18:21]
	v_mfma_f32_16x16x32_bf16 v[6:9], v[234:237], v[226:229], v[6:9]
	v_mfma_f32_16x16x32_bf16 v[2:5], v[242:245], v[226:229], v[2:5]
	s_setprio 0
	s_add_i32 s42, 0, 0x18000
	v_add_u32_e32 v165, s42, v162
	s_barrier
	ds_read_b128 v[156:159], v165
	ds_read_b128 v[166:169], v165 offset:1024
	ds_read_b128 v[170:173], v165 offset:2048
	ds_read_b128 v[194:197], v165 offset:3072
	s_add_u32 s30, s30, 0x80000
	s_addc_u32 s31, s31, 0
	s_mov_b32 m0, s49
	v_lshl_add_u64 v[230:231], s[30:31], 0, v[0:1]
	ds_read_b128 v[198:201], v164 offset:32768
	ds_read_b128 v[202:205], v164 offset:33792
	ds_read_b128 v[206:209], v164 offset:34816
	ds_read_b128 v[210:213], v164 offset:35840
	ds_read_b128 v[214:217], v164 offset:36864
	ds_read_b128 v[218:221], v164 offset:37888
	ds_read_b128 v[222:225], v164 offset:38912
	ds_read_b128 v[226:229], v164 offset:39936
	global_load_lds_dwordx4 v[230:231], off
	v_lshl_add_u64 v[230:231], s[30:31], 0, v[130:131]
	s_mov_b32 m0, s50
	s_nop 0
	global_load_lds_dwordx4 v[230:231], off
	s_waitcnt lgkmcnt(8)
	s_barrier
	s_waitcnt lgkmcnt(0)
	s_setprio 1
	s_waitcnt lgkmcnt(0)
	v_mfma_f32_16x16x32_bf16 v[126:129], v[156:159], v[198:201], v[126:129]
	v_mfma_f32_16x16x32_bf16 v[122:125], v[170:173], v[198:201], v[122:125]
	v_mfma_f32_16x16x32_bf16 v[110:113], v[156:159], v[206:209], v[110:113]
	v_mfma_f32_16x16x32_bf16 v[106:109], v[170:173], v[206:209], v[106:109]
	v_mfma_f32_16x16x32_bf16 v[94:97], v[156:159], v[214:217], v[94:97]
	v_mfma_f32_16x16x32_bf16 v[90:93], v[170:173], v[214:217], v[90:93]
	v_mfma_f32_16x16x32_bf16 v[78:81], v[156:159], v[222:225], v[78:81]
	v_mfma_f32_16x16x32_bf16 v[74:77], v[170:173], v[222:225], v[74:77]
	v_mfma_f32_16x16x32_bf16 v[126:129], v[166:169], v[202:205], v[126:129]
	v_mfma_f32_16x16x32_bf16 v[122:125], v[194:197], v[202:205], v[122:125]
	v_mfma_f32_16x16x32_bf16 v[110:113], v[166:169], v[210:213], v[110:113]
	v_mfma_f32_16x16x32_bf16 v[106:109], v[194:197], v[210:213], v[106:109]
	v_mfma_f32_16x16x32_bf16 v[94:97], v[166:169], v[218:221], v[94:97]
	v_mfma_f32_16x16x32_bf16 v[90:93], v[194:197], v[218:221], v[90:93]
	v_mfma_f32_16x16x32_bf16 v[78:81], v[166:169], v[226:229], v[78:81]
	v_mfma_f32_16x16x32_bf16 v[74:77], v[194:197], v[226:229], v[74:77]
	s_setprio 0
	s_barrier
	s_add_i32 s30, 0, 0x1c000
	s_add_i32 s31, s42, s40
	v_add_u32_e32 v165, s30, v162
	v_lshl_add_u64 v[136:137], v[136:137], 0, s[58:59]
	s_mov_b32 m0, s31
	ds_read_b128 v[230:233], v165
	ds_read_b128 v[234:237], v165 offset:1024
	ds_read_b128 v[238:241], v165 offset:2048
	ds_read_b128 v[242:245], v165 offset:3072
	global_load_lds_dwordx4 v[136:137], off
	v_lshl_add_u64 v[136:137], v[160:161], 0, s[58:59]
	s_add_i32 m0, s31, 0x2000
	s_nop 0
	global_load_lds_dwordx4 v[136:137], off
	s_barrier
	s_waitcnt lgkmcnt(0)
	s_setprio 1
	s_waitcnt lgkmcnt(0)
	v_mfma_f32_16x16x32_bf16 v[118:121], v[230:233], v[198:201], v[118:121]
	v_mfma_f32_16x16x32_bf16 v[114:117], v[238:241], v[198:201], v[114:117]
	v_mfma_f32_16x16x32_bf16 v[102:105], v[230:233], v[206:209], v[102:105]
	v_mfma_f32_16x16x32_bf16 v[98:101], v[238:241], v[206:209], v[98:101]
	v_mfma_f32_16x16x32_bf16 v[86:89], v[230:233], v[214:217], v[86:89]
	v_mfma_f32_16x16x32_bf16 v[82:85], v[238:241], v[214:217], v[82:85]
	v_mfma_f32_16x16x32_bf16 v[70:73], v[230:233], v[222:225], v[70:73]
	v_mfma_f32_16x16x32_bf16 v[66:69], v[238:241], v[222:225], v[66:69]
	v_mfma_f32_16x16x32_bf16 v[118:121], v[234:237], v[202:205], v[118:121]
	v_mfma_f32_16x16x32_bf16 v[114:117], v[242:245], v[202:205], v[114:117]
	v_mfma_f32_16x16x32_bf16 v[102:105], v[234:237], v[210:213], v[102:105]
	v_mfma_f32_16x16x32_bf16 v[98:101], v[242:245], v[210:213], v[98:101]
	v_mfma_f32_16x16x32_bf16 v[86:89], v[234:237], v[218:221], v[86:89]
	v_mfma_f32_16x16x32_bf16 v[82:85], v[242:245], v[218:221], v[82:85]
	v_mfma_f32_16x16x32_bf16 v[70:73], v[234:237], v[226:229], v[70:73]
	v_mfma_f32_16x16x32_bf16 v[66:69], v[242:245], v[226:229], v[66:69]
	s_setprio 0
	s_mov_b32 m0, s51
	v_lshl_add_u64 v[136:137], v[174:175], 0, s[58:59]
	s_barrier
	ds_read_b128 v[198:201], v164 offset:49152
	ds_read_b128 v[202:205], v164 offset:50176
	ds_read_b128 v[206:209], v164 offset:51200
	ds_read_b128 v[210:213], v164 offset:52224
	ds_read_b128 v[214:217], v164 offset:53248
	ds_read_b128 v[218:221], v164 offset:54272
	ds_read_b128 v[222:225], v164 offset:55296
	ds_read_b128 v[226:229], v164 offset:56320
	global_load_lds_dwordx4 v[136:137], off
	v_lshl_add_u64 v[136:137], v[246:247], 0, s[58:59]
	s_mov_b32 m0, s52
	s_nop 0
	global_load_lds_dwordx4 v[136:137], off
	s_barrier
; #define PG8_MMA(ai, bj, At, Bt) do { __builtin_amdgcn_s_setprio(1); _Pragma("unroll") for (int m = 0; m < 4; ++m) _Pragma("unroll") for (int n = 0; n < 2; ++n) _Pragma("unroll") for (int k = 0; k < 2; ++k) \
;         acc[ai][bj][m][n] = __builtin_amdgcn_mfma_f32_16x16x32_bf16(Bt[n][k], At[m][k], acc[ai][bj][m][n], 0, 0, 0); __builtin_amdgcn_s_setprio(0); } while (0)
; #define PG8_WAIT_V(n) asm volatile("s_waitcnt vmcnt(" #n ")" ::: "memory")
; #define PG8_BAR __builtin_amdgcn_s_barrier()
; template <class Epi>
; __device__ __forceinline__ void gemm_phase(LAS unsigned char* lds, const Gemm g, const TileOrder& S, const Epi& E) {
;     ...
;             PG8_WAIT_V(6); PG8_BAR; PG8_MMA(1, 1, At, B1); PG8_BAR;
;         }
;     __device__ __forceinline__ void operator()(const AccT& acc, const Unit& u, int wr, int wc, int fr, int fq) const {
;     ...
;                 const int row = u.pm * 256 + ai * 128 + wr * 64 + m * 16 + fr;
;                 const bool ok = row < res.valid;
;                 const float* rp = res.row(ok ? row : 0);
; #pragma unroll
;                 for (int bj = 0; bj < 2; ++bj)
; #pragma unroll
;                     for (int n = 0; n < 2; ++n) {
;                         const int col = u.pn * 256 + bj * 128 + wc * 32 + n * 16 + 4 * fq;
;                         f32x4 v = acc[ai][bj][m][n];
;                         if (zero) v = (f32x4){0.f, 0.f, 0.f, 0.f};
;                         if (ok) v += *(const f32x4*)(rp + col);
	s_waitcnt lgkmcnt(0)
	s_setprio 1
	s_waitcnt lgkmcnt(0)
	v_mfma_f32_16x16x32_bf16 v[62:65], v[156:159], v[198:201], v[62:65]
	v_mfma_f32_16x16x32_bf16 v[58:61], v[170:173], v[198:201], v[58:61]
	v_mfma_f32_16x16x32_bf16 v[46:49], v[156:159], v[206:209], v[46:49]
	v_mfma_f32_16x16x32_bf16 v[42:45], v[170:173], v[206:209], v[42:45]
	v_mfma_f32_16x16x32_bf16 v[30:33], v[156:159], v[214:217], v[30:33]
	v_mfma_f32_16x16x32_bf16 v[26:29], v[170:173], v[214:217], v[26:29]
	v_mfma_f32_16x16x32_bf16 v[14:17], v[156:159], v[222:225], v[14:17]
	v_mfma_f32_16x16x32_bf16 v[10:13], v[170:173], v[222:225], v[10:13]
	v_mfma_f32_16x16x32_bf16 v[62:65], v[166:169], v[202:205], v[62:65]
	v_mfma_f32_16x16x32_bf16 v[58:61], v[194:197], v[202:205], v[58:61]
	v_mfma_f32_16x16x32_bf16 v[46:49], v[166:169], v[210:213], v[46:49]
	v_mfma_f32_16x16x32_bf16 v[42:45], v[194:197], v[210:213], v[42:45]
	v_mfma_f32_16x16x32_bf16 v[30:33], v[166:169], v[218:221], v[30:33]
	v_mfma_f32_16x16x32_bf16 v[26:29], v[194:197], v[218:221], v[26:29]
	v_mfma_f32_16x16x32_bf16 v[14:17], v[166:169], v[226:229], v[14:17]
	v_mfma_f32_16x16x32_bf16 v[10:13], v[194:197], v[226:229], v[10:13]
	s_setprio 0
	s_barrier
	s_add_u32 s28, s28, 0x80080
	s_addc_u32 s29, s29, 0
	s_add_i32 s30, s30, s40
	v_lshl_add_u64 v[136:137], s[28:29], 0, v[0:1]
	s_mov_b32 m0, s30
	s_nop 0
	global_load_lds_dwordx4 v[136:137], off
	v_lshl_add_u64 v[136:137], s[28:29], 0, v[130:131]
	s_add_i32 m0, s30, 0x2000
	s_nop 0
	global_load_lds_dwordx4 v[136:137], off
	s_waitcnt vmcnt(6)
	s_barrier
	s_setprio 1
	v_mfma_f32_16x16x32_bf16 v[54:57], v[230:233], v[198:201], v[54:57]
	v_mfma_f32_16x16x32_bf16 v[50:53], v[238:241], v[198:201], v[50:53]
	v_mfma_f32_16x16x32_bf16 v[38:41], v[230:233], v[206:209], v[38:41]
	v_mfma_f32_16x16x32_bf16 v[34:37], v[238:241], v[206:209], v[34:37]
	v_mfma_f32_16x16x32_bf16 v[22:25], v[230:233], v[214:217], v[22:25]
	v_mfma_f32_16x16x32_bf16 v[18:21], v[238:241], v[214:217], v[18:21]
	v_mfma_f32_16x16x32_bf16 v[6:9], v[230:233], v[222:225], v[6:9]
	v_mfma_f32_16x16x32_bf16 v[2:5], v[238:241], v[222:225], v[2:5]
	v_mfma_f32_16x16x32_bf16 v[54:57], v[234:237], v[202:205], v[54:57]
	v_mfma_f32_16x16x32_bf16 v[50:53], v[242:245], v[202:205], v[50:53]
	v_mfma_f32_16x16x32_bf16 v[38:41], v[234:237], v[210:213], v[38:41]
	v_mfma_f32_16x16x32_bf16 v[34:37], v[242:245], v[210:213], v[34:37]
	v_mfma_f32_16x16x32_bf16 v[22:25], v[234:237], v[218:221], v[22:25]
	v_mfma_f32_16x16x32_bf16 v[18:21], v[242:245], v[218:221], v[18:21]
	v_mfma_f32_16x16x32_bf16 v[6:9], v[234:237], v[226:229], v[6:9]
	v_mfma_f32_16x16x32_bf16 v[2:5], v[242:245], v[226:229], v[2:5]
	s_setprio 0
	s_add_i32 s67, s67, 2
	s_add_u32 s26, s26, 0x100
	s_addc_u32 s27, s27, 0
	s_add_u32 s65, s65, 0x100
	s_addc_u32 s66, s66, 0
	s_cmp_gt_u32 s67, 29
	s_barrier
	s_cbranch_scc0 .LBB0_1343
	v_lshl_add_u32 v156, s8, 8, v139
	v_lshl_or_b32 v136, s6, 8, v163
	v_ashrrev_i32_e32 v137, 31, v136
	v_ashrrev_i32_e32 v157, 31, v156
	v_lshlrev_b64 v[156:157], 13, v[156:157]
	v_lshl_add_u64 v[156:157], v[136:137], 2, v[156:157]
	v_lshl_add_u64 v[160:161], s[12:13], 0, v[156:157]
	v_lshl_add_u64 v[158:159], s[0:1], 0, v[156:157]
	global_load_dwordx4 v[166:169], v[160:161], off
	global_load_dwordx4 v[170:173], v[160:161], off offset:64
	global_load_dwordx4 v[194:197], v[160:161], off offset:512
	global_load_dwordx4 v[198:201], v[160:161], off offset:576
	s_mov_b64 s[6:7], 0x20000
	v_lshl_add_u64 v[156:157], v[160:161], 0, s[6:7]
	global_load_dwordx4 v[202:205], v[156:157], off
	global_load_dwordx4 v[206:209], v[156:157], off offset:64
	global_load_dwordx4 v[210:213], v[156:157], off offset:512
	global_load_dwordx4 v[214:217], v[156:157], off offset:576
	s_mov_b64 s[6:7], 0x40000
	v_lshl_add_u64 v[136:137], v[160:161], 0, s[6:7]
	global_load_dwordx4 v[218:221], v[136:137], off
	global_load_dwordx4 v[222:225], v[136:137], off offset:64
	global_load_dwordx4 v[226:229], v[136:137], off offset:512
	global_load_dwordx4 v[230:233], v[136:137], off offset:576
	s_mov_b64 s[6:7], 0x60000
	v_lshl_add_u64 v[156:157], v[160:161], 0, s[6:7]
	global_load_dwordx4 v[234:237], v[156:157], off
	global_load_dwordx4 v[238:241], v[156:157], off offset:64
	global_load_dwordx4 v[242:245], v[156:157], off offset:512
	global_load_dwordx4 v[248:251], v[156:157], off offset:576
	s_waitcnt vmcnt(0)
;     __device__ __forceinline__ void operator()(const AccT& acc, const Unit& u, int wr, int wc, int fr, int fq) const {
;     ...
; #pragma unroll
;                 for (int bj = 0; bj < 2; ++bj)
; #pragma unroll
;                     for (int n = 0; n < 2; ++n) {
;                         const int col = u.pn * 256 + bj * 128 + wc * 32 + n * 16 + 4 * fq;
;                         f32x4 v = acc[ai][bj][m][n];
;                         if (zero) v = (f32x4){0.f, 0.f, 0.f, 0.f};
;                         if (ok) v += *(const f32x4*)(rp + col);
;                         *(f32x4*)(O + (size_t)row * DM + col) = v;
	v_pk_add_f32 v[126:127], v[126:127], v[166:167]
	v_pk_add_f32 v[128:129], v[128:129], v[168:169]
	v_pk_add_f32 v[122:123], v[122:123], v[170:171]
	v_pk_add_f32 v[124:125], v[124:125], v[172:173]
	v_pk_add_f32 v[118:119], v[118:119], v[194:195]
	v_pk_add_f32 v[120:121], v[120:121], v[196:197]
	v_pk_add_f32 v[114:115], v[114:115], v[198:199]
	v_pk_add_f32 v[116:117], v[116:117], v[200:201]
	global_store_dwordx4 v[158:159], v[126:129], off
	global_store_dwordx4 v[158:159], v[122:125], off offset:64
	global_store_dwordx4 v[158:159], v[118:121], off offset:512
	global_store_dwordx4 v[158:159], v[114:117], off offset:576
	s_mov_b64 s[6:7], 0x20000
	v_lshl_add_u64 v[156:157], v[158:159], 0, s[6:7]
	v_pk_add_f32 v[110:111], v[110:111], v[202:203]
	v_pk_add_f32 v[112:113], v[112:113], v[204:205]
	v_pk_add_f32 v[106:107], v[106:107], v[206:207]
	v_pk_add_f32 v[108:109], v[108:109], v[208:209]
	v_pk_add_f32 v[102:103], v[102:103], v[210:211]
	v_pk_add_f32 v[104:105], v[104:105], v[212:213]
	v_pk_add_f32 v[98:99], v[98:99], v[214:215]
	v_pk_add_f32 v[100:101], v[100:101], v[216:217]
	global_store_dwordx4 v[156:157], v[110:113], off
	global_store_dwordx4 v[156:157], v[106:109], off offset:64
	global_store_dwordx4 v[156:157], v[102:105], off offset:512
	global_store_dwordx4 v[156:157], v[98:101], off offset:576
	s_mov_b64 s[6:7], 0x40000
	v_lshl_add_u64 v[136:137], v[158:159], 0, s[6:7]
	v_pk_add_f32 v[94:95], v[94:95], v[218:219]
	v_pk_add_f32 v[96:97], v[96:97], v[220:221]
	v_pk_add_f32 v[90:91], v[90:91], v[222:223]
	v_pk_add_f32 v[92:93], v[92:93], v[224:225]
	v_pk_add_f32 v[86:87], v[86:87], v[226:227]
	v_pk_add_f32 v[88:89], v[88:89], v[228:229]
	v_pk_add_f32 v[82:83], v[82:83], v[230:231]
	v_pk_add_f32 v[84:85], v[84:85], v[232:233]
	global_store_dwordx4 v[136:137], v[94:97], off
	global_store_dwordx4 v[136:137], v[90:93], off offset:64
	global_store_dwordx4 v[136:137], v[86:89], off offset:512
	global_store_dwordx4 v[136:137], v[82:85], off offset:576
	s_mov_b64 s[6:7], 0x60000
	v_lshl_add_u64 v[156:157], v[158:159], 0, s[6:7]
	v_pk_add_f32 v[78:79], v[78:79], v[234:235]
	v_pk_add_f32 v[80:81], v[80:81], v[236:237]
	v_pk_add_f32 v[74:75], v[74:75], v[238:239]
	v_pk_add_f32 v[76:77], v[76:77], v[240:241]
	v_pk_add_f32 v[70:71], v[70:71], v[242:243]
	v_pk_add_f32 v[72:73], v[72:73], v[244:245]
	v_pk_add_f32 v[66:67], v[66:67], v[248:249]
	v_pk_add_f32 v[68:69], v[68:69], v[250:251]
	global_store_dwordx4 v[156:157], v[78:81], off
	global_store_dwordx4 v[156:157], v[74:77], off offset:64
	global_store_dwordx4 v[156:157], v[70:73], off offset:512
	global_store_dwordx4 v[156:157], v[66:69], off offset:576
	s_mov_b64 s[6:7], 0x100000
	v_lshl_add_u64 v[136:137], v[160:161], 0, s[6:7]
	global_load_dwordx4 v[166:169], v[136:137], off
	global_load_dwordx4 v[170:173], v[136:137], off offset:64
	global_load_dwordx4 v[194:197], v[136:137], off offset:512
	global_load_dwordx4 v[198:201], v[136:137], off offset:576
	s_mov_b64 s[6:7], 0x120000
	v_lshl_add_u64 v[156:157], v[160:161], 0, s[6:7]
	global_load_dwordx4 v[202:205], v[156:157], off
	global_load_dwordx4 v[206:209], v[156:157], off offset:64
	global_load_dwordx4 v[210:213], v[156:157], off offset:512
	global_load_dwordx4 v[214:217], v[156:157], off offset:576
	s_mov_b64 s[6:7], 0x140000
	v_lshl_add_u64 v[136:137], v[160:161], 0, s[6:7]
	global_load_dwordx4 v[218:221], v[136:137], off
	global_load_dwordx4 v[222:225], v[136:137], off offset:64
	global_load_dwordx4 v[226:229], v[136:137], off offset:512
	global_load_dwordx4 v[230:233], v[136:137], off offset:576
	s_mov_b64 s[6:7], 0x160000
	v_lshl_add_u64 v[156:157], v[160:161], 0, s[6:7]
	global_load_dwordx4 v[234:237], v[156:157], off
	global_load_dwordx4 v[238:241], v[156:157], off offset:64
	global_load_dwordx4 v[242:245], v[156:157], off offset:512
	global_load_dwordx4 v[248:251], v[156:157], off offset:576
	s_waitcnt vmcnt(0)
	s_mov_b64 s[6:7], 0x100000
	v_lshl_add_u64 v[136:137], v[158:159], 0, s[6:7]
	v_pk_add_f32 v[62:63], v[62:63], v[166:167]
	v_pk_add_f32 v[64:65], v[64:65], v[168:169]
	v_pk_add_f32 v[58:59], v[58:59], v[170:171]
	v_pk_add_f32 v[60:61], v[60:61], v[172:173]
	v_pk_add_f32 v[54:55], v[54:55], v[194:195]
	v_pk_add_f32 v[56:57], v[56:57], v[196:197]
	v_pk_add_f32 v[50:51], v[50:51], v[198:199]
	v_pk_add_f32 v[52:53], v[52:53], v[200:201]
	global_store_dwordx4 v[136:137], v[62:65], off
	global_store_dwordx4 v[136:137], v[58:61], off offset:64
	global_store_dwordx4 v[136:137], v[54:57], off offset:512
	global_store_dwordx4 v[136:137], v[50:53], off offset:576
	s_mov_b64 s[6:7], 0x120000
	v_lshl_add_u64 v[156:157], v[158:159], 0, s[6:7]
	v_pk_add_f32 v[46:47], v[46:47], v[202:203]
	v_pk_add_f32 v[48:49], v[48:49], v[204:205]
	v_pk_add_f32 v[42:43], v[42:43], v[206:207]
	v_pk_add_f32 v[44:45], v[44:45], v[208:209]
	v_pk_add_f32 v[38:39], v[38:39], v[210:211]
	v_pk_add_f32 v[40:41], v[40:41], v[212:213]
	v_pk_add_f32 v[34:35], v[34:35], v[214:215]
	v_pk_add_f32 v[36:37], v[36:37], v[216:217]
	global_store_dwordx4 v[156:157], v[46:49], off
	global_store_dwordx4 v[156:157], v[42:45], off offset:64
	global_store_dwordx4 v[156:157], v[38:41], off offset:512
	global_store_dwordx4 v[156:157], v[34:37], off offset:576
	s_mov_b64 s[6:7], 0x140000
	v_lshl_add_u64 v[136:137], v[158:159], 0, s[6:7]
	v_pk_add_f32 v[30:31], v[30:31], v[218:219]
	v_pk_add_f32 v[32:33], v[32:33], v[220:221]
	v_pk_add_f32 v[26:27], v[26:27], v[222:223]
	v_pk_add_f32 v[28:29], v[28:29], v[224:225]
	v_pk_add_f32 v[22:23], v[22:23], v[226:227]
	v_pk_add_f32 v[24:25], v[24:25], v[228:229]
	v_pk_add_f32 v[18:19], v[18:19], v[230:231]
	v_pk_add_f32 v[20:21], v[20:21], v[232:233]
	global_store_dwordx4 v[136:137], v[30:33], off
	global_store_dwordx4 v[136:137], v[26:29], off offset:64
	global_store_dwordx4 v[136:137], v[22:25], off offset:512
	global_store_dwordx4 v[136:137], v[18:21], off offset:576
	s_mov_b64 s[6:7], 0x160000
	v_lshl_add_u64 v[156:157], v[158:159], 0, s[6:7]
	v_pk_add_f32 v[14:15], v[14:15], v[234:235]
	v_pk_add_f32 v[16:17], v[16:17], v[236:237]
	v_pk_add_f32 v[10:11], v[10:11], v[238:239]
	v_pk_add_f32 v[12:13], v[12:13], v[240:241]
	v_pk_add_f32 v[6:7], v[6:7], v[242:243]
	v_pk_add_f32 v[8:9], v[8:9], v[244:245]
	v_pk_add_f32 v[2:3], v[2:3], v[248:249]
	v_pk_add_f32 v[4:5], v[4:5], v[250:251]
	global_store_dwordx4 v[156:157], v[14:17], off
	global_store_dwordx4 v[156:157], v[10:13], off offset:64
	global_store_dwordx4 v[156:157], v[6:9], off offset:512
	global_store_dwordx4 v[156:157], v[2:5], off offset:576
	s_branch .LBB0_1335

; template <class Epi>
; __device__ __forceinline__ void gemm_phase(LAS unsigned char* lds, const Gemm g, const TileOrder& S, const Epi& E) {
;     ...
;     for (;;) {
;         const bool has_next = S.next(ui + 1, nxt);
;         const char* nA = has_next ? PG8_BASEA(nxt.z) + (size_t)nxt.pm * tstepA : cA; const char* nB = has_next ? PG8_BASEB(nxt.z) + (size_t)nxt.pn * tstepB : cB;
.LBB0_1616:
	s_and_b64 vcc, exec, s[4:5]
	s_mov_b32 s40, s36
	s_mov_b32 s41, s37
	s_mov_b64 s[20:21], s[8:9]
	s_mov_b64 s[18:19], s[16:17]
	s_cbranch_vccnz .LBB0_1679

; #define PG8_STAGE(bufoff, gbase, voff) do { _Pragma("unroll") for (int _i = 0; _i < 2; ++_i) \
;         __builtin_amdgcn_global_load_lds((const unsigned*)((const char*)(gbase) + (voff)[_i]), (LAS unsigned*)(lds + (bufoff) + ldsw + _i * 8192), 16, 0, 0); } while (0)
; #define PG8_LDA(dst, b, h) do { _Pragma("unroll") for (int m = 0; m < 4; ++m) _Pragma("unroll") for (int k = 0; k < 2; ++k) dst[m][k] = *(const LAS bf16x8*)(lds + PG8_SA(b, h) + aoff + m * 2048 + k * 1024); } while (0)
; #define PG8_LDB(dst, b, h) do { _Pragma("unroll") for (int n = 0; n < 2; ++n) _Pragma("unroll") for (int k = 0; k < 2; ++k) dst[n][k] = *(const LAS bf16x8*)(lds + PG8_SB(b, h) + boff + n * 2048 + k * 1024); } while (0)
; #define PG8_MMA(ai, bj, At, Bt) do { __builtin_amdgcn_s_setprio(1); _Pragma("unroll") for (int m = 0; m < 4; ++m) _Pragma("unroll") for (int n = 0; n < 2; ++n) _Pragma("unroll") for (int k = 0; k < 2; ++k) \
;         acc[ai][bj][m][n] = __builtin_amdgcn_mfma_f32_16x16x32_bf16(Bt[n][k], At[m][k], acc[ai][bj][m][n], 0, 0, 0); __builtin_amdgcn_s_setprio(0); } while (0)
; #define PG8_WAIT_V(n) asm volatile("s_waitcnt vmcnt(" #n ")" ::: "memory")
; #define PG8_WAIT_L(n) asm volatile("s_waitcnt lgkmcnt(" #n ")" ::: "memory")
; #define PG8_BAR __builtin_amdgcn_s_barrier()
; #define PG8_SCHED __builtin_amdgcn_sched_barrier(0)
; template <class Epi>
; __device__ __forceinline__ void gemm_phase(LAS unsigned char* lds, const Gemm g, const TileOrder& S, const Epi& E) {
;     ...
;             PG8_LDB(B0, 0, 0); PG8_SCHED; PG8_LDA(At, 0, 0); PG8_STAGE(PG8_SA(1, 1), a1 + hstepA, voffA);
;             PG8_WAIT_L(8); PG8_BAR; PG8_WAIT_L(0); PG8_MMA(0, 0, At, B0); PG8_BAR; PG8_SCHED;
;             PG8_LDB(B1, 0, 1); PG8_STAGE(PG8_SB(0, 0), b2, voffB);
;             PG8_BAR; PG8_WAIT_L(0); PG8_MMA(0, 1, At, B1); PG8_BAR;
;             PG8_LDA(At, 0, 1); PG8_STAGE(PG8_SA(0, 0), a2, voffA);
;             PG8_BAR; PG8_WAIT_L(0); PG8_MMA(1, 0, At, B0); PG8_BAR; PG8_SCHED;
;             PG8_STAGE(PG8_SB(0, 1), b2 + hstepB, voffB);
;             PG8_WAIT_V(6); PG8_BAR; PG8_MMA(1, 1, At, B1); PG8_BAR;
;             PG8_LDB(B0, 1, 0); PG8_SCHED; PG8_LDA(At, 1, 0); PG8_STAGE(PG8_SA(0, 1), a2 + hstepA, voffA);
;             PG8_WAIT_L(8); PG8_BAR; PG8_WAIT_L(0); PG8_MMA(0, 0, At, B0); PG8_BAR; PG8_SCHED;
.LBB0_1628:
	v_add_u32_e32 v136, s64, v162
	ds_read_b128 v[156:159], v136
	ds_read_b128 v[166:169], v136 offset:1024
	ds_read_b128 v[170:173], v136 offset:2048
	ds_read_b128 v[194:197], v136 offset:3072
	s_add_u32 s6, s18, 0x100
	s_addc_u32 s7, s19, 0
	s_cmpk_eq_i32 s46, 0x54
	s_cselect_b32 s23, s17, s7
	s_cselect_b32 s22, s16, s6
	s_cselect_b32 s21, s9, s45
	s_cselect_b32 s20, s8, s44
	v_lshl_add_u64 v[136:137], s[18:19], 0, v[132:133]
	s_add_i32 m0, s27, 0xc000
	ds_read_b128 v[198:201], v164
	ds_read_b128 v[202:205], v164 offset:1024
	ds_read_b128 v[206:209], v164 offset:2048
	ds_read_b128 v[210:213], v164 offset:3072
	ds_read_b128 v[214:217], v164 offset:4096
	ds_read_b128 v[218:221], v164 offset:5120
	ds_read_b128 v[222:225], v164 offset:6144
	ds_read_b128 v[226:229], v164 offset:7168
	global_load_lds_dwordx4 v[136:137], off
	v_lshl_add_u64 v[136:137], s[18:19], 0, v[134:135]
	s_add_i32 m0, s27, 0xe000
	s_nop 0
	global_load_lds_dwordx4 v[136:137], off
	s_waitcnt lgkmcnt(8)
	s_barrier
	s_waitcnt lgkmcnt(0)
	s_setprio 1
	s_waitcnt lgkmcnt(0)
	v_mfma_f32_16x16x32_bf16 v[126:129], v[156:159], v[198:201], v[126:129]
	v_mfma_f32_16x16x32_bf16 v[122:125], v[170:173], v[198:201], v[122:125]
	v_mfma_f32_16x16x32_bf16 v[110:113], v[156:159], v[206:209], v[110:113]
	v_mfma_f32_16x16x32_bf16 v[106:109], v[170:173], v[206:209], v[106:109]
	v_mfma_f32_16x16x32_bf16 v[94:97], v[156:159], v[214:217], v[94:97]
	v_mfma_f32_16x16x32_bf16 v[90:93], v[170:173], v[214:217], v[90:93]
	v_mfma_f32_16x16x32_bf16 v[78:81], v[156:159], v[222:225], v[78:81]
	v_mfma_f32_16x16x32_bf16 v[74:77], v[170:173], v[222:225], v[74:77]
	v_mfma_f32_16x16x32_bf16 v[126:129], v[166:169], v[202:205], v[126:129]
	v_mfma_f32_16x16x32_bf16 v[122:125], v[194:197], v[202:205], v[122:125]
	v_mfma_f32_16x16x32_bf16 v[110:113], v[166:169], v[210:213], v[110:113]
	v_mfma_f32_16x16x32_bf16 v[106:109], v[194:197], v[210:213], v[106:109]
	v_mfma_f32_16x16x32_bf16 v[94:97], v[166:169], v[218:221], v[94:97]
	v_mfma_f32_16x16x32_bf16 v[90:93], v[194:197], v[218:221], v[90:93]
	v_mfma_f32_16x16x32_bf16 v[78:81], v[166:169], v[226:229], v[78:81]
	v_mfma_f32_16x16x32_bf16 v[74:77], v[194:197], v[226:229], v[74:77]
	s_setprio 0
	s_barrier
	s_add_i32 s42, 0, 0x14000
	v_add_u32_e32 v136, s42, v162
	s_add_i32 s18, s64, s26
	ds_read_b128 v[230:233], v136
	ds_read_b128 v[234:237], v136 offset:1024
	ds_read_b128 v[238:241], v136 offset:2048
	ds_read_b128 v[242:245], v136 offset:3072
	v_lshl_add_u64 v[136:137], s[20:21], 0, v[0:1]
	s_mov_b32 m0, s18
	v_lshl_add_u64 v[160:161], s[20:21], 0, v[130:131]
	global_load_lds_dwordx4 v[136:137], off
	s_add_i32 m0, s18, 0x2000
	s_nop 0
	global_load_lds_dwordx4 v[160:161], off
	s_barrier
	s_waitcnt lgkmcnt(0)
	s_setprio 1
	s_waitcnt lgkmcnt(0)
	v_mfma_f32_16x16x32_bf16 v[118:121], v[230:233], v[198:201], v[118:121]
	v_mfma_f32_16x16x32_bf16 v[114:117], v[238:241], v[198:201], v[114:117]
	v_mfma_f32_16x16x32_bf16 v[102:105], v[230:233], v[206:209], v[102:105]
	v_mfma_f32_16x16x32_bf16 v[98:101], v[238:241], v[206:209], v[98:101]
	v_mfma_f32_16x16x32_bf16 v[86:89], v[230:233], v[214:217], v[86:89]
	v_mfma_f32_16x16x32_bf16 v[82:85], v[238:241], v[214:217], v[82:85]
	v_mfma_f32_16x16x32_bf16 v[70:73], v[230:233], v[222:225], v[70:73]
	v_mfma_f32_16x16x32_bf16 v[66:69], v[238:241], v[222:225], v[66:69]
	v_mfma_f32_16x16x32_bf16 v[118:121], v[234:237], v[202:205], v[118:121]
	v_mfma_f32_16x16x32_bf16 v[114:117], v[242:245], v[202:205], v[114:117]
	v_mfma_f32_16x16x32_bf16 v[102:105], v[234:237], v[210:213], v[102:105]
	v_mfma_f32_16x16x32_bf16 v[98:101], v[242:245], v[210:213], v[98:101]
	v_mfma_f32_16x16x32_bf16 v[86:89], v[234:237], v[218:221], v[86:89]
	v_mfma_f32_16x16x32_bf16 v[82:85], v[242:245], v[218:221], v[82:85]
	v_mfma_f32_16x16x32_bf16 v[70:73], v[234:237], v[226:229], v[70:73]
	v_mfma_f32_16x16x32_bf16 v[66:69], v[242:245], v[226:229], v[66:69]
	s_setprio 0
	s_mov_b32 m0, s27
	v_lshl_add_u64 v[174:175], s[22:23], 0, v[0:1]
	s_barrier
	ds_read_b128 v[198:201], v164 offset:16384
	ds_read_b128 v[202:205], v164 offset:17408
	ds_read_b128 v[206:209], v164 offset:18432
	ds_read_b128 v[210:213], v164 offset:19456
	ds_read_b128 v[214:217], v164 offset:20480
	ds_read_b128 v[218:221], v164 offset:21504
	ds_read_b128 v[222:225], v164 offset:22528
	ds_read_b128 v[226:229], v164 offset:23552
	global_load_lds_dwordx4 v[174:175], off
	v_lshl_add_u64 v[246:247], s[22:23], 0, v[130:131]
	s_mov_b32 m0, s28
	s_nop 0
	global_load_lds_dwordx4 v[246:247], off
	s_barrier
	s_waitcnt lgkmcnt(0)
	s_setprio 1
	s_waitcnt lgkmcnt(0)
	v_mfma_f32_16x16x32_bf16 v[62:65], v[156:159], v[198:201], v[62:65]
	v_mfma_f32_16x16x32_bf16 v[58:61], v[170:173], v[198:201], v[58:61]
	v_mfma_f32_16x16x32_bf16 v[46:49], v[156:159], v[206:209], v[46:49]
	v_mfma_f32_16x16x32_bf16 v[42:45], v[170:173], v[206:209], v[42:45]
	v_mfma_f32_16x16x32_bf16 v[30:33], v[156:159], v[214:217], v[30:33]
	v_mfma_f32_16x16x32_bf16 v[26:29], v[170:173], v[214:217], v[26:29]
	v_mfma_f32_16x16x32_bf16 v[14:17], v[156:159], v[222:225], v[14:17]
	v_mfma_f32_16x16x32_bf16 v[10:13], v[170:173], v[222:225], v[10:13]
	v_mfma_f32_16x16x32_bf16 v[62:65], v[166:169], v[202:205], v[62:65]
	v_mfma_f32_16x16x32_bf16 v[58:61], v[194:197], v[202:205], v[58:61]
	v_mfma_f32_16x16x32_bf16 v[46:49], v[166:169], v[210:213], v[46:49]
	v_mfma_f32_16x16x32_bf16 v[42:45], v[194:197], v[210:213], v[42:45]
	v_mfma_f32_16x16x32_bf16 v[30:33], v[166:169], v[218:221], v[30:33]
	v_mfma_f32_16x16x32_bf16 v[26:29], v[194:197], v[218:221], v[26:29]
	v_mfma_f32_16x16x32_bf16 v[14:17], v[166:169], v[226:229], v[14:17]
	v_mfma_f32_16x16x32_bf16 v[10:13], v[194:197], v[226:229], v[10:13]
	s_setprio 0
	s_barrier
; #define PG8_STAGE(bufoff, gbase, voff) do { _Pragma("unroll") for (int _i = 0; _i < 2; ++_i) \
;         __builtin_amdgcn_global_load_lds((const unsigned*)((const char*)(gbase) + (voff)[_i]), (LAS unsigned*)(lds + (bufoff) + ldsw + _i * 8192), 16, 0, 0); } while (0)
; #define PG8_LDA(dst, b, h) do { _Pragma("unroll") for (int m = 0; m < 4; ++m) _Pragma("unroll") for (int k = 0; k < 2; ++k) dst[m][k] = *(const LAS bf16x8*)(lds + PG8_SA(b, h) + aoff + m * 2048 + k * 1024); } while (0)
; #define PG8_LDB(dst, b, h) do { _Pragma("unroll") for (int n = 0; n < 2; ++n) _Pragma("unroll") for (int k = 0; k < 2; ++k) dst[n][k] = *(const LAS bf16x8*)(lds + PG8_SB(b, h) + boff + n * 2048 + k * 1024); } while (0)
; #define PG8_MMA(ai, bj, At, Bt) do { __builtin_amdgcn_s_setprio(1); _Pragma("unroll") for (int m = 0; m < 4; ++m) _Pragma("unroll") for (int n = 0; n < 2; ++n) _Pragma("unroll") for (int k = 0; k < 2; ++k) \
;         acc[ai][bj][m][n] = __builtin_amdgcn_mfma_f32_16x16x32_bf16(Bt[n][k], At[m][k], acc[ai][bj][m][n], 0, 0, 0); __builtin_amdgcn_s_setprio(0); } while (0)
; #define PG8_WAIT_V(n) asm volatile("s_waitcnt vmcnt(" #n ")" ::: "memory")
; #define PG8_WAIT_L(n) asm volatile("s_waitcnt lgkmcnt(" #n ")" ::: "memory")
; #define PG8_BAR __builtin_amdgcn_s_barrier()
; #define PG8_SCHED __builtin_amdgcn_sched_barrier(0)
; template <class Epi>
; __device__ __forceinline__ void gemm_phase(LAS unsigned char* lds, const Gemm g, const TileOrder& S, const Epi& E) {
;     ...
;             PG8_STAGE(PG8_SB(0, 1), b2 + hstepB, voffB);
;             PG8_WAIT_V(6); PG8_BAR; PG8_MMA(1, 1, At, B1); PG8_BAR;
;             PG8_LDB(B0, 1, 0); PG8_SCHED; PG8_LDA(At, 1, 0); PG8_STAGE(PG8_SA(0, 1), a2 + hstepA, voffA);
;             PG8_WAIT_L(8); PG8_BAR; PG8_WAIT_L(0); PG8_MMA(0, 0, At, B0); PG8_BAR; PG8_SCHED;
;             PG8_LDB(B1, 1, 1); PG8_STAGE(PG8_SB(1, 0), b3, voffB);
;             PG8_BAR; PG8_WAIT_L(0); PG8_MMA(0, 1, At, B1); PG8_BAR;
;             PG8_LDA(At, 1, 1); PG8_STAGE(PG8_SA(1, 0), a3, voffA);
;             PG8_BAR; PG8_WAIT_L(0); PG8_MMA(1, 0, At, B0); PG8_BAR; PG8_SCHED;
	s_add_u32 s18, s20, 0x160000
	s_addc_u32 s19, s21, 0
	s_add_i32 s42, s42, s26
	v_lshl_add_u64 v[156:157], s[18:19], 0, v[0:1]
	s_mov_b32 m0, s42
	s_nop 0
	global_load_lds_dwordx4 v[156:157], off
	v_lshl_add_u64 v[156:157], s[18:19], 0, v[130:131]
	s_add_i32 m0, s42, 0x2000
	s_nop 0
	global_load_lds_dwordx4 v[156:157], off
	s_waitcnt vmcnt(6)
	s_barrier
	s_setprio 1
	v_mfma_f32_16x16x32_bf16 v[54:57], v[230:233], v[198:201], v[54:57]
	v_mfma_f32_16x16x32_bf16 v[50:53], v[238:241], v[198:201], v[50:53]
	v_mfma_f32_16x16x32_bf16 v[38:41], v[230:233], v[206:209], v[38:41]
	v_mfma_f32_16x16x32_bf16 v[34:37], v[238:241], v[206:209], v[34:37]
	v_mfma_f32_16x16x32_bf16 v[22:25], v[230:233], v[214:217], v[22:25]
	v_mfma_f32_16x16x32_bf16 v[18:21], v[238:241], v[214:217], v[18:21]
	v_mfma_f32_16x16x32_bf16 v[6:9], v[230:233], v[222:225], v[6:9]
	v_mfma_f32_16x16x32_bf16 v[2:5], v[238:241], v[222:225], v[2:5]
	v_mfma_f32_16x16x32_bf16 v[54:57], v[234:237], v[202:205], v[54:57]
	v_mfma_f32_16x16x32_bf16 v[50:53], v[242:245], v[202:205], v[50:53]
	v_mfma_f32_16x16x32_bf16 v[38:41], v[234:237], v[210:213], v[38:41]
	v_mfma_f32_16x16x32_bf16 v[34:37], v[242:245], v[210:213], v[34:37]
	v_mfma_f32_16x16x32_bf16 v[22:25], v[234:237], v[218:221], v[22:25]
	v_mfma_f32_16x16x32_bf16 v[18:21], v[242:245], v[218:221], v[18:21]
	v_mfma_f32_16x16x32_bf16 v[6:9], v[234:237], v[226:229], v[6:9]
	v_mfma_f32_16x16x32_bf16 v[2:5], v[242:245], v[226:229], v[2:5]
	s_setprio 0
	s_add_i32 s42, 0, 0x18000
	v_add_u32_e32 v165, s42, v162
	s_barrier
	ds_read_b128 v[156:159], v165
	ds_read_b128 v[166:169], v165 offset:1024
	ds_read_b128 v[170:173], v165 offset:2048
	ds_read_b128 v[194:197], v165 offset:3072
	s_add_u32 s18, s22, 0x160000
	s_addc_u32 s19, s23, 0
	s_mov_b32 m0, s29
	v_lshl_add_u64 v[230:231], s[18:19], 0, v[0:1]
	ds_read_b128 v[198:201], v164 offset:32768
	ds_read_b128 v[202:205], v164 offset:33792
	ds_read_b128 v[206:209], v164 offset:34816
	ds_read_b128 v[210:213], v164 offset:35840
	ds_read_b128 v[214:217], v164 offset:36864
	ds_read_b128 v[218:221], v164 offset:37888
	ds_read_b128 v[222:225], v164 offset:38912
	ds_read_b128 v[226:229], v164 offset:39936
	global_load_lds_dwordx4 v[230:231], off
	v_lshl_add_u64 v[230:231], s[18:19], 0, v[130:131]
	s_mov_b32 m0, s30
	s_nop 0
	global_load_lds_dwordx4 v[230:231], off
	s_waitcnt lgkmcnt(8)
	s_barrier
	s_waitcnt lgkmcnt(0)
	s_setprio 1
	s_waitcnt lgkmcnt(0)
	v_mfma_f32_16x16x32_bf16 v[126:129], v[156:159], v[198:201], v[126:129]
	v_mfma_f32_16x16x32_bf16 v[122:125], v[170:173], v[198:201], v[122:125]
	v_mfma_f32_16x16x32_bf16 v[110:113], v[156:159], v[206:209], v[110:113]
	v_mfma_f32_16x16x32_bf16 v[106:109], v[170:173], v[206:209], v[106:109]
	v_mfma_f32_16x16x32_bf16 v[94:97], v[156:159], v[214:217], v[94:97]
	v_mfma_f32_16x16x32_bf16 v[90:93], v[170:173], v[214:217], v[90:93]
	v_mfma_f32_16x16x32_bf16 v[78:81], v[156:159], v[222:225], v[78:81]
	v_mfma_f32_16x16x32_bf16 v[74:77], v[170:173], v[222:225], v[74:77]
	v_mfma_f32_16x16x32_bf16 v[126:129], v[166:169], v[202:205], v[126:129]
	v_mfma_f32_16x16x32_bf16 v[122:125], v[194:197], v[202:205], v[122:125]
	v_mfma_f32_16x16x32_bf16 v[110:113], v[166:169], v[210:213], v[110:113]
	v_mfma_f32_16x16x32_bf16 v[106:109], v[194:197], v[210:213], v[106:109]
	v_mfma_f32_16x16x32_bf16 v[94:97], v[166:169], v[218:221], v[94:97]
	v_mfma_f32_16x16x32_bf16 v[90:93], v[194:197], v[218:221], v[90:93]
	v_mfma_f32_16x16x32_bf16 v[78:81], v[166:169], v[226:229], v[78:81]
	v_mfma_f32_16x16x32_bf16 v[74:77], v[194:197], v[226:229], v[74:77]
	s_setprio 0
	s_barrier
	s_add_i32 s22, 0, 0x1c000
	s_add_i32 s18, s42, s26
	v_add_u32_e32 v165, s22, v162
	v_lshl_add_u64 v[136:137], v[136:137], 0, s[58:59]
	s_mov_b32 m0, s18
	ds_read_b128 v[230:233], v165
	ds_read_b128 v[234:237], v165 offset:1024
	ds_read_b128 v[238:241], v165 offset:2048
	ds_read_b128 v[242:245], v165 offset:3072
	global_load_lds_dwordx4 v[136:137], off
	v_lshl_add_u64 v[136:137], v[160:161], 0, s[58:59]
	s_add_i32 m0, s18, 0x2000
	s_nop 0
	global_load_lds_dwordx4 v[136:137], off
	s_barrier
	s_waitcnt lgkmcnt(0)
	s_setprio 1
	s_waitcnt lgkmcnt(0)
	v_mfma_f32_16x16x32_bf16 v[118:121], v[230:233], v[198:201], v[118:121]
	v_mfma_f32_16x16x32_bf16 v[114:117], v[238:241], v[198:201], v[114:117]
	v_mfma_f32_16x16x32_bf16 v[102:105], v[230:233], v[206:209], v[102:105]
	v_mfma_f32_16x16x32_bf16 v[98:101], v[238:241], v[206:209], v[98:101]
	v_mfma_f32_16x16x32_bf16 v[86:89], v[230:233], v[214:217], v[86:89]
	v_mfma_f32_16x16x32_bf16 v[82:85], v[238:241], v[214:217], v[82:85]
	v_mfma_f32_16x16x32_bf16 v[70:73], v[230:233], v[222:225], v[70:73]
	v_mfma_f32_16x16x32_bf16 v[66:69], v[238:241], v[222:225], v[66:69]
	v_mfma_f32_16x16x32_bf16 v[118:121], v[234:237], v[202:205], v[118:121]
	v_mfma_f32_16x16x32_bf16 v[114:117], v[242:245], v[202:205], v[114:117]
	v_mfma_f32_16x16x32_bf16 v[102:105], v[234:237], v[210:213], v[102:105]
	v_mfma_f32_16x16x32_bf16 v[98:101], v[242:245], v[210:213], v[98:101]
	v_mfma_f32_16x16x32_bf16 v[86:89], v[234:237], v[218:221], v[86:89]
	v_mfma_f32_16x16x32_bf16 v[82:85], v[242:245], v[218:221], v[82:85]
	v_mfma_f32_16x16x32_bf16 v[70:73], v[234:237], v[226:229], v[70:73]
	v_mfma_f32_16x16x32_bf16 v[66:69], v[242:245], v[226:229], v[66:69]
	s_setprio 0
	s_mov_b32 m0, s31
	v_lshl_add_u64 v[136:137], v[174:175], 0, s[58:59]
	s_barrier
	ds_read_b128 v[198:201], v164 offset:49152
	ds_read_b128 v[202:205], v164 offset:50176
	ds_read_b128 v[206:209], v164 offset:51200
	ds_read_b128 v[210:213], v164 offset:52224
	ds_read_b128 v[214:217], v164 offset:53248
	ds_read_b128 v[218:221], v164 offset:54272
	ds_read_b128 v[222:225], v164 offset:55296
	ds_read_b128 v[226:229], v164 offset:56320
	global_load_lds_dwordx4 v[136:137], off
	v_lshl_add_u64 v[136:137], v[246:247], 0, s[58:59]
	s_mov_b32 m0, s34
	s_nop 0
	global_load_lds_dwordx4 v[136:137], off
	s_barrier
; #define PG8_STAGE(bufoff, gbase, voff) do { _Pragma("unroll") for (int _i = 0; _i < 2; ++_i) \
;         __builtin_amdgcn_global_load_lds((const unsigned*)((const char*)(gbase) + (voff)[_i]), (LAS unsigned*)(lds + (bufoff) + ldsw + _i * 8192), 16, 0, 0); } while (0)
; #define PG8_MMA(ai, bj, At, Bt) do { __builtin_amdgcn_s_setprio(1); _Pragma("unroll") for (int m = 0; m < 4; ++m) _Pragma("unroll") for (int n = 0; n < 2; ++n) _Pragma("unroll") for (int k = 0; k < 2; ++k) \
;         acc[ai][bj][m][n] = __builtin_amdgcn_mfma_f32_16x16x32_bf16(Bt[n][k], At[m][k], acc[ai][bj][m][n], 0, 0, 0); __builtin_amdgcn_s_setprio(0); } while (0)
; #define PG8_WAIT_V(n) asm volatile("s_waitcnt vmcnt(" #n ")" ::: "memory")
; #define PG8_BAR __builtin_amdgcn_s_barrier()
; template <class Epi>
; __device__ __forceinline__ void gemm_phase(LAS unsigned char* lds, const Gemm g, const TileOrder& S, const Epi& E) {
;     ...
;             PG8_STAGE(PG8_SB(1, 1), b3 + hstepB, voffB);
;             PG8_WAIT_V(6); PG8_BAR; PG8_MMA(1, 1, At, B1); PG8_BAR;
;     __device__ __forceinline__ void operator()(const AccT& acc, const Unit& u, int wr, int wc, int fr, int fq) const {
; #pragma unroll
;         for (int ai = 0; ai < 2; ++ai)
; #pragma unroll
;             for (int m = 0; m < 4; ++m) {
;                 const int row = u.pm * 256 + ai * 128 + wr * 64 + m * 16 + fr;
;                 const bool ok = row < res.valid;
;                 const float* rp = res.row(ok ? row : 0);
; #pragma unroll
;                 for (int bj = 0; bj < 2; ++bj)
; #pragma unroll
;                     for (int n = 0; n < 2; ++n) {
;                         const int col = u.pn * 256 + bj * 128 + wc * 32 + n * 16 + 4 * fq;
;                         f32x4 v = acc[ai][bj][m][n];
;                         if (zero) v = (f32x4){0.f, 0.f, 0.f, 0.f};
;                         if (ok) v += *(const f32x4*)(rp + col);
;                         *(f32x4*)(O + (size_t)row * DM + col) = v;
	s_waitcnt lgkmcnt(0)
	s_setprio 1
	s_waitcnt lgkmcnt(0)
	v_mfma_f32_16x16x32_bf16 v[62:65], v[156:159], v[198:201], v[62:65]
	v_mfma_f32_16x16x32_bf16 v[58:61], v[170:173], v[198:201], v[58:61]
	v_mfma_f32_16x16x32_bf16 v[46:49], v[156:159], v[206:209], v[46:49]
	v_mfma_f32_16x16x32_bf16 v[42:45], v[170:173], v[206:209], v[42:45]
	v_mfma_f32_16x16x32_bf16 v[30:33], v[156:159], v[214:217], v[30:33]
	v_mfma_f32_16x16x32_bf16 v[26:29], v[170:173], v[214:217], v[26:29]
	v_mfma_f32_16x16x32_bf16 v[14:17], v[156:159], v[222:225], v[14:17]
	v_mfma_f32_16x16x32_bf16 v[10:13], v[170:173], v[222:225], v[10:13]
	v_mfma_f32_16x16x32_bf16 v[62:65], v[166:169], v[202:205], v[62:65]
	v_mfma_f32_16x16x32_bf16 v[58:61], v[194:197], v[202:205], v[58:61]
	v_mfma_f32_16x16x32_bf16 v[46:49], v[166:169], v[210:213], v[46:49]
	v_mfma_f32_16x16x32_bf16 v[42:45], v[194:197], v[210:213], v[42:45]
	v_mfma_f32_16x16x32_bf16 v[30:33], v[166:169], v[218:221], v[30:33]
	v_mfma_f32_16x16x32_bf16 v[26:29], v[194:197], v[218:221], v[26:29]
	v_mfma_f32_16x16x32_bf16 v[14:17], v[166:169], v[226:229], v[14:17]
	v_mfma_f32_16x16x32_bf16 v[10:13], v[194:197], v[226:229], v[10:13]
	s_setprio 0
	s_barrier
	s_add_u32 s18, s20, 0x160080
	s_addc_u32 s19, s21, 0
	s_add_i32 s20, s22, s26
	v_lshl_add_u64 v[136:137], s[18:19], 0, v[0:1]
	s_mov_b32 m0, s20
	s_nop 0
	global_load_lds_dwordx4 v[136:137], off
	v_lshl_add_u64 v[136:137], s[18:19], 0, v[130:131]
	s_add_i32 m0, s20, 0x2000
	s_nop 0
	global_load_lds_dwordx4 v[136:137], off
	s_waitcnt vmcnt(6)
	s_barrier
	s_setprio 1
	v_mfma_f32_16x16x32_bf16 v[54:57], v[230:233], v[198:201], v[54:57]
	v_mfma_f32_16x16x32_bf16 v[50:53], v[238:241], v[198:201], v[50:53]
	v_mfma_f32_16x16x32_bf16 v[38:41], v[230:233], v[206:209], v[38:41]
	v_mfma_f32_16x16x32_bf16 v[34:37], v[238:241], v[206:209], v[34:37]
	v_mfma_f32_16x16x32_bf16 v[22:25], v[230:233], v[214:217], v[22:25]
	v_mfma_f32_16x16x32_bf16 v[18:21], v[238:241], v[214:217], v[18:21]
	v_mfma_f32_16x16x32_bf16 v[6:9], v[230:233], v[222:225], v[6:9]
	v_mfma_f32_16x16x32_bf16 v[2:5], v[238:241], v[222:225], v[2:5]
	v_mfma_f32_16x16x32_bf16 v[54:57], v[234:237], v[202:205], v[54:57]
	v_mfma_f32_16x16x32_bf16 v[50:53], v[242:245], v[202:205], v[50:53]
	v_mfma_f32_16x16x32_bf16 v[38:41], v[234:237], v[210:213], v[38:41]
	v_mfma_f32_16x16x32_bf16 v[34:37], v[242:245], v[210:213], v[34:37]
	v_mfma_f32_16x16x32_bf16 v[22:25], v[234:237], v[218:221], v[22:25]
	v_mfma_f32_16x16x32_bf16 v[18:21], v[242:245], v[218:221], v[18:21]
	v_mfma_f32_16x16x32_bf16 v[6:9], v[234:237], v[226:229], v[6:9]
	v_mfma_f32_16x16x32_bf16 v[2:5], v[242:245], v[226:229], v[2:5]
	s_setprio 0
	s_add_i32 s46, s46, 2
	s_add_u32 s44, s44, 0x100
	s_addc_u32 s45, s45, 0
	s_cmpk_gt_u32 s46, 0x55
	s_mov_b64 s[18:19], s[6:7]
	s_barrier
	s_cbranch_scc0 .LBB0_1628
	v_lshl_add_u32 v156, s41, 8, v139
	v_lshl_or_b32 v136, s40, 8, v163
	v_ashrrev_i32_e32 v137, 31, v136
	v_ashrrev_i32_e32 v157, 31, v156
	v_lshlrev_b64 v[156:157], 13, v[156:157]
	v_lshl_add_u64 v[156:157], v[136:137], 2, v[156:157]
	v_lshl_add_u64 v[160:161], s[0:1], 0, v[156:157]
	v_lshl_add_u64 v[158:159], s[10:11], 0, v[156:157]
	global_load_dwordx4 v[166:169], v[160:161], off
	global_load_dwordx4 v[170:173], v[160:161], off offset:64
	global_load_dwordx4 v[194:197], v[160:161], off offset:512
	global_load_dwordx4 v[198:201], v[160:161], off offset:576
	s_mov_b64 s[6:7], 0x20000
	v_lshl_add_u64 v[156:157], v[160:161], 0, s[6:7]
	global_load_dwordx4 v[202:205], v[156:157], off
	global_load_dwordx4 v[206:209], v[156:157], off offset:64
	global_load_dwordx4 v[210:213], v[156:157], off offset:512
	global_load_dwordx4 v[214:217], v[156:157], off offset:576
	s_mov_b64 s[6:7], 0x40000
	v_lshl_add_u64 v[136:137], v[160:161], 0, s[6:7]
	global_load_dwordx4 v[218:221], v[136:137], off
	global_load_dwordx4 v[222:225], v[136:137], off offset:64
	global_load_dwordx4 v[226:229], v[136:137], off offset:512
	global_load_dwordx4 v[230:233], v[136:137], off offset:576
	s_mov_b64 s[6:7], 0x60000
	v_lshl_add_u64 v[156:157], v[160:161], 0, s[6:7]
	global_load_dwordx4 v[234:237], v[156:157], off
	global_load_dwordx4 v[238:241], v[156:157], off offset:64
	global_load_dwordx4 v[242:245], v[156:157], off offset:512
	global_load_dwordx4 v[248:251], v[156:157], off offset:576
	s_waitcnt vmcnt(0)
;     __device__ __forceinline__ void operator()(const AccT& acc, const Unit& u, int wr, int wc, int fr, int fq) const {
; #pragma unroll
;         for (int ai = 0; ai < 2; ++ai)
; #pragma unroll
;             for (int m = 0; m < 4; ++m) {
;                 const int row = u.pm * 256 + ai * 128 + wr * 64 + m * 16 + fr;
;                 const bool ok = row < res.valid;
;                 const float* rp = res.row(ok ? row : 0);
; #pragma unroll
;                 for (int bj = 0; bj < 2; ++bj)
; #pragma unroll
;                     for (int n = 0; n < 2; ++n) {
;                         const int col = u.pn * 256 + bj * 128 + wc * 32 + n * 16 + 4 * fq;
;                         f32x4 v = acc[ai][bj][m][n];
;                         if (zero) v = (f32x4){0.f, 0.f, 0.f, 0.f};
;                         if (ok) v += *(const f32x4*)(rp + col);
;                         *(f32x4*)(O + (size_t)row * DM + col) = v;
;                     }
;             }
	v_pk_add_f32 v[126:127], v[126:127], v[166:167]
	v_pk_add_f32 v[128:129], v[128:129], v[168:169]
	v_pk_add_f32 v[122:123], v[122:123], v[170:171]
	v_pk_add_f32 v[124:125], v[124:125], v[172:173]
	v_pk_add_f32 v[118:119], v[118:119], v[194:195]
	v_pk_add_f32 v[120:121], v[120:121], v[196:197]
	v_pk_add_f32 v[114:115], v[114:115], v[198:199]
	v_pk_add_f32 v[116:117], v[116:117], v[200:201]
	global_store_dwordx4 v[158:159], v[126:129], off
	global_store_dwordx4 v[158:159], v[122:125], off offset:64
	global_store_dwordx4 v[158:159], v[118:121], off offset:512
	global_store_dwordx4 v[158:159], v[114:117], off offset:576
	s_mov_b64 s[6:7], 0x20000
	v_lshl_add_u64 v[156:157], v[158:159], 0, s[6:7]
	v_pk_add_f32 v[110:111], v[110:111], v[202:203]
	v_pk_add_f32 v[112:113], v[112:113], v[204:205]
	v_pk_add_f32 v[106:107], v[106:107], v[206:207]
	v_pk_add_f32 v[108:109], v[108:109], v[208:209]
	v_pk_add_f32 v[102:103], v[102:103], v[210:211]
	v_pk_add_f32 v[104:105], v[104:105], v[212:213]
	v_pk_add_f32 v[98:99], v[98:99], v[214:215]
	v_pk_add_f32 v[100:101], v[100:101], v[216:217]
	global_store_dwordx4 v[156:157], v[110:113], off
	global_store_dwordx4 v[156:157], v[106:109], off offset:64
	global_store_dwordx4 v[156:157], v[102:105], off offset:512
	global_store_dwordx4 v[156:157], v[98:101], off offset:576
	s_mov_b64 s[6:7], 0x40000
	v_lshl_add_u64 v[136:137], v[158:159], 0, s[6:7]
	v_pk_add_f32 v[94:95], v[94:95], v[218:219]
	v_pk_add_f32 v[96:97], v[96:97], v[220:221]
	v_pk_add_f32 v[90:91], v[90:91], v[222:223]
	v_pk_add_f32 v[92:93], v[92:93], v[224:225]
	v_pk_add_f32 v[86:87], v[86:87], v[226:227]
	v_pk_add_f32 v[88:89], v[88:89], v[228:229]
	v_pk_add_f32 v[82:83], v[82:83], v[230:231]
	v_pk_add_f32 v[84:85], v[84:85], v[232:233]
	global_store_dwordx4 v[136:137], v[94:97], off
	global_store_dwordx4 v[136:137], v[90:93], off offset:64
	global_store_dwordx4 v[136:137], v[86:89], off offset:512
	global_store_dwordx4 v[136:137], v[82:85], off offset:576
	s_mov_b64 s[6:7], 0x60000
	v_lshl_add_u64 v[156:157], v[158:159], 0, s[6:7]
	v_pk_add_f32 v[78:79], v[78:79], v[234:235]
	v_pk_add_f32 v[80:81], v[80:81], v[236:237]
	v_pk_add_f32 v[74:75], v[74:75], v[238:239]
	v_pk_add_f32 v[76:77], v[76:77], v[240:241]
	v_pk_add_f32 v[70:71], v[70:71], v[242:243]
	v_pk_add_f32 v[72:73], v[72:73], v[244:245]
	v_pk_add_f32 v[66:67], v[66:67], v[248:249]
	v_pk_add_f32 v[68:69], v[68:69], v[250:251]
	global_store_dwordx4 v[156:157], v[78:81], off
	global_store_dwordx4 v[156:157], v[74:77], off offset:64
	global_store_dwordx4 v[156:157], v[70:73], off offset:512
	global_store_dwordx4 v[156:157], v[66:69], off offset:576
	s_mov_b64 s[6:7], 0x100000
	v_lshl_add_u64 v[136:137], v[160:161], 0, s[6:7]
	global_load_dwordx4 v[166:169], v[136:137], off
	global_load_dwordx4 v[170:173], v[136:137], off offset:64
	global_load_dwordx4 v[194:197], v[136:137], off offset:512
	global_load_dwordx4 v[198:201], v[136:137], off offset:576
	s_mov_b64 s[6:7], 0x120000
	v_lshl_add_u64 v[156:157], v[160:161], 0, s[6:7]
	global_load_dwordx4 v[202:205], v[156:157], off
	global_load_dwordx4 v[206:209], v[156:157], off offset:64
	global_load_dwordx4 v[210:213], v[156:157], off offset:512
	global_load_dwordx4 v[214:217], v[156:157], off offset:576
	s_mov_b64 s[6:7], 0x140000
	v_lshl_add_u64 v[136:137], v[160:161], 0, s[6:7]
	global_load_dwordx4 v[218:221], v[136:137], off
	global_load_dwordx4 v[222:225], v[136:137], off offset:64
	global_load_dwordx4 v[226:229], v[136:137], off offset:512
	global_load_dwordx4 v[230:233], v[136:137], off offset:576
	s_mov_b64 s[6:7], 0x160000
	v_lshl_add_u64 v[156:157], v[160:161], 0, s[6:7]
	global_load_dwordx4 v[234:237], v[156:157], off
	global_load_dwordx4 v[238:241], v[156:157], off offset:64
	global_load_dwordx4 v[242:245], v[156:157], off offset:512
	global_load_dwordx4 v[248:251], v[156:157], off offset:576
	s_waitcnt vmcnt(0)
	s_mov_b64 s[6:7], 0x100000
	v_lshl_add_u64 v[136:137], v[158:159], 0, s[6:7]
	v_pk_add_f32 v[62:63], v[62:63], v[166:167]
	v_pk_add_f32 v[64:65], v[64:65], v[168:169]
	v_pk_add_f32 v[58:59], v[58:59], v[170:171]
	v_pk_add_f32 v[60:61], v[60:61], v[172:173]
	v_pk_add_f32 v[54:55], v[54:55], v[194:195]
	v_pk_add_f32 v[56:57], v[56:57], v[196:197]
	v_pk_add_f32 v[50:51], v[50:51], v[198:199]
	v_pk_add_f32 v[52:53], v[52:53], v[200:201]
	global_store_dwordx4 v[136:137], v[62:65], off
	global_store_dwordx4 v[136:137], v[58:61], off offset:64
	global_store_dwordx4 v[136:137], v[54:57], off offset:512
	global_store_dwordx4 v[136:137], v[50:53], off offset:576
	s_mov_b64 s[6:7], 0x120000
	v_lshl_add_u64 v[156:157], v[158:159], 0, s[6:7]
	v_pk_add_f32 v[46:47], v[46:47], v[202:203]
	v_pk_add_f32 v[48:49], v[48:49], v[204:205]
	v_pk_add_f32 v[42:43], v[42:43], v[206:207]
	v_pk_add_f32 v[44:45], v[44:45], v[208:209]
	v_pk_add_f32 v[38:39], v[38:39], v[210:211]
	v_pk_add_f32 v[40:41], v[40:41], v[212:213]
	v_pk_add_f32 v[34:35], v[34:35], v[214:215]
	v_pk_add_f32 v[36:37], v[36:37], v[216:217]
	global_store_dwordx4 v[156:157], v[46:49], off
	global_store_dwordx4 v[156:157], v[42:45], off offset:64
	global_store_dwordx4 v[156:157], v[38:41], off offset:512
	global_store_dwordx4 v[156:157], v[34:37], off offset:576
	s_mov_b64 s[6:7], 0x140000
	v_lshl_add_u64 v[136:137], v[158:159], 0, s[6:7]
	v_pk_add_f32 v[30:31], v[30:31], v[218:219]
	v_pk_add_f32 v[32:33], v[32:33], v[220:221]
	v_pk_add_f32 v[26:27], v[26:27], v[222:223]
	v_pk_add_f32 v[28:29], v[28:29], v[224:225]
	v_pk_add_f32 v[22:23], v[22:23], v[226:227]
	v_pk_add_f32 v[24:25], v[24:25], v[228:229]
	v_pk_add_f32 v[18:19], v[18:19], v[230:231]
	v_pk_add_f32 v[20:21], v[20:21], v[232:233]
	global_store_dwordx4 v[136:137], v[30:33], off
	global_store_dwordx4 v[136:137], v[26:29], off offset:64
	global_store_dwordx4 v[136:137], v[22:25], off offset:512
	global_store_dwordx4 v[136:137], v[18:21], off offset:576
	s_mov_b64 s[6:7], 0x160000
	v_lshl_add_u64 v[156:157], v[158:159], 0, s[6:7]
	v_pk_add_f32 v[14:15], v[14:15], v[234:235]
	v_pk_add_f32 v[16:17], v[16:17], v[236:237]
	v_pk_add_f32 v[10:11], v[10:11], v[238:239]
	v_pk_add_f32 v[12:13], v[12:13], v[240:241]
	v_pk_add_f32 v[6:7], v[6:7], v[242:243]
	v_pk_add_f32 v[8:9], v[8:9], v[244:245]
	v_pk_add_f32 v[2:3], v[2:3], v[248:249]
	v_pk_add_f32 v[4:5], v[4:5], v[250:251]
	global_store_dwordx4 v[156:157], v[14:17], off
	global_store_dwordx4 v[156:157], v[10:13], off offset:64
	global_store_dwordx4 v[156:157], v[6:9], off offset:512
	global_store_dwordx4 v[156:157], v[2:5], off offset:576
	s_branch .LBB0_1616
